# row phases: write-through (sc1) stores for the f32 residual-stream rows so seams have no dirty L2 lines to flush; nt on read-once loads
# speedup vs baseline: 1.0207x; 1.0027x over previous
; __device__ __forceinline__ float lo_bf(unsigned w) { return __uint_as_float(w << 16); }
; __device__ __forceinline__ float hi_bf(unsigned w) { return __uint_as_float(w & 0xffff0000u); }
; template <bool HAS_F, bool HAS_H>
; __device__ __forceinline__ void phase_rows(const Params& p, int sp, int sn, float resw, bool from_input, bool write_x = true) {
;     ...
;             for (int j = 0; j < 4; ++j) { const u32x2 w = *(const u32x2*)(F + (size_t)row * D + 4 * lane + 256 * j);
;                 f[j] = (f32x4){lo_bf(w.x), hi_bf(w.x), lo_bf(w.y), hi_bf(w.y)}; ss += (f[j].x * f[j].x + f[j].y * f[j].y) + (f[j].z * f[j].z + f[j].w * f[j].w); }
;             const float rs = 1.0f / sqrtf(wave_sum(ss) * (1.0f / D) + EPS) * resw;
;             const float* gate = mod + b * 9216 + sp * 3072 + 2048; const float* gp = p.in[7] + sp * D;
; #pragma unroll
;             for (int j = 0; j < 4; ++j) { const f32x4 g = *(const f32x4*)(gate + 4 * lane + 256 * j), q = *(const f32x4*)(gp + 4 * lane + 256 * j);
;                 v[j] = v[j] + g * (f[j] * rs * q);
;                 if (write_x) *(f32x4*)(p.out + (size_t)row * D + 4 * lane + 256 * j) = v[j]; }
;         }
;         if (HAS_H) {
;             float ss = 0.f;
; #pragma unroll
;             for (int j = 0; j < 4; ++j) ss += (v[j].x * v[j].x + v[j].y * v[j].y) + (v[j].z * v[j].z + v[j].w * v[j].w);
;             const float rs = 1.0f / sqrtf(wave_sum(ss) * (1.0f / D) + EPS);
.Lrp4_pk4:
	s_waitcnt vmcnt(16)
	v_lshlrev_b32_e32 v112, 16, v20
	v_and_b32_e32 v113, 0xffff0000, v20
	v_lshlrev_b32_e32 v114, 16, v21
	v_and_b32_e32 v115, 0xffff0000, v21
	v_lshlrev_b32_e32 v116, 16, v22
	v_and_b32_e32 v117, 0xffff0000, v22
	v_lshlrev_b32_e32 v118, 16, v23
	v_and_b32_e32 v119, 0xffff0000, v23
	v_lshlrev_b32_e32 v120, 16, v24
	v_and_b32_e32 v121, 0xffff0000, v24
	v_lshlrev_b32_e32 v122, 16, v25
	v_and_b32_e32 v123, 0xffff0000, v25
	v_lshlrev_b32_e32 v124, 16, v26
	v_and_b32_e32 v125, 0xffff0000, v26
	v_lshlrev_b32_e32 v100, 16, v27
	v_and_b32_e32 v101, 0xffff0000, v27
	v_pk_mul_f32 v[102:103], v[112:113], v[112:113]
	v_pk_mul_f32 v[106:107], v[114:115], v[114:115]
	v_pk_fma_f32 v[102:103], v[116:117], v[116:117], v[102:103]
	v_pk_fma_f32 v[106:107], v[118:119], v[118:119], v[106:107]
	v_pk_fma_f32 v[102:103], v[120:121], v[120:121], v[102:103]
	v_pk_fma_f32 v[106:107], v[122:123], v[122:123], v[106:107]
	v_pk_fma_f32 v[102:103], v[124:125], v[124:125], v[102:103]
	v_pk_fma_f32 v[106:107], v[100:101], v[100:101], v[106:107]
	v_pk_add_f32 v[102:103], v[102:103], v[106:107]
	v_add_f32_e32 v102, v102, v103
	s_nop 1
	v_add_f32_dpp v102, v102, v102 quad_perm:[1,0,3,2] row_mask:0xf bank_mask:0xf
	s_nop 1
	v_add_f32_dpp v102, v102, v102 quad_perm:[2,3,0,1] row_mask:0xf bank_mask:0xf
	s_nop 1
	v_add_f32_dpp v102, v102, v102 row_half_mirror row_mask:0xf bank_mask:0xf
	s_nop 1
	v_add_f32_dpp v102, v102, v102 row_mirror row_mask:0xf bank_mask:0xf
	s_nop 1
	v_add_f32_dpp v102, v102, v102 row_bcast:15 row_mask:0xa bank_mask:0xf
	s_nop 1
	v_add_f32_dpp v102, v102, v102 row_bcast:31 row_mask:0xc bank_mask:0xf
	s_nop 1
	v_readlane_b32 s74, v102, 63
	s_nop 2
	v_mov_b32_e32 v102, s74
	v_fmamk_f32 v102, v102, 0x3a800000, v2
	v_mul_f32_e32 v103, 0x4f800000, v102
	v_cmp_gt_f32_e32 vcc, 0xf800000, v102
	s_nop 1
	v_cndmask_b32_e32 v102, v102, v103, vcc
	v_sqrt_f32_e32 v103, v102
	s_nop 0
	v_add_u32_e32 v104, -1, v103
	v_add_u32_e32 v106, 1, v103
	v_fma_f32 v107, -v104, v103, v102
	v_fma_f32 v108, -v106, v103, v102
	v_cmp_ge_f32_e64 s[76:77], 0, v107
	s_nop 1
	v_cndmask_b32_e64 v103, v103, v104, s[76:77]
	v_cmp_lt_f32_e64 s[76:77], 0, v108
	s_nop 1
	v_cndmask_b32_e64 v103, v103, v106, s[76:77]
	v_mul_f32_e32 v104, 0x37800000, v103
	v_cndmask_b32_e32 v103, v103, v104, vcc
	v_cmp_class_f32_e32 vcc, v102, v3
	s_nop 1
	v_cndmask_b32_e32 v102, v103, v102, vcc
	v_div_scale_f32 v103, s[76:77], v102, v102, 1.0
	v_rcp_f32_e32 v104, v103
	v_div_scale_f32 v106, vcc, 1.0, v102, 1.0
	v_fma_f32 v107, -v103, v104, 1.0
	v_fmac_f32_e32 v104, v107, v104
	v_mul_f32_e32 v107, v106, v104
	v_fma_f32 v108, -v103, v107, v106
	v_fmac_f32_e32 v107, v108, v104
	v_fma_f32 v103, -v103, v107, v106
	v_div_fmas_f32 v103, v103, v104, v107
	v_div_fixup_f32 v110, v103, v102, 1.0
	v_mul_f32_e32 v110, 0.5, v110
	v_pk_mul_f32 v[112:113], v[112:113], v[110:111] op_sel_hi:[1,0]
	v_pk_mul_f32 v[114:115], v[114:115], v[110:111] op_sel_hi:[1,0]
	v_pk_mul_f32 v[116:117], v[116:117], v[110:111] op_sel_hi:[1,0]
	v_pk_mul_f32 v[118:119], v[118:119], v[110:111] op_sel_hi:[1,0]
	v_pk_mul_f32 v[120:121], v[120:121], v[110:111] op_sel_hi:[1,0]
	v_pk_mul_f32 v[122:123], v[122:123], v[110:111] op_sel_hi:[1,0]
	v_pk_mul_f32 v[124:125], v[124:125], v[110:111] op_sel_hi:[1,0]
	v_pk_mul_f32 v[100:101], v[100:101], v[110:111] op_sel_hi:[1,0]
	v_pk_mul_f32 v[112:113], v[176:177], v[112:113]
	v_pk_mul_f32 v[114:115], v[178:179], v[114:115]
	v_pk_mul_f32 v[116:117], v[180:181], v[116:117]
	v_pk_mul_f32 v[118:119], v[182:183], v[118:119]
	v_pk_mul_f32 v[120:121], v[184:185], v[120:121]
	v_pk_mul_f32 v[122:123], v[186:187], v[122:123]
	v_pk_mul_f32 v[124:125], v[188:189], v[124:125]
	v_pk_mul_f32 v[100:101], v[190:191], v[100:101]
	v_pk_fma_f32 v[4:5], v[160:161], v[112:113], v[4:5]
	v_pk_fma_f32 v[6:7], v[162:163], v[114:115], v[6:7]
	v_pk_fma_f32 v[8:9], v[164:165], v[116:117], v[8:9]
	v_pk_fma_f32 v[10:11], v[166:167], v[118:119], v[10:11]
	v_pk_fma_f32 v[12:13], v[168:169], v[120:121], v[12:13]
	v_pk_fma_f32 v[14:15], v[170:171], v[122:123], v[14:15]
	v_pk_fma_f32 v[16:17], v[172:173], v[124:125], v[16:17]
	v_pk_fma_f32 v[18:19], v[174:175], v[100:101], v[18:19]
	s_lshl_b32 s60, s55, 12
	s_add_u32 s72, s84, s60
	s_addc_u32 s73, s85, 0
	global_store_dwordx4 v0, v[4:7], s[72:73] sc1
	global_store_dwordx4 v0, v[8:11], s[72:73] offset:1024 sc1
	global_store_dwordx4 v0, v[12:15], s[72:73] offset:2048 sc1
	global_store_dwordx4 v0, v[16:19], s[72:73] offset:3072 sc1
	v_pk_mul_f32 v[102:103], v[4:5], v[4:5]
	v_pk_mul_f32 v[106:107], v[6:7], v[6:7]
	v_pk_fma_f32 v[102:103], v[8:9], v[8:9], v[102:103]
	v_pk_fma_f32 v[106:107], v[10:11], v[10:11], v[106:107]
	v_pk_fma_f32 v[102:103], v[12:13], v[12:13], v[102:103]
	v_pk_fma_f32 v[106:107], v[14:15], v[14:15], v[106:107]
	v_pk_fma_f32 v[102:103], v[16:17], v[16:17], v[102:103]
	v_pk_fma_f32 v[106:107], v[18:19], v[18:19], v[106:107]
	v_pk_add_f32 v[102:103], v[102:103], v[106:107]
	v_add_f32_e32 v102, v102, v103
	s_nop 1
	v_add_f32_dpp v102, v102, v102 quad_perm:[1,0,3,2] row_mask:0xf bank_mask:0xf
	s_nop 1
	v_add_f32_dpp v102, v102, v102 quad_perm:[2,3,0,1] row_mask:0xf bank_mask:0xf
	s_nop 1
	v_add_f32_dpp v102, v102, v102 row_half_mirror row_mask:0xf bank_mask:0xf
	s_nop 1
	v_add_f32_dpp v102, v102, v102 row_mirror row_mask:0xf bank_mask:0xf
	s_nop 1
	v_add_f32_dpp v102, v102, v102 row_bcast:15 row_mask:0xa bank_mask:0xf
	s_nop 1
	v_add_f32_dpp v102, v102, v102 row_bcast:31 row_mask:0xc bank_mask:0xf
	s_nop 1
	v_readlane_b32 s74, v102, 63
	s_nop 2
	v_mov_b32_e32 v102, s74
	v_fmamk_f32 v102, v102, 0x3a800000, v2
	v_mul_f32_e32 v103, 0x4f800000, v102
; __device__ __forceinline__ unsigned pk_bf16(float lo, float hi) { const f32x2 v = {lo, hi}; const bf16x2_t b = __builtin_convertvector(v, bf16x2_t); return __builtin_bit_cast(unsigned, b); }
; __device__ __forceinline__ float lo_bf(unsigned w) { return __uint_as_float(w << 16); }
; __device__ __forceinline__ float hi_bf(unsigned w) { return __uint_as_float(w & 0xffff0000u); }
; template <bool HAS_F, bool HAS_H>
; __device__ __forceinline__ void phase_rows(const Params& p, int sp, int sn, float resw, bool from_input, bool write_x = true) {
;     ...
;     for (int row = gw; row < T; row += NGW) {
;         const int b = row_batch(row);
;         const float* xin = !from_input ? p.out + (size_t)row * D : (row < TP ? p.in[0] + (size_t)row * D : p.in[1] + (size_t)(row - TP) * D);
;         f32x4 v[4];
; #pragma unroll
;         for (int j = 0; j < 4; ++j) v[j] = *(const f32x4*)(xin + 4 * lane + 256 * j);
;         if (HAS_F) {
;             f32x4 f[4]; float ss = 0.f;
; #pragma unroll
;             for (int j = 0; j < 4; ++j) { const u32x2 w = *(const u32x2*)(F + (size_t)row * D + 4 * lane + 256 * j);
;                 f[j] = (f32x4){lo_bf(w.x), hi_bf(w.x), lo_bf(w.y), hi_bf(w.y)}; ss += (f[j].x * f[j].x + f[j].y * f[j].y) + (f[j].z * f[j].z + f[j].w * f[j].w); }
;             const float rs = 1.0f / sqrtf(wave_sum(ss) * (1.0f / D) + EPS) * resw;
;             const float* gate = mod + b * 9216 + sp * 3072 + 2048; const float* gp = p.in[7] + sp * D;
; #pragma unroll
;             for (int j = 0; j < 4; ++j) { const f32x4 g = *(const f32x4*)(gate + 4 * lane + 256 * j), q = *(const f32x4*)(gp + 4 * lane + 256 * j);
;     ...
;             const float rs = 1.0f / sqrtf(wave_sum(ss) * (1.0f / D) + EPS);
;             const float* sh = mod + b * 9216 + sn * 3072; const float* scl = sh + 1024; const float* gq = p.in[6] + sn * D;
; #pragma unroll
;             for (int j = 0; j < 4; ++j) { const f32x4 a = *(const f32x4*)(sh + 4 * lane + 256 * j), s = *(const f32x4*)(scl + 4 * lane + 256 * j), q = *(const f32x4*)(gq + 4 * lane + 256 * j);
;                 const f32x4 h = (v[j] * rs * q) * (s + 1.0f) + a;
;                 u32x2 w; w.x = pk_bf16(h.x, h.y); w.y = pk_bf16(h.z, h.w);
;                 *(u32x2*)(H + (size_t)row * D + 4 * lane + 256 * j) = w; }
	v_cmp_gt_f32_e32 vcc, 0xf800000, v102
	s_nop 1
	v_cndmask_b32_e32 v102, v102, v103, vcc
	v_sqrt_f32_e32 v103, v102
	s_nop 0
	v_add_u32_e32 v104, -1, v103
	v_add_u32_e32 v106, 1, v103
	v_fma_f32 v107, -v104, v103, v102
	v_fma_f32 v108, -v106, v103, v102
	v_cmp_ge_f32_e64 s[76:77], 0, v107
	s_nop 1
	v_cndmask_b32_e64 v103, v103, v104, s[76:77]
	v_cmp_lt_f32_e64 s[76:77], 0, v108
	s_nop 1
	v_cndmask_b32_e64 v103, v103, v106, s[76:77]
	v_mul_f32_e32 v104, 0x37800000, v103
	v_cndmask_b32_e32 v103, v103, v104, vcc
	v_cmp_class_f32_e32 vcc, v102, v3
	s_nop 1
	v_cndmask_b32_e32 v102, v103, v102, vcc
	v_div_scale_f32 v103, s[76:77], v102, v102, 1.0
	v_rcp_f32_e32 v104, v103
	v_div_scale_f32 v106, vcc, 1.0, v102, 1.0
	v_fma_f32 v107, -v103, v104, 1.0
	v_fmac_f32_e32 v104, v107, v104
	v_mul_f32_e32 v107, v106, v104
	v_fma_f32 v108, -v103, v107, v106
	v_fmac_f32_e32 v107, v108, v104
	v_fma_f32 v103, -v103, v107, v106
	v_div_fmas_f32 v103, v103, v104, v107
	v_div_fixup_f32 v110, v103, v102, 1.0
	s_lshl_b32 s60, s55, 11
	s_add_u32 s70, s78, s60
	s_addc_u32 s71, s79, 0
	v_pk_mul_f32 v[112:113], v[4:5], v[110:111] op_sel_hi:[1,0]
	v_pk_mul_f32 v[114:115], v[6:7], v[110:111] op_sel_hi:[1,0]
	v_pk_mul_f32 v[116:117], v[8:9], v[110:111] op_sel_hi:[1,0]
	v_pk_mul_f32 v[118:119], v[10:11], v[110:111] op_sel_hi:[1,0]
	v_pk_mul_f32 v[120:121], v[12:13], v[110:111] op_sel_hi:[1,0]
	v_pk_mul_f32 v[122:123], v[14:15], v[110:111] op_sel_hi:[1,0]
	v_pk_mul_f32 v[124:125], v[16:17], v[110:111] op_sel_hi:[1,0]
	v_pk_mul_f32 v[100:101], v[18:19], v[110:111] op_sel_hi:[1,0]
	v_pk_mul_f32 v[112:113], v[192:193], v[112:113]
	v_pk_mul_f32 v[114:115], v[194:195], v[114:115]
	v_pk_mul_f32 v[116:117], v[196:197], v[116:117]
	v_pk_mul_f32 v[118:119], v[198:199], v[118:119]
	v_pk_mul_f32 v[120:121], v[200:201], v[120:121]
	v_pk_mul_f32 v[122:123], v[202:203], v[122:123]
	v_pk_mul_f32 v[124:125], v[204:205], v[124:125]
	v_pk_mul_f32 v[100:101], v[206:207], v[100:101]
	v_pk_fma_f32 v[112:113], v[208:209], v[112:113], v[224:225]
	v_pk_fma_f32 v[114:115], v[210:211], v[114:115], v[226:227]
	v_pk_fma_f32 v[116:117], v[212:213], v[116:117], v[228:229]
	v_pk_fma_f32 v[118:119], v[214:215], v[118:119], v[230:231]
	v_pk_fma_f32 v[120:121], v[216:217], v[120:121], v[232:233]
	v_pk_fma_f32 v[122:123], v[218:219], v[122:123], v[234:235]
	v_pk_fma_f32 v[124:125], v[220:221], v[124:125], v[236:237]
	v_pk_fma_f32 v[100:101], v[222:223], v[100:101], v[238:239]
	v_cvt_pk_bf16_f32 v240, v112, v113
	v_cvt_pk_bf16_f32 v241, v114, v115
	v_cvt_pk_bf16_f32 v242, v116, v117
	v_cvt_pk_bf16_f32 v243, v118, v119
	v_cvt_pk_bf16_f32 v244, v120, v121
	v_cvt_pk_bf16_f32 v245, v122, v123
	v_cvt_pk_bf16_f32 v246, v124, v125
	v_cvt_pk_bf16_f32 v247, v100, v101
	global_store_dwordx2 v1, v[240:241], s[70:71]
	global_store_dwordx2 v1, v[242:243], s[70:71] offset:512
	global_store_dwordx2 v1, v[244:245], s[70:71] offset:1024
	global_store_dwordx2 v1, v[246:247], s[70:71] offset:1536
	s_add_u32 s55, s55, 8
	s_add_u32 s57, s55, 16
	s_min_u32 s57, s57, s54
	s_cmp_lt_u32 s57, 0x8000
	s_cselect_b32 s64, s8, s10
	s_cselect_b32 s65, s9, s11
	s_cselect_b32 s60, 0, 0x8000
	s_sub_u32 s60, s57, s60
	s_lshl_b32 s60, s60, 12
	s_add_u32 s64, s64, s60
	s_addc_u32 s65, s65, 0
	s_lshl_b32 s60, s57, 11
	s_add_u32 s66, s82, s60
	s_addc_u32 s67, s83, 0
	global_load_dwordx4 v[4:7], v0, s[64:65] nt
	global_load_dwordx4 v[8:11], v0, s[64:65] offset:1024 nt
	global_load_dwordx4 v[12:15], v0, s[64:65] offset:2048 nt
	global_load_dwordx4 v[16:19], v0, s[64:65] offset:3072 nt
	global_load_dwordx2 v[20:21], v1, s[66:67] nt
	global_load_dwordx2 v[22:23], v1, s[66:67] offset:512 nt
	global_load_dwordx2 v[24:25], v1, s[66:67] offset:1024 nt
	global_load_dwordx2 v[26:27], v1, s[66:67] offset:1536 nt
	s_lshr_b32 s60, s55, 11
	s_sub_u32 s61, s55, 0x8000
	s_lshr_b32 s61, s61, 12
	s_add_u32 s61, s61, 16
	s_cmp_lt_u32 s55, 0x8000
	s_cselect_b32 s63, s60, s61
	s_cmp_eq_u32 s63, s56
	s_cbranch_scc1 .Lrp4_pk5
	s_mov_b32 s56, s63
	s_mul_i32 s60, s56, 0x9000
	s_add_u32 s60, s60, 0x3182000
	s_add_u32 s0, s92, s60
	s_addc_u32 s1, s93, 0
	global_load_dwordx4 v[160:163], v0, s[0:1]
	global_load_dwordx4 v[164:167], v0, s[0:1] offset:1024
	global_load_dwordx4 v[168:171], v0, s[0:1] offset:2048
	global_load_dwordx4 v[172:175], v0, s[0:1] offset:3072
	s_add_u32 s0, s22, 0x0
	s_addc_u32 s1, s23, 0
	global_load_dwordx4 v[176:179], v0, s[0:1]
	global_load_dwordx4 v[180:183], v0, s[0:1] offset:1024
	global_load_dwordx4 v[184:187], v0, s[0:1] offset:2048
	global_load_dwordx4 v[188:191], v0, s[0:1] offset:3072
	s_add_u32 s0, s20, 0x1000
	s_addc_u32 s1, s21, 0
	global_load_dwordx4 v[192:195], v0, s[0:1]
	global_load_dwordx4 v[196:199], v0, s[0:1] offset:1024
	global_load_dwordx4 v[200:203], v0, s[0:1] offset:2048
	global_load_dwordx4 v[204:207], v0, s[0:1] offset:3072
	s_mul_i32 s60, s56, 0x9000
	s_add_u32 s60, s60, 0x3184000
	s_add_u32 s0, s92, s60
	s_addc_u32 s1, s93, 0
	global_load_dwordx4 v[208:211], v0, s[0:1]
	global_load_dwordx4 v[212:215], v0, s[0:1] offset:1024
	global_load_dwordx4 v[216:219], v0, s[0:1] offset:2048
	global_load_dwordx4 v[220:223], v0, s[0:1] offset:3072
	s_mul_i32 s60, s56, 0x9000
	s_add_u32 s60, s60, 0x3183000
	s_add_u32 s0, s92, s60
	s_addc_u32 s1, s93, 0
	global_load_dwordx4 v[224:227], v0, s[0:1]
	global_load_dwordx4 v[228:231], v0, s[0:1] offset:1024
	global_load_dwordx4 v[232:235], v0, s[0:1] offset:2048
	global_load_dwordx4 v[236:239], v0, s[0:1] offset:3072
	s_waitcnt vmcnt(0)
	v_pk_add_f32 v[208:209], v[208:209], 1.0 op_sel_hi:[1,0]
	v_pk_add_f32 v[210:211], v[210:211], 1.0 op_sel_hi:[1,0]
	v_pk_add_f32 v[212:213], v[212:213], 1.0 op_sel_hi:[1,0]
	v_pk_add_f32 v[214:215], v[214:215], 1.0 op_sel_hi:[1,0]
	v_pk_add_f32 v[216:217], v[216:217], 1.0 op_sel_hi:[1,0]
	v_pk_add_f32 v[218:219], v[218:219], 1.0 op_sel_hi:[1,0]
	v_pk_add_f32 v[220:221], v[220:221], 1.0 op_sel_hi:[1,0]
	v_pk_add_f32 v[222:223], v[222:223], 1.0 op_sel_hi:[1,0]
; __device__ __forceinline__ float lo_bf(unsigned w) { return __uint_as_float(w << 16); }
; __device__ __forceinline__ float hi_bf(unsigned w) { return __uint_as_float(w & 0xffff0000u); }
; template <bool HAS_F, bool HAS_H>
; __device__ __forceinline__ void phase_rows(const Params& p, int sp, int sn, float resw, bool from_input, bool write_x = true) {
;     ...
;             for (int j = 0; j < 4; ++j) { const u32x2 w = *(const u32x2*)(F + (size_t)row * D + 4 * lane + 256 * j);
;                 f[j] = (f32x4){lo_bf(w.x), hi_bf(w.x), lo_bf(w.y), hi_bf(w.y)}; ss += (f[j].x * f[j].x + f[j].y * f[j].y) + (f[j].z * f[j].z + f[j].w * f[j].w); }
;             const float rs = 1.0f / sqrtf(wave_sum(ss) * (1.0f / D) + EPS) * resw;
;             const float* gate = mod + b * 9216 + sp * 3072 + 2048; const float* gp = p.in[7] + sp * D;
; #pragma unroll
;             for (int j = 0; j < 4; ++j) { const f32x4 g = *(const f32x4*)(gate + 4 * lane + 256 * j), q = *(const f32x4*)(gp + 4 * lane + 256 * j);
;                 v[j] = v[j] + g * (f[j] * rs * q);
;                 if (write_x) *(f32x4*)(p.out + (size_t)row * D + 4 * lane + 256 * j) = v[j]; }
;         }
;         if (HAS_H) {
;             float ss = 0.f;
; #pragma unroll
;             for (int j = 0; j < 4; ++j) ss += (v[j].x * v[j].x + v[j].y * v[j].y) + (v[j].z * v[j].z + v[j].w * v[j].w);
;             const float rs = 1.0f / sqrtf(wave_sum(ss) * (1.0f / D) + EPS);
.Lrp4_pk5:
	s_waitcnt vmcnt(24)
	v_lshlrev_b32_e32 v112, 16, v52
	v_and_b32_e32 v113, 0xffff0000, v52
	v_lshlrev_b32_e32 v114, 16, v53
	v_and_b32_e32 v115, 0xffff0000, v53
	v_lshlrev_b32_e32 v116, 16, v54
	v_and_b32_e32 v117, 0xffff0000, v54
	v_lshlrev_b32_e32 v118, 16, v55
	v_and_b32_e32 v119, 0xffff0000, v55
	v_lshlrev_b32_e32 v120, 16, v56
	v_and_b32_e32 v121, 0xffff0000, v56
	v_lshlrev_b32_e32 v122, 16, v57
	v_and_b32_e32 v123, 0xffff0000, v57
	v_lshlrev_b32_e32 v124, 16, v58
	v_and_b32_e32 v125, 0xffff0000, v58
	v_lshlrev_b32_e32 v100, 16, v59
	v_and_b32_e32 v101, 0xffff0000, v59
	v_pk_mul_f32 v[102:103], v[112:113], v[112:113]
	v_pk_mul_f32 v[106:107], v[114:115], v[114:115]
	v_pk_fma_f32 v[102:103], v[116:117], v[116:117], v[102:103]
	v_pk_fma_f32 v[106:107], v[118:119], v[118:119], v[106:107]
	v_pk_fma_f32 v[102:103], v[120:121], v[120:121], v[102:103]
	v_pk_fma_f32 v[106:107], v[122:123], v[122:123], v[106:107]
	v_pk_fma_f32 v[102:103], v[124:125], v[124:125], v[102:103]
	v_pk_fma_f32 v[106:107], v[100:101], v[100:101], v[106:107]
	v_pk_add_f32 v[102:103], v[102:103], v[106:107]
	v_add_f32_e32 v102, v102, v103
	s_nop 1
	v_add_f32_dpp v102, v102, v102 quad_perm:[1,0,3,2] row_mask:0xf bank_mask:0xf
	s_nop 1
	v_add_f32_dpp v102, v102, v102 quad_perm:[2,3,0,1] row_mask:0xf bank_mask:0xf
	s_nop 1
	v_add_f32_dpp v102, v102, v102 row_half_mirror row_mask:0xf bank_mask:0xf
	s_nop 1
	v_add_f32_dpp v102, v102, v102 row_mirror row_mask:0xf bank_mask:0xf
	s_nop 1
	v_add_f32_dpp v102, v102, v102 row_bcast:15 row_mask:0xa bank_mask:0xf
	s_nop 1
	v_add_f32_dpp v102, v102, v102 row_bcast:31 row_mask:0xc bank_mask:0xf
	s_nop 1
	v_readlane_b32 s74, v102, 63
	s_nop 2
	v_mov_b32_e32 v102, s74
	v_fmamk_f32 v102, v102, 0x3a800000, v2
	v_mul_f32_e32 v103, 0x4f800000, v102
	v_cmp_gt_f32_e32 vcc, 0xf800000, v102
	s_nop 1
	v_cndmask_b32_e32 v102, v102, v103, vcc
	v_sqrt_f32_e32 v103, v102
	s_nop 0
	v_add_u32_e32 v104, -1, v103
	v_add_u32_e32 v106, 1, v103
	v_fma_f32 v107, -v104, v103, v102
	v_fma_f32 v108, -v106, v103, v102
	v_cmp_ge_f32_e64 s[76:77], 0, v107
	s_nop 1
	v_cndmask_b32_e64 v103, v103, v104, s[76:77]
	v_cmp_lt_f32_e64 s[76:77], 0, v108
	s_nop 1
	v_cndmask_b32_e64 v103, v103, v106, s[76:77]
	v_mul_f32_e32 v104, 0x37800000, v103
	v_cndmask_b32_e32 v103, v103, v104, vcc
	v_cmp_class_f32_e32 vcc, v102, v3
	s_nop 1
	v_cndmask_b32_e32 v102, v103, v102, vcc
	v_div_scale_f32 v103, s[76:77], v102, v102, 1.0
	v_rcp_f32_e32 v104, v103
	v_div_scale_f32 v106, vcc, 1.0, v102, 1.0
	v_fma_f32 v107, -v103, v104, 1.0
	v_fmac_f32_e32 v104, v107, v104
	v_mul_f32_e32 v107, v106, v104
	v_fma_f32 v108, -v103, v107, v106
	v_fmac_f32_e32 v107, v108, v104
	v_fma_f32 v103, -v103, v107, v106
	v_div_fmas_f32 v103, v103, v104, v107
	v_div_fixup_f32 v110, v103, v102, 1.0
	v_mul_f32_e32 v110, 0.5, v110
	v_pk_mul_f32 v[112:113], v[112:113], v[110:111] op_sel_hi:[1,0]
	v_pk_mul_f32 v[114:115], v[114:115], v[110:111] op_sel_hi:[1,0]
	v_pk_mul_f32 v[116:117], v[116:117], v[110:111] op_sel_hi:[1,0]
	v_pk_mul_f32 v[118:119], v[118:119], v[110:111] op_sel_hi:[1,0]
	v_pk_mul_f32 v[120:121], v[120:121], v[110:111] op_sel_hi:[1,0]
	v_pk_mul_f32 v[122:123], v[122:123], v[110:111] op_sel_hi:[1,0]
	v_pk_mul_f32 v[124:125], v[124:125], v[110:111] op_sel_hi:[1,0]
	v_pk_mul_f32 v[100:101], v[100:101], v[110:111] op_sel_hi:[1,0]
	v_pk_mul_f32 v[112:113], v[176:177], v[112:113]
	v_pk_mul_f32 v[114:115], v[178:179], v[114:115]
	v_pk_mul_f32 v[116:117], v[180:181], v[116:117]
	v_pk_mul_f32 v[118:119], v[182:183], v[118:119]
	v_pk_mul_f32 v[120:121], v[184:185], v[120:121]
	v_pk_mul_f32 v[122:123], v[186:187], v[122:123]
	v_pk_mul_f32 v[124:125], v[188:189], v[124:125]
	v_pk_mul_f32 v[100:101], v[190:191], v[100:101]
	v_pk_fma_f32 v[36:37], v[160:161], v[112:113], v[36:37]
	v_pk_fma_f32 v[38:39], v[162:163], v[114:115], v[38:39]
	v_pk_fma_f32 v[40:41], v[164:165], v[116:117], v[40:41]
	v_pk_fma_f32 v[42:43], v[166:167], v[118:119], v[42:43]
	v_pk_fma_f32 v[44:45], v[168:169], v[120:121], v[44:45]
	v_pk_fma_f32 v[46:47], v[170:171], v[122:123], v[46:47]
	v_pk_fma_f32 v[48:49], v[172:173], v[124:125], v[48:49]
	v_pk_fma_f32 v[50:51], v[174:175], v[100:101], v[50:51]
	s_lshl_b32 s60, s55, 12
	s_add_u32 s72, s84, s60
	s_addc_u32 s73, s85, 0
	global_store_dwordx4 v0, v[36:39], s[72:73] sc1
	global_store_dwordx4 v0, v[40:43], s[72:73] offset:1024 sc1
	global_store_dwordx4 v0, v[44:47], s[72:73] offset:2048 sc1
	global_store_dwordx4 v0, v[48:51], s[72:73] offset:3072 sc1
	v_pk_mul_f32 v[102:103], v[36:37], v[36:37]
	v_pk_mul_f32 v[106:107], v[38:39], v[38:39]
	v_pk_fma_f32 v[102:103], v[40:41], v[40:41], v[102:103]
	v_pk_fma_f32 v[106:107], v[42:43], v[42:43], v[106:107]
	v_pk_fma_f32 v[102:103], v[44:45], v[44:45], v[102:103]
	v_pk_fma_f32 v[106:107], v[46:47], v[46:47], v[106:107]
	v_pk_fma_f32 v[102:103], v[48:49], v[48:49], v[102:103]
	v_pk_fma_f32 v[106:107], v[50:51], v[50:51], v[106:107]
	v_pk_add_f32 v[102:103], v[102:103], v[106:107]
	v_add_f32_e32 v102, v102, v103
	s_nop 1
	v_add_f32_dpp v102, v102, v102 quad_perm:[1,0,3,2] row_mask:0xf bank_mask:0xf
	s_nop 1
	v_add_f32_dpp v102, v102, v102 quad_perm:[2,3,0,1] row_mask:0xf bank_mask:0xf
	s_nop 1
	v_add_f32_dpp v102, v102, v102 row_half_mirror row_mask:0xf bank_mask:0xf
	s_nop 1
	v_add_f32_dpp v102, v102, v102 row_mirror row_mask:0xf bank_mask:0xf
	s_nop 1
	v_add_f32_dpp v102, v102, v102 row_bcast:15 row_mask:0xa bank_mask:0xf
	s_nop 1
	v_add_f32_dpp v102, v102, v102 row_bcast:31 row_mask:0xc bank_mask:0xf
	s_nop 1
	v_readlane_b32 s74, v102, 63
	s_nop 2
	v_mov_b32_e32 v102, s74
	v_fmamk_f32 v102, v102, 0x3a800000, v2
	v_mul_f32_e32 v103, 0x4f800000, v102
; __device__ __forceinline__ unsigned pk_bf16(float lo, float hi) { const f32x2 v = {lo, hi}; const bf16x2_t b = __builtin_convertvector(v, bf16x2_t); return __builtin_bit_cast(unsigned, b); }
; __device__ __forceinline__ float lo_bf(unsigned w) { return __uint_as_float(w << 16); }
; __device__ __forceinline__ float hi_bf(unsigned w) { return __uint_as_float(w & 0xffff0000u); }
; template <bool HAS_F, bool HAS_H>
; __device__ __forceinline__ void phase_rows(const Params& p, int sp, int sn, float resw, bool from_input, bool write_x = true) {
;     ...
;     for (int row = gw; row < T; row += NGW) {
;         const int b = row_batch(row);
;         const float* xin = !from_input ? p.out + (size_t)row * D : (row < TP ? p.in[0] + (size_t)row * D : p.in[1] + (size_t)(row - TP) * D);
;         f32x4 v[4];
; #pragma unroll
;         for (int j = 0; j < 4; ++j) v[j] = *(const f32x4*)(xin + 4 * lane + 256 * j);
;         if (HAS_F) {
;             f32x4 f[4]; float ss = 0.f;
; #pragma unroll
;             for (int j = 0; j < 4; ++j) { const u32x2 w = *(const u32x2*)(F + (size_t)row * D + 4 * lane + 256 * j);
;                 f[j] = (f32x4){lo_bf(w.x), hi_bf(w.x), lo_bf(w.y), hi_bf(w.y)}; ss += (f[j].x * f[j].x + f[j].y * f[j].y) + (f[j].z * f[j].z + f[j].w * f[j].w); }
;             const float rs = 1.0f / sqrtf(wave_sum(ss) * (1.0f / D) + EPS) * resw;
;             const float* gate = mod + b * 9216 + sp * 3072 + 2048; const float* gp = p.in[7] + sp * D;
; #pragma unroll
;             for (int j = 0; j < 4; ++j) { const f32x4 g = *(const f32x4*)(gate + 4 * lane + 256 * j), q = *(const f32x4*)(gp + 4 * lane + 256 * j);
;     ...
;             const float rs = 1.0f / sqrtf(wave_sum(ss) * (1.0f / D) + EPS);
;             const float* sh = mod + b * 9216 + sn * 3072; const float* scl = sh + 1024; const float* gq = p.in[6] + sn * D;
; #pragma unroll
;             for (int j = 0; j < 4; ++j) { const f32x4 a = *(const f32x4*)(sh + 4 * lane + 256 * j), s = *(const f32x4*)(scl + 4 * lane + 256 * j), q = *(const f32x4*)(gq + 4 * lane + 256 * j);
;                 const f32x4 h = (v[j] * rs * q) * (s + 1.0f) + a;
;                 u32x2 w; w.x = pk_bf16(h.x, h.y); w.y = pk_bf16(h.z, h.w);
;                 *(u32x2*)(H + (size_t)row * D + 4 * lane + 256 * j) = w; }
	v_cmp_gt_f32_e32 vcc, 0xf800000, v102
	s_nop 1
	v_cndmask_b32_e32 v102, v102, v103, vcc
	v_sqrt_f32_e32 v103, v102
	s_nop 0
	v_add_u32_e32 v104, -1, v103
	v_add_u32_e32 v106, 1, v103
	v_fma_f32 v107, -v104, v103, v102
	v_fma_f32 v108, -v106, v103, v102
	v_cmp_ge_f32_e64 s[76:77], 0, v107
	s_nop 1
	v_cndmask_b32_e64 v103, v103, v104, s[76:77]
	v_cmp_lt_f32_e64 s[76:77], 0, v108
	s_nop 1
	v_cndmask_b32_e64 v103, v103, v106, s[76:77]
	v_mul_f32_e32 v104, 0x37800000, v103
	v_cndmask_b32_e32 v103, v103, v104, vcc
	v_cmp_class_f32_e32 vcc, v102, v3
	s_nop 1
	v_cndmask_b32_e32 v102, v103, v102, vcc
	v_div_scale_f32 v103, s[76:77], v102, v102, 1.0
	v_rcp_f32_e32 v104, v103
	v_div_scale_f32 v106, vcc, 1.0, v102, 1.0
	v_fma_f32 v107, -v103, v104, 1.0
	v_fmac_f32_e32 v104, v107, v104
	v_mul_f32_e32 v107, v106, v104
	v_fma_f32 v108, -v103, v107, v106
	v_fmac_f32_e32 v107, v108, v104
	v_fma_f32 v103, -v103, v107, v106
	v_div_fmas_f32 v103, v103, v104, v107
	v_div_fixup_f32 v110, v103, v102, 1.0
	s_lshl_b32 s60, s55, 11
	s_add_u32 s70, s78, s60
	s_addc_u32 s71, s79, 0
	v_pk_mul_f32 v[112:113], v[36:37], v[110:111] op_sel_hi:[1,0]
	v_pk_mul_f32 v[114:115], v[38:39], v[110:111] op_sel_hi:[1,0]
	v_pk_mul_f32 v[116:117], v[40:41], v[110:111] op_sel_hi:[1,0]
	v_pk_mul_f32 v[118:119], v[42:43], v[110:111] op_sel_hi:[1,0]
	v_pk_mul_f32 v[120:121], v[44:45], v[110:111] op_sel_hi:[1,0]
	v_pk_mul_f32 v[122:123], v[46:47], v[110:111] op_sel_hi:[1,0]
	v_pk_mul_f32 v[124:125], v[48:49], v[110:111] op_sel_hi:[1,0]
	v_pk_mul_f32 v[100:101], v[50:51], v[110:111] op_sel_hi:[1,0]
	v_pk_mul_f32 v[112:113], v[192:193], v[112:113]
	v_pk_mul_f32 v[114:115], v[194:195], v[114:115]
	v_pk_mul_f32 v[116:117], v[196:197], v[116:117]
	v_pk_mul_f32 v[118:119], v[198:199], v[118:119]
	v_pk_mul_f32 v[120:121], v[200:201], v[120:121]
	v_pk_mul_f32 v[122:123], v[202:203], v[122:123]
	v_pk_mul_f32 v[124:125], v[204:205], v[124:125]
	v_pk_mul_f32 v[100:101], v[206:207], v[100:101]
	v_pk_fma_f32 v[112:113], v[208:209], v[112:113], v[224:225]
	v_pk_fma_f32 v[114:115], v[210:211], v[114:115], v[226:227]
	v_pk_fma_f32 v[116:117], v[212:213], v[116:117], v[228:229]
	v_pk_fma_f32 v[118:119], v[214:215], v[118:119], v[230:231]
	v_pk_fma_f32 v[120:121], v[216:217], v[120:121], v[232:233]
	v_pk_fma_f32 v[122:123], v[218:219], v[122:123], v[234:235]
	v_pk_fma_f32 v[124:125], v[220:221], v[124:125], v[236:237]
	v_pk_fma_f32 v[100:101], v[222:223], v[100:101], v[238:239]
	v_cvt_pk_bf16_f32 v240, v112, v113
	v_cvt_pk_bf16_f32 v241, v114, v115
	v_cvt_pk_bf16_f32 v242, v116, v117
	v_cvt_pk_bf16_f32 v243, v118, v119
	v_cvt_pk_bf16_f32 v244, v120, v121
	v_cvt_pk_bf16_f32 v245, v122, v123
	v_cvt_pk_bf16_f32 v246, v124, v125
	v_cvt_pk_bf16_f32 v247, v100, v101
	global_store_dwordx2 v1, v[240:241], s[70:71]
	global_store_dwordx2 v1, v[242:243], s[70:71] offset:512
	global_store_dwordx2 v1, v[244:245], s[70:71] offset:1024
	global_store_dwordx2 v1, v[246:247], s[70:71] offset:1536
	s_add_u32 s55, s55, 8
	s_add_u32 s57, s55, 16
	s_min_u32 s57, s57, s54
	s_cmp_lt_u32 s57, 0x8000
	s_cselect_b32 s64, s8, s10
	s_cselect_b32 s65, s9, s11
	s_cselect_b32 s60, 0, 0x8000
	s_sub_u32 s60, s57, s60
	s_lshl_b32 s60, s60, 12
	s_add_u32 s64, s64, s60
	s_addc_u32 s65, s65, 0
	s_lshl_b32 s60, s57, 11
	s_add_u32 s66, s82, s60
	s_addc_u32 s67, s83, 0
	global_load_dwordx4 v[36:39], v0, s[64:65] nt
	global_load_dwordx4 v[40:43], v0, s[64:65] offset:1024 nt
	global_load_dwordx4 v[44:47], v0, s[64:65] offset:2048 nt
	global_load_dwordx4 v[48:51], v0, s[64:65] offset:3072 nt
	global_load_dwordx2 v[52:53], v1, s[66:67] nt
	global_load_dwordx2 v[54:55], v1, s[66:67] offset:512 nt
	global_load_dwordx2 v[56:57], v1, s[66:67] offset:1024 nt
	global_load_dwordx2 v[58:59], v1, s[66:67] offset:1536 nt
	s_lshr_b32 s60, s55, 11
	s_sub_u32 s61, s55, 0x8000
	s_lshr_b32 s61, s61, 12
	s_add_u32 s61, s61, 16
	s_cmp_lt_u32 s55, 0x8000
	s_cselect_b32 s63, s60, s61
	s_cmp_eq_u32 s63, s56
	s_cbranch_scc1 .Lrp4_pk6
	s_mov_b32 s56, s63
	s_mul_i32 s60, s56, 0x9000
	s_add_u32 s60, s60, 0x3182000
	s_add_u32 s0, s92, s60
	s_addc_u32 s1, s93, 0
	global_load_dwordx4 v[160:163], v0, s[0:1]
	global_load_dwordx4 v[164:167], v0, s[0:1] offset:1024
	global_load_dwordx4 v[168:171], v0, s[0:1] offset:2048
	global_load_dwordx4 v[172:175], v0, s[0:1] offset:3072
	s_add_u32 s0, s22, 0x0
	s_addc_u32 s1, s23, 0
	global_load_dwordx4 v[176:179], v0, s[0:1]
	global_load_dwordx4 v[180:183], v0, s[0:1] offset:1024
	global_load_dwordx4 v[184:187], v0, s[0:1] offset:2048
	global_load_dwordx4 v[188:191], v0, s[0:1] offset:3072
	s_add_u32 s0, s20, 0x1000
	s_addc_u32 s1, s21, 0
	global_load_dwordx4 v[192:195], v0, s[0:1]
	global_load_dwordx4 v[196:199], v0, s[0:1] offset:1024
	global_load_dwordx4 v[200:203], v0, s[0:1] offset:2048
	global_load_dwordx4 v[204:207], v0, s[0:1] offset:3072
	s_mul_i32 s60, s56, 0x9000
	s_add_u32 s60, s60, 0x3184000
	s_add_u32 s0, s92, s60
	s_addc_u32 s1, s93, 0
	global_load_dwordx4 v[208:211], v0, s[0:1]
	global_load_dwordx4 v[212:215], v0, s[0:1] offset:1024
	global_load_dwordx4 v[216:219], v0, s[0:1] offset:2048
	global_load_dwordx4 v[220:223], v0, s[0:1] offset:3072
	s_mul_i32 s60, s56, 0x9000
	s_add_u32 s60, s60, 0x3183000
	s_add_u32 s0, s92, s60
	s_addc_u32 s1, s93, 0
	global_load_dwordx4 v[224:227], v0, s[0:1]
	global_load_dwordx4 v[228:231], v0, s[0:1] offset:1024
	global_load_dwordx4 v[232:235], v0, s[0:1] offset:2048
	global_load_dwordx4 v[236:239], v0, s[0:1] offset:3072
	s_waitcnt vmcnt(0)
	v_pk_add_f32 v[208:209], v[208:209], 1.0 op_sel_hi:[1,0]
	v_pk_add_f32 v[210:211], v[210:211], 1.0 op_sel_hi:[1,0]
	v_pk_add_f32 v[212:213], v[212:213], 1.0 op_sel_hi:[1,0]
	v_pk_add_f32 v[214:215], v[214:215], 1.0 op_sel_hi:[1,0]
	v_pk_add_f32 v[216:217], v[216:217], 1.0 op_sel_hi:[1,0]
	v_pk_add_f32 v[218:219], v[218:219], 1.0 op_sel_hi:[1,0]
	v_pk_add_f32 v[220:221], v[220:221], 1.0 op_sel_hi:[1,0]
	v_pk_add_f32 v[222:223], v[222:223], 1.0 op_sel_hi:[1,0]
; __device__ __forceinline__ float lo_bf(unsigned w) { return __uint_as_float(w << 16); }
; __device__ __forceinline__ float hi_bf(unsigned w) { return __uint_as_float(w & 0xffff0000u); }
; template <bool HAS_F, bool HAS_H>
; __device__ __forceinline__ void phase_rows(const Params& p, int sp, int sn, float resw, bool from_input, bool write_x = true) {
;     ...
;             for (int j = 0; j < 4; ++j) { const u32x2 w = *(const u32x2*)(F + (size_t)row * D + 4 * lane + 256 * j);
;                 f[j] = (f32x4){lo_bf(w.x), hi_bf(w.x), lo_bf(w.y), hi_bf(w.y)}; ss += (f[j].x * f[j].x + f[j].y * f[j].y) + (f[j].z * f[j].z + f[j].w * f[j].w); }
;             const float rs = 1.0f / sqrtf(wave_sum(ss) * (1.0f / D) + EPS) * resw;
;             const float* gate = mod + b * 9216 + sp * 3072 + 2048; const float* gp = p.in[7] + sp * D;
; #pragma unroll
;             for (int j = 0; j < 4; ++j) { const f32x4 g = *(const f32x4*)(gate + 4 * lane + 256 * j), q = *(const f32x4*)(gp + 4 * lane + 256 * j);
;                 v[j] = v[j] + g * (f[j] * rs * q);
;                 if (write_x) *(f32x4*)(p.out + (size_t)row * D + 4 * lane + 256 * j) = v[j]; }
.Lrp4_pk6:
	s_waitcnt vmcnt(32)
	v_lshlrev_b32_e32 v112, 16, v84
	v_and_b32_e32 v113, 0xffff0000, v84
	v_lshlrev_b32_e32 v114, 16, v85
	v_and_b32_e32 v115, 0xffff0000, v85
	v_lshlrev_b32_e32 v116, 16, v86
	v_and_b32_e32 v117, 0xffff0000, v86
	v_lshlrev_b32_e32 v118, 16, v87
	v_and_b32_e32 v119, 0xffff0000, v87
	v_lshlrev_b32_e32 v120, 16, v88
	v_and_b32_e32 v121, 0xffff0000, v88
	v_lshlrev_b32_e32 v122, 16, v89
	v_and_b32_e32 v123, 0xffff0000, v89
	v_lshlrev_b32_e32 v124, 16, v90
	v_and_b32_e32 v125, 0xffff0000, v90
	v_lshlrev_b32_e32 v100, 16, v91
	v_and_b32_e32 v101, 0xffff0000, v91
	v_pk_mul_f32 v[102:103], v[112:113], v[112:113]
	v_pk_mul_f32 v[106:107], v[114:115], v[114:115]
	v_pk_fma_f32 v[102:103], v[116:117], v[116:117], v[102:103]
	v_pk_fma_f32 v[106:107], v[118:119], v[118:119], v[106:107]
	v_pk_fma_f32 v[102:103], v[120:121], v[120:121], v[102:103]
	v_pk_fma_f32 v[106:107], v[122:123], v[122:123], v[106:107]
	v_pk_fma_f32 v[102:103], v[124:125], v[124:125], v[102:103]
	v_pk_fma_f32 v[106:107], v[100:101], v[100:101], v[106:107]
	v_pk_add_f32 v[102:103], v[102:103], v[106:107]
	v_add_f32_e32 v102, v102, v103
	s_nop 1
	v_add_f32_dpp v102, v102, v102 quad_perm:[1,0,3,2] row_mask:0xf bank_mask:0xf
	s_nop 1
	v_add_f32_dpp v102, v102, v102 quad_perm:[2,3,0,1] row_mask:0xf bank_mask:0xf
	s_nop 1
	v_add_f32_dpp v102, v102, v102 row_half_mirror row_mask:0xf bank_mask:0xf
	s_nop 1
	v_add_f32_dpp v102, v102, v102 row_mirror row_mask:0xf bank_mask:0xf
	s_nop 1
	v_add_f32_dpp v102, v102, v102 row_bcast:15 row_mask:0xa bank_mask:0xf
	s_nop 1
	v_add_f32_dpp v102, v102, v102 row_bcast:31 row_mask:0xc bank_mask:0xf
	s_nop 1
	v_readlane_b32 s74, v102, 63
	s_nop 2
	v_mov_b32_e32 v102, s74
	v_fmamk_f32 v102, v102, 0x3a800000, v2
	v_mul_f32_e32 v103, 0x4f800000, v102
	v_cmp_gt_f32_e32 vcc, 0xf800000, v102
	s_nop 1
	v_cndmask_b32_e32 v102, v102, v103, vcc
	v_sqrt_f32_e32 v103, v102
	s_nop 0
	v_add_u32_e32 v104, -1, v103
	v_add_u32_e32 v106, 1, v103
	v_fma_f32 v107, -v104, v103, v102
	v_fma_f32 v108, -v106, v103, v102
	v_cmp_ge_f32_e64 s[76:77], 0, v107
	s_nop 1
	v_cndmask_b32_e64 v103, v103, v104, s[76:77]
	v_cmp_lt_f32_e64 s[76:77], 0, v108
	s_nop 1
	v_cndmask_b32_e64 v103, v103, v106, s[76:77]
	v_mul_f32_e32 v104, 0x37800000, v103
	v_cndmask_b32_e32 v103, v103, v104, vcc
	v_cmp_class_f32_e32 vcc, v102, v3
	s_nop 1
	v_cndmask_b32_e32 v102, v103, v102, vcc
	v_div_scale_f32 v103, s[76:77], v102, v102, 1.0
	v_rcp_f32_e32 v104, v103
	v_div_scale_f32 v106, vcc, 1.0, v102, 1.0
	v_fma_f32 v107, -v103, v104, 1.0
	v_fmac_f32_e32 v104, v107, v104
	v_mul_f32_e32 v107, v106, v104
	v_fma_f32 v108, -v103, v107, v106
	v_fmac_f32_e32 v107, v108, v104
	v_fma_f32 v103, -v103, v107, v106
	v_div_fmas_f32 v103, v103, v104, v107
	v_div_fixup_f32 v110, v103, v102, 1.0
	v_mul_f32_e32 v110, 0.5, v110
	v_pk_mul_f32 v[112:113], v[112:113], v[110:111] op_sel_hi:[1,0]
	v_pk_mul_f32 v[114:115], v[114:115], v[110:111] op_sel_hi:[1,0]
	v_pk_mul_f32 v[116:117], v[116:117], v[110:111] op_sel_hi:[1,0]
	v_pk_mul_f32 v[118:119], v[118:119], v[110:111] op_sel_hi:[1,0]
	v_pk_mul_f32 v[120:121], v[120:121], v[110:111] op_sel_hi:[1,0]
	v_pk_mul_f32 v[122:123], v[122:123], v[110:111] op_sel_hi:[1,0]
	v_pk_mul_f32 v[124:125], v[124:125], v[110:111] op_sel_hi:[1,0]
	v_pk_mul_f32 v[100:101], v[100:101], v[110:111] op_sel_hi:[1,0]
	v_pk_mul_f32 v[112:113], v[176:177], v[112:113]
	v_pk_mul_f32 v[114:115], v[178:179], v[114:115]
	v_pk_mul_f32 v[116:117], v[180:181], v[116:117]
	v_pk_mul_f32 v[118:119], v[182:183], v[118:119]
	v_pk_mul_f32 v[120:121], v[184:185], v[120:121]
	v_pk_mul_f32 v[122:123], v[186:187], v[122:123]
	v_pk_mul_f32 v[124:125], v[188:189], v[124:125]
	v_pk_mul_f32 v[100:101], v[190:191], v[100:101]
	v_pk_fma_f32 v[68:69], v[160:161], v[112:113], v[68:69]
	v_pk_fma_f32 v[70:71], v[162:163], v[114:115], v[70:71]
	v_pk_fma_f32 v[72:73], v[164:165], v[116:117], v[72:73]
	v_pk_fma_f32 v[74:75], v[166:167], v[118:119], v[74:75]
	v_pk_fma_f32 v[76:77], v[168:169], v[120:121], v[76:77]
	v_pk_fma_f32 v[78:79], v[170:171], v[122:123], v[78:79]
	v_pk_fma_f32 v[80:81], v[172:173], v[124:125], v[80:81]
	v_pk_fma_f32 v[82:83], v[174:175], v[100:101], v[82:83]
	s_lshl_b32 s60, s55, 12
	s_add_u32 s72, s84, s60
	s_addc_u32 s73, s85, 0
	global_store_dwordx4 v0, v[68:71], s[72:73] sc1
; __device__ __forceinline__ unsigned pk_bf16(float lo, float hi) { const f32x2 v = {lo, hi}; const bf16x2_t b = __builtin_convertvector(v, bf16x2_t); return __builtin_bit_cast(unsigned, b); }
; template <bool HAS_F, bool HAS_H>
; __device__ __forceinline__ void phase_rows(const Params& p, int sp, int sn, float resw, bool from_input, bool write_x = true) {
;     ...
;                 if (write_x) *(f32x4*)(p.out + (size_t)row * D + 4 * lane + 256 * j) = v[j]; }
;         }
;         if (HAS_H) {
;             float ss = 0.f;
; #pragma unroll
;             for (int j = 0; j < 4; ++j) ss += (v[j].x * v[j].x + v[j].y * v[j].y) + (v[j].z * v[j].z + v[j].w * v[j].w);
;             const float rs = 1.0f / sqrtf(wave_sum(ss) * (1.0f / D) + EPS);
;             const float* sh = mod + b * 9216 + sn * 3072; const float* scl = sh + 1024; const float* gq = p.in[6] + sn * D;
; #pragma unroll
;             for (int j = 0; j < 4; ++j) { const f32x4 a = *(const f32x4*)(sh + 4 * lane + 256 * j), s = *(const f32x4*)(scl + 4 * lane + 256 * j), q = *(const f32x4*)(gq + 4 * lane + 256 * j);
;                 const f32x4 h = (v[j] * rs * q) * (s + 1.0f) + a;
;                 u32x2 w; w.x = pk_bf16(h.x, h.y); w.y = pk_bf16(h.z, h.w);
;                 *(u32x2*)(H + (size_t)row * D + 4 * lane + 256 * j) = w; }
	global_store_dwordx4 v0, v[72:75], s[72:73] offset:1024 sc1
	global_store_dwordx4 v0, v[76:79], s[72:73] offset:2048 sc1
	global_store_dwordx4 v0, v[80:83], s[72:73] offset:3072 sc1
	v_pk_mul_f32 v[102:103], v[68:69], v[68:69]
	v_pk_mul_f32 v[106:107], v[70:71], v[70:71]
	v_pk_fma_f32 v[102:103], v[72:73], v[72:73], v[102:103]
	v_pk_fma_f32 v[106:107], v[74:75], v[74:75], v[106:107]
	v_pk_fma_f32 v[102:103], v[76:77], v[76:77], v[102:103]
	v_pk_fma_f32 v[106:107], v[78:79], v[78:79], v[106:107]
	v_pk_fma_f32 v[102:103], v[80:81], v[80:81], v[102:103]
	v_pk_fma_f32 v[106:107], v[82:83], v[82:83], v[106:107]
	v_pk_add_f32 v[102:103], v[102:103], v[106:107]
	v_add_f32_e32 v102, v102, v103
	s_nop 1
	v_add_f32_dpp v102, v102, v102 quad_perm:[1,0,3,2] row_mask:0xf bank_mask:0xf
	s_nop 1
	v_add_f32_dpp v102, v102, v102 quad_perm:[2,3,0,1] row_mask:0xf bank_mask:0xf
	s_nop 1
	v_add_f32_dpp v102, v102, v102 row_half_mirror row_mask:0xf bank_mask:0xf
	s_nop 1
	v_add_f32_dpp v102, v102, v102 row_mirror row_mask:0xf bank_mask:0xf
	s_nop 1
	v_add_f32_dpp v102, v102, v102 row_bcast:15 row_mask:0xa bank_mask:0xf
	s_nop 1
	v_add_f32_dpp v102, v102, v102 row_bcast:31 row_mask:0xc bank_mask:0xf
	s_nop 1
	v_readlane_b32 s74, v102, 63
	s_nop 2
	v_mov_b32_e32 v102, s74
	v_fmamk_f32 v102, v102, 0x3a800000, v2
	v_mul_f32_e32 v103, 0x4f800000, v102
	v_cmp_gt_f32_e32 vcc, 0xf800000, v102
	s_nop 1
	v_cndmask_b32_e32 v102, v102, v103, vcc
	v_sqrt_f32_e32 v103, v102
	s_nop 0
	v_add_u32_e32 v104, -1, v103
	v_add_u32_e32 v106, 1, v103
	v_fma_f32 v107, -v104, v103, v102
	v_fma_f32 v108, -v106, v103, v102
	v_cmp_ge_f32_e64 s[76:77], 0, v107
	s_nop 1
	v_cndmask_b32_e64 v103, v103, v104, s[76:77]
	v_cmp_lt_f32_e64 s[76:77], 0, v108
	s_nop 1
	v_cndmask_b32_e64 v103, v103, v106, s[76:77]
	v_mul_f32_e32 v104, 0x37800000, v103
	v_cndmask_b32_e32 v103, v103, v104, vcc
	v_cmp_class_f32_e32 vcc, v102, v3
	s_nop 1
	v_cndmask_b32_e32 v102, v103, v102, vcc
	v_div_scale_f32 v103, s[76:77], v102, v102, 1.0
	v_rcp_f32_e32 v104, v103
	v_div_scale_f32 v106, vcc, 1.0, v102, 1.0
	v_fma_f32 v107, -v103, v104, 1.0
	v_fmac_f32_e32 v104, v107, v104
	v_mul_f32_e32 v107, v106, v104
	v_fma_f32 v108, -v103, v107, v106
	v_fmac_f32_e32 v107, v108, v104
	v_fma_f32 v103, -v103, v107, v106
	v_div_fmas_f32 v103, v103, v104, v107
	v_div_fixup_f32 v110, v103, v102, 1.0
	s_lshl_b32 s60, s55, 11
	s_add_u32 s70, s78, s60
	s_addc_u32 s71, s79, 0
	v_pk_mul_f32 v[112:113], v[68:69], v[110:111] op_sel_hi:[1,0]
	v_pk_mul_f32 v[114:115], v[70:71], v[110:111] op_sel_hi:[1,0]
	v_pk_mul_f32 v[116:117], v[72:73], v[110:111] op_sel_hi:[1,0]
	v_pk_mul_f32 v[118:119], v[74:75], v[110:111] op_sel_hi:[1,0]
	v_pk_mul_f32 v[120:121], v[76:77], v[110:111] op_sel_hi:[1,0]
	v_pk_mul_f32 v[122:123], v[78:79], v[110:111] op_sel_hi:[1,0]
	v_pk_mul_f32 v[124:125], v[80:81], v[110:111] op_sel_hi:[1,0]
	v_pk_mul_f32 v[100:101], v[82:83], v[110:111] op_sel_hi:[1,0]
	v_pk_mul_f32 v[112:113], v[192:193], v[112:113]
	v_pk_mul_f32 v[114:115], v[194:195], v[114:115]
	v_pk_mul_f32 v[116:117], v[196:197], v[116:117]
	v_pk_mul_f32 v[118:119], v[198:199], v[118:119]
	v_pk_mul_f32 v[120:121], v[200:201], v[120:121]
	v_pk_mul_f32 v[122:123], v[202:203], v[122:123]
	v_pk_mul_f32 v[124:125], v[204:205], v[124:125]
	v_pk_mul_f32 v[100:101], v[206:207], v[100:101]
	v_pk_fma_f32 v[112:113], v[208:209], v[112:113], v[224:225]
	v_pk_fma_f32 v[114:115], v[210:211], v[114:115], v[226:227]
	v_pk_fma_f32 v[116:117], v[212:213], v[116:117], v[228:229]
	v_pk_fma_f32 v[118:119], v[214:215], v[118:119], v[230:231]
	v_pk_fma_f32 v[120:121], v[216:217], v[120:121], v[232:233]
	v_pk_fma_f32 v[122:123], v[218:219], v[122:123], v[234:235]
	v_pk_fma_f32 v[124:125], v[220:221], v[124:125], v[236:237]
	v_pk_fma_f32 v[100:101], v[222:223], v[100:101], v[238:239]
	v_cvt_pk_bf16_f32 v240, v112, v113
	v_cvt_pk_bf16_f32 v241, v114, v115
	v_cvt_pk_bf16_f32 v242, v116, v117
	v_cvt_pk_bf16_f32 v243, v118, v119
	v_cvt_pk_bf16_f32 v244, v120, v121
	v_cvt_pk_bf16_f32 v245, v122, v123
	v_cvt_pk_bf16_f32 v246, v124, v125
	v_cvt_pk_bf16_f32 v247, v100, v101
	global_store_dwordx2 v1, v[240:241], s[70:71]
	global_store_dwordx2 v1, v[242:243], s[70:71] offset:512
	global_store_dwordx2 v1, v[244:245], s[70:71] offset:1024
	global_store_dwordx2 v1, v[246:247], s[70:71] offset:1536
	s_add_u32 s55, s55, 8

; __device__ __forceinline__ float lo_bf(unsigned w) { return __uint_as_float(w << 16); }
; __device__ __forceinline__ float hi_bf(unsigned w) { return __uint_as_float(w & 0xffff0000u); }
; template <bool HAS_F, bool HAS_H>
; __device__ __forceinline__ void phase_rows(const Params& p, int sp, int sn, float resw, bool from_input, bool write_x = true) {
;     ...
;             for (int j = 0; j < 4; ++j) { const u32x2 w = *(const u32x2*)(F + (size_t)row * D + 4 * lane + 256 * j);
;                 f[j] = (f32x4){lo_bf(w.x), hi_bf(w.x), lo_bf(w.y), hi_bf(w.y)}; ss += (f[j].x * f[j].x + f[j].y * f[j].y) + (f[j].z * f[j].z + f[j].w * f[j].w); }
;             const float rs = 1.0f / sqrtf(wave_sum(ss) * (1.0f / D) + EPS) * resw;
;             const float* gate = mod + b * 9216 + sp * 3072 + 2048; const float* gp = p.in[7] + sp * D;
; #pragma unroll
;             for (int j = 0; j < 4; ++j) { const f32x4 g = *(const f32x4*)(gate + 4 * lane + 256 * j), q = *(const f32x4*)(gp + 4 * lane + 256 * j);
;                 v[j] = v[j] + g * (f[j] * rs * q);
;                 if (write_x) *(f32x4*)(p.out + (size_t)row * D + 4 * lane + 256 * j) = v[j]; }
;         }
;         if (HAS_H) {
;             float ss = 0.f;
; #pragma unroll
;             for (int j = 0; j < 4; ++j) ss += (v[j].x * v[j].x + v[j].y * v[j].y) + (v[j].z * v[j].z + v[j].w * v[j].w);
;             const float rs = 1.0f / sqrtf(wave_sum(ss) * (1.0f / D) + EPS);
.Lrp4_pk7:
	s_waitcnt vmcnt(32)
	v_lshlrev_b32_e32 v112, 16, v20
	v_and_b32_e32 v113, 0xffff0000, v20
	v_lshlrev_b32_e32 v114, 16, v21
	v_and_b32_e32 v115, 0xffff0000, v21
	v_lshlrev_b32_e32 v116, 16, v22
	v_and_b32_e32 v117, 0xffff0000, v22
	v_lshlrev_b32_e32 v118, 16, v23
	v_and_b32_e32 v119, 0xffff0000, v23
	v_lshlrev_b32_e32 v120, 16, v24
	v_and_b32_e32 v121, 0xffff0000, v24
	v_lshlrev_b32_e32 v122, 16, v25
	v_and_b32_e32 v123, 0xffff0000, v25
	v_lshlrev_b32_e32 v124, 16, v26
	v_and_b32_e32 v125, 0xffff0000, v26
	v_lshlrev_b32_e32 v100, 16, v27
	v_and_b32_e32 v101, 0xffff0000, v27
	v_pk_mul_f32 v[102:103], v[112:113], v[112:113]
	v_pk_mul_f32 v[106:107], v[114:115], v[114:115]
	v_pk_fma_f32 v[102:103], v[116:117], v[116:117], v[102:103]
	v_pk_fma_f32 v[106:107], v[118:119], v[118:119], v[106:107]
	v_pk_fma_f32 v[102:103], v[120:121], v[120:121], v[102:103]
	v_pk_fma_f32 v[106:107], v[122:123], v[122:123], v[106:107]
	v_pk_fma_f32 v[102:103], v[124:125], v[124:125], v[102:103]
	v_pk_fma_f32 v[106:107], v[100:101], v[100:101], v[106:107]
	v_pk_add_f32 v[102:103], v[102:103], v[106:107]
	v_add_f32_e32 v102, v102, v103
	s_nop 1
	v_add_f32_dpp v102, v102, v102 quad_perm:[1,0,3,2] row_mask:0xf bank_mask:0xf
	s_nop 1
	v_add_f32_dpp v102, v102, v102 quad_perm:[2,3,0,1] row_mask:0xf bank_mask:0xf
	s_nop 1
	v_add_f32_dpp v102, v102, v102 row_half_mirror row_mask:0xf bank_mask:0xf
	s_nop 1
	v_add_f32_dpp v102, v102, v102 row_mirror row_mask:0xf bank_mask:0xf
	s_nop 1
	v_add_f32_dpp v102, v102, v102 row_bcast:15 row_mask:0xa bank_mask:0xf
	s_nop 1
	v_add_f32_dpp v102, v102, v102 row_bcast:31 row_mask:0xc bank_mask:0xf
	s_nop 1
	v_readlane_b32 s74, v102, 63
	s_nop 2
	v_mov_b32_e32 v102, s74
	v_fmamk_f32 v102, v102, 0x3a800000, v2
	v_mul_f32_e32 v103, 0x4f800000, v102
	v_cmp_gt_f32_e32 vcc, 0xf800000, v102
	s_nop 1
	v_cndmask_b32_e32 v102, v102, v103, vcc
	v_sqrt_f32_e32 v103, v102
	s_nop 0
	v_add_u32_e32 v104, -1, v103
	v_add_u32_e32 v106, 1, v103
	v_fma_f32 v107, -v104, v103, v102
	v_fma_f32 v108, -v106, v103, v102
	v_cmp_ge_f32_e64 s[76:77], 0, v107
	s_nop 1
	v_cndmask_b32_e64 v103, v103, v104, s[76:77]
	v_cmp_lt_f32_e64 s[76:77], 0, v108
	s_nop 1
	v_cndmask_b32_e64 v103, v103, v106, s[76:77]
	v_mul_f32_e32 v104, 0x37800000, v103
	v_cndmask_b32_e32 v103, v103, v104, vcc
	v_cmp_class_f32_e32 vcc, v102, v3
	s_nop 1
	v_cndmask_b32_e32 v102, v103, v102, vcc
	v_div_scale_f32 v103, s[76:77], v102, v102, 1.0
	v_rcp_f32_e32 v104, v103
	v_div_scale_f32 v106, vcc, 1.0, v102, 1.0
	v_fma_f32 v107, -v103, v104, 1.0
	v_fmac_f32_e32 v104, v107, v104
	v_mul_f32_e32 v107, v106, v104
	v_fma_f32 v108, -v103, v107, v106
	v_fmac_f32_e32 v107, v108, v104
	v_fma_f32 v103, -v103, v107, v106
	v_div_fmas_f32 v103, v103, v104, v107
	v_div_fixup_f32 v110, v103, v102, 1.0
	v_mul_f32_e32 v110, 0.5, v110
	v_pk_mul_f32 v[112:113], v[112:113], v[110:111] op_sel_hi:[1,0]
	v_pk_mul_f32 v[114:115], v[114:115], v[110:111] op_sel_hi:[1,0]
	v_pk_mul_f32 v[116:117], v[116:117], v[110:111] op_sel_hi:[1,0]
	v_pk_mul_f32 v[118:119], v[118:119], v[110:111] op_sel_hi:[1,0]
	v_pk_mul_f32 v[120:121], v[120:121], v[110:111] op_sel_hi:[1,0]
	v_pk_mul_f32 v[122:123], v[122:123], v[110:111] op_sel_hi:[1,0]
	v_pk_mul_f32 v[124:125], v[124:125], v[110:111] op_sel_hi:[1,0]
	v_pk_mul_f32 v[100:101], v[100:101], v[110:111] op_sel_hi:[1,0]
	v_pk_mul_f32 v[112:113], v[176:177], v[112:113]
	v_pk_mul_f32 v[114:115], v[178:179], v[114:115]
	v_pk_mul_f32 v[116:117], v[180:181], v[116:117]
	v_pk_mul_f32 v[118:119], v[182:183], v[118:119]
	v_pk_mul_f32 v[120:121], v[184:185], v[120:121]
	v_pk_mul_f32 v[122:123], v[186:187], v[122:123]
	v_pk_mul_f32 v[124:125], v[188:189], v[124:125]
	v_pk_mul_f32 v[100:101], v[190:191], v[100:101]
	v_pk_fma_f32 v[4:5], v[160:161], v[112:113], v[4:5]
	v_pk_fma_f32 v[6:7], v[162:163], v[114:115], v[6:7]
	v_pk_fma_f32 v[8:9], v[164:165], v[116:117], v[8:9]
	v_pk_fma_f32 v[10:11], v[166:167], v[118:119], v[10:11]
	v_pk_fma_f32 v[12:13], v[168:169], v[120:121], v[12:13]
	v_pk_fma_f32 v[14:15], v[170:171], v[122:123], v[14:15]
	v_pk_fma_f32 v[16:17], v[172:173], v[124:125], v[16:17]
	v_pk_fma_f32 v[18:19], v[174:175], v[100:101], v[18:19]
	s_lshl_b32 s60, s55, 12
	s_add_u32 s72, s84, s60
	s_addc_u32 s73, s85, 0
	global_store_dwordx4 v0, v[4:7], s[72:73] sc1
	global_store_dwordx4 v0, v[8:11], s[72:73] offset:1024 sc1
	global_store_dwordx4 v0, v[12:15], s[72:73] offset:2048 sc1
	global_store_dwordx4 v0, v[16:19], s[72:73] offset:3072 sc1
	v_pk_mul_f32 v[102:103], v[4:5], v[4:5]
	v_pk_mul_f32 v[106:107], v[6:7], v[6:7]
	v_pk_fma_f32 v[102:103], v[8:9], v[8:9], v[102:103]
	v_pk_fma_f32 v[106:107], v[10:11], v[10:11], v[106:107]
	v_pk_fma_f32 v[102:103], v[12:13], v[12:13], v[102:103]
	v_pk_fma_f32 v[106:107], v[14:15], v[14:15], v[106:107]
	v_pk_fma_f32 v[102:103], v[16:17], v[16:17], v[102:103]
	v_pk_fma_f32 v[106:107], v[18:19], v[18:19], v[106:107]
	v_pk_add_f32 v[102:103], v[102:103], v[106:107]
	v_add_f32_e32 v102, v102, v103
	s_nop 1
	v_add_f32_dpp v102, v102, v102 quad_perm:[1,0,3,2] row_mask:0xf bank_mask:0xf
	s_nop 1
	v_add_f32_dpp v102, v102, v102 quad_perm:[2,3,0,1] row_mask:0xf bank_mask:0xf
	s_nop 1
	v_add_f32_dpp v102, v102, v102 row_half_mirror row_mask:0xf bank_mask:0xf
	s_nop 1
	v_add_f32_dpp v102, v102, v102 row_mirror row_mask:0xf bank_mask:0xf
	s_nop 1
	v_add_f32_dpp v102, v102, v102 row_bcast:15 row_mask:0xa bank_mask:0xf
	s_nop 1
	v_add_f32_dpp v102, v102, v102 row_bcast:31 row_mask:0xc bank_mask:0xf
	s_nop 1
	v_readlane_b32 s74, v102, 63
	s_nop 2
	v_mov_b32_e32 v102, s74
	v_fmamk_f32 v102, v102, 0x3a800000, v2
	v_mul_f32_e32 v103, 0x4f800000, v102
; __device__ __forceinline__ unsigned pk_bf16(float lo, float hi) { const f32x2 v = {lo, hi}; const bf16x2_t b = __builtin_convertvector(v, bf16x2_t); return __builtin_bit_cast(unsigned, b); }
; __device__ __forceinline__ float lo_bf(unsigned w) { return __uint_as_float(w << 16); }
; __device__ __forceinline__ float hi_bf(unsigned w) { return __uint_as_float(w & 0xffff0000u); }
; template <bool HAS_F, bool HAS_H>
; __device__ __forceinline__ void phase_rows(const Params& p, int sp, int sn, float resw, bool from_input, bool write_x = true) {
;     ...
;     for (int row = gw; row < T; row += NGW) {
;         const int b = row_batch(row);
;         const float* xin = !from_input ? p.out + (size_t)row * D : (row < TP ? p.in[0] + (size_t)row * D : p.in[1] + (size_t)(row - TP) * D);
;         f32x4 v[4];
; #pragma unroll
;         for (int j = 0; j < 4; ++j) v[j] = *(const f32x4*)(xin + 4 * lane + 256 * j);
;         if (HAS_F) {
;             f32x4 f[4]; float ss = 0.f;
; #pragma unroll
;             for (int j = 0; j < 4; ++j) { const u32x2 w = *(const u32x2*)(F + (size_t)row * D + 4 * lane + 256 * j);
;                 f[j] = (f32x4){lo_bf(w.x), hi_bf(w.x), lo_bf(w.y), hi_bf(w.y)}; ss += (f[j].x * f[j].x + f[j].y * f[j].y) + (f[j].z * f[j].z + f[j].w * f[j].w); }
;             const float rs = 1.0f / sqrtf(wave_sum(ss) * (1.0f / D) + EPS) * resw;
;             const float* gate = mod + b * 9216 + sp * 3072 + 2048; const float* gp = p.in[7] + sp * D;
; #pragma unroll
;             for (int j = 0; j < 4; ++j) { const f32x4 g = *(const f32x4*)(gate + 4 * lane + 256 * j), q = *(const f32x4*)(gp + 4 * lane + 256 * j);
;     ...
;             const float rs = 1.0f / sqrtf(wave_sum(ss) * (1.0f / D) + EPS);
;             const float* sh = mod + b * 9216 + sn * 3072; const float* scl = sh + 1024; const float* gq = p.in[6] + sn * D;
; #pragma unroll
;             for (int j = 0; j < 4; ++j) { const f32x4 a = *(const f32x4*)(sh + 4 * lane + 256 * j), s = *(const f32x4*)(scl + 4 * lane + 256 * j), q = *(const f32x4*)(gq + 4 * lane + 256 * j);
;                 const f32x4 h = (v[j] * rs * q) * (s + 1.0f) + a;
;                 u32x2 w; w.x = pk_bf16(h.x, h.y); w.y = pk_bf16(h.z, h.w);
;                 *(u32x2*)(H + (size_t)row * D + 4 * lane + 256 * j) = w; }
	v_cmp_gt_f32_e32 vcc, 0xf800000, v102
	s_nop 1
	v_cndmask_b32_e32 v102, v102, v103, vcc
	v_sqrt_f32_e32 v103, v102
	s_nop 0
	v_add_u32_e32 v104, -1, v103
	v_add_u32_e32 v106, 1, v103
	v_fma_f32 v107, -v104, v103, v102
	v_fma_f32 v108, -v106, v103, v102
	v_cmp_ge_f32_e64 s[76:77], 0, v107
	s_nop 1
	v_cndmask_b32_e64 v103, v103, v104, s[76:77]
	v_cmp_lt_f32_e64 s[76:77], 0, v108
	s_nop 1
	v_cndmask_b32_e64 v103, v103, v106, s[76:77]
	v_mul_f32_e32 v104, 0x37800000, v103
	v_cndmask_b32_e32 v103, v103, v104, vcc
	v_cmp_class_f32_e32 vcc, v102, v3
	s_nop 1
	v_cndmask_b32_e32 v102, v103, v102, vcc
	v_div_scale_f32 v103, s[76:77], v102, v102, 1.0
	v_rcp_f32_e32 v104, v103
	v_div_scale_f32 v106, vcc, 1.0, v102, 1.0
	v_fma_f32 v107, -v103, v104, 1.0
	v_fmac_f32_e32 v104, v107, v104
	v_mul_f32_e32 v107, v106, v104
	v_fma_f32 v108, -v103, v107, v106
	v_fmac_f32_e32 v107, v108, v104
	v_fma_f32 v103, -v103, v107, v106
	v_div_fmas_f32 v103, v103, v104, v107
	v_div_fixup_f32 v110, v103, v102, 1.0
	s_lshl_b32 s60, s55, 11
	s_add_u32 s70, s78, s60
	s_addc_u32 s71, s79, 0
	v_pk_mul_f32 v[112:113], v[4:5], v[110:111] op_sel_hi:[1,0]
	v_pk_mul_f32 v[114:115], v[6:7], v[110:111] op_sel_hi:[1,0]
	v_pk_mul_f32 v[116:117], v[8:9], v[110:111] op_sel_hi:[1,0]
	v_pk_mul_f32 v[118:119], v[10:11], v[110:111] op_sel_hi:[1,0]
	v_pk_mul_f32 v[120:121], v[12:13], v[110:111] op_sel_hi:[1,0]
	v_pk_mul_f32 v[122:123], v[14:15], v[110:111] op_sel_hi:[1,0]
	v_pk_mul_f32 v[124:125], v[16:17], v[110:111] op_sel_hi:[1,0]
	v_pk_mul_f32 v[100:101], v[18:19], v[110:111] op_sel_hi:[1,0]
	v_pk_mul_f32 v[112:113], v[192:193], v[112:113]
	v_pk_mul_f32 v[114:115], v[194:195], v[114:115]
	v_pk_mul_f32 v[116:117], v[196:197], v[116:117]
	v_pk_mul_f32 v[118:119], v[198:199], v[118:119]
	v_pk_mul_f32 v[120:121], v[200:201], v[120:121]
	v_pk_mul_f32 v[122:123], v[202:203], v[122:123]
	v_pk_mul_f32 v[124:125], v[204:205], v[124:125]
	v_pk_mul_f32 v[100:101], v[206:207], v[100:101]
	v_pk_fma_f32 v[112:113], v[208:209], v[112:113], v[224:225]
	v_pk_fma_f32 v[114:115], v[210:211], v[114:115], v[226:227]
	v_pk_fma_f32 v[116:117], v[212:213], v[116:117], v[228:229]
	v_pk_fma_f32 v[118:119], v[214:215], v[118:119], v[230:231]
	v_pk_fma_f32 v[120:121], v[216:217], v[120:121], v[232:233]
	v_pk_fma_f32 v[122:123], v[218:219], v[122:123], v[234:235]
	v_pk_fma_f32 v[124:125], v[220:221], v[124:125], v[236:237]
	v_pk_fma_f32 v[100:101], v[222:223], v[100:101], v[238:239]
	v_cvt_pk_bf16_f32 v240, v112, v113
	v_cvt_pk_bf16_f32 v241, v114, v115
	v_cvt_pk_bf16_f32 v242, v116, v117
	v_cvt_pk_bf16_f32 v243, v118, v119
	v_cvt_pk_bf16_f32 v244, v120, v121
	v_cvt_pk_bf16_f32 v245, v122, v123
	v_cvt_pk_bf16_f32 v246, v124, v125
	v_cvt_pk_bf16_f32 v247, v100, v101
	global_store_dwordx2 v1, v[240:241], s[70:71]
	global_store_dwordx2 v1, v[242:243], s[70:71] offset:512
	global_store_dwordx2 v1, v[244:245], s[70:71] offset:1024
	global_store_dwordx2 v1, v[246:247], s[70:71] offset:1536
	s_add_u32 s55, s55, 8
	s_add_u32 s57, s55, 16
	s_min_u32 s57, s57, s54
	s_cmp_lt_u32 s57, 0x8000
	s_cselect_b32 s64, s8, s10
	s_cselect_b32 s65, s9, s11
	s_cselect_b32 s60, 0, 0x8000
	s_sub_u32 s60, s57, s60
	s_lshl_b32 s60, s60, 12
	s_add_u32 s64, s64, s60
	s_addc_u32 s65, s65, 0
	s_lshl_b32 s60, s57, 11
	s_add_u32 s66, s82, s60
	s_addc_u32 s67, s83, 0
	global_load_dwordx4 v[4:7], v0, s[64:65] nt
	global_load_dwordx4 v[8:11], v0, s[64:65] offset:1024 nt
	global_load_dwordx4 v[12:15], v0, s[64:65] offset:2048 nt
	global_load_dwordx4 v[16:19], v0, s[64:65] offset:3072 nt
	global_load_dwordx2 v[20:21], v1, s[66:67] nt
	global_load_dwordx2 v[22:23], v1, s[66:67] offset:512 nt
	global_load_dwordx2 v[24:25], v1, s[66:67] offset:1024 nt
	global_load_dwordx2 v[26:27], v1, s[66:67] offset:1536 nt
	s_lshr_b32 s60, s55, 11
	s_sub_u32 s61, s55, 0x8000
	s_lshr_b32 s61, s61, 12
	s_add_u32 s61, s61, 16
	s_cmp_lt_u32 s55, 0x8000
	s_cselect_b32 s63, s60, s61
	s_cmp_eq_u32 s63, s56
	s_cbranch_scc1 .Lrp4_pk8
	s_mov_b32 s56, s63
	s_mul_i32 s60, s56, 0x9000
	s_add_u32 s60, s60, 0x3182000
	s_add_u32 s0, s92, s60
	s_addc_u32 s1, s93, 0
	global_load_dwordx4 v[160:163], v0, s[0:1]
	global_load_dwordx4 v[164:167], v0, s[0:1] offset:1024
	global_load_dwordx4 v[168:171], v0, s[0:1] offset:2048
	global_load_dwordx4 v[172:175], v0, s[0:1] offset:3072
	s_add_u32 s0, s22, 0x0
	s_addc_u32 s1, s23, 0
	global_load_dwordx4 v[176:179], v0, s[0:1]
	global_load_dwordx4 v[180:183], v0, s[0:1] offset:1024
	global_load_dwordx4 v[184:187], v0, s[0:1] offset:2048
	global_load_dwordx4 v[188:191], v0, s[0:1] offset:3072
	s_add_u32 s0, s20, 0x1000
	s_addc_u32 s1, s21, 0
	global_load_dwordx4 v[192:195], v0, s[0:1]
	global_load_dwordx4 v[196:199], v0, s[0:1] offset:1024
	global_load_dwordx4 v[200:203], v0, s[0:1] offset:2048
	global_load_dwordx4 v[204:207], v0, s[0:1] offset:3072
	s_mul_i32 s60, s56, 0x9000
	s_add_u32 s60, s60, 0x3184000
	s_add_u32 s0, s92, s60
	s_addc_u32 s1, s93, 0
	global_load_dwordx4 v[208:211], v0, s[0:1]
	global_load_dwordx4 v[212:215], v0, s[0:1] offset:1024
	global_load_dwordx4 v[216:219], v0, s[0:1] offset:2048
	global_load_dwordx4 v[220:223], v0, s[0:1] offset:3072
	s_mul_i32 s60, s56, 0x9000
	s_add_u32 s60, s60, 0x3183000
	s_add_u32 s0, s92, s60
	s_addc_u32 s1, s93, 0
	global_load_dwordx4 v[224:227], v0, s[0:1]
	global_load_dwordx4 v[228:231], v0, s[0:1] offset:1024
	global_load_dwordx4 v[232:235], v0, s[0:1] offset:2048
	global_load_dwordx4 v[236:239], v0, s[0:1] offset:3072
	s_waitcnt vmcnt(0)
	v_pk_add_f32 v[208:209], v[208:209], 1.0 op_sel_hi:[1,0]
	v_pk_add_f32 v[210:211], v[210:211], 1.0 op_sel_hi:[1,0]
	v_pk_add_f32 v[212:213], v[212:213], 1.0 op_sel_hi:[1,0]
	v_pk_add_f32 v[214:215], v[214:215], 1.0 op_sel_hi:[1,0]
	v_pk_add_f32 v[216:217], v[216:217], 1.0 op_sel_hi:[1,0]
	v_pk_add_f32 v[218:219], v[218:219], 1.0 op_sel_hi:[1,0]
	v_pk_add_f32 v[220:221], v[220:221], 1.0 op_sel_hi:[1,0]
	v_pk_add_f32 v[222:223], v[222:223], 1.0 op_sel_hi:[1,0]
; __device__ __forceinline__ float lo_bf(unsigned w) { return __uint_as_float(w << 16); }
; __device__ __forceinline__ float hi_bf(unsigned w) { return __uint_as_float(w & 0xffff0000u); }
; template <bool HAS_F, bool HAS_H>
; __device__ __forceinline__ void phase_rows(const Params& p, int sp, int sn, float resw, bool from_input, bool write_x = true) {
;     ...
;             for (int j = 0; j < 4; ++j) { const u32x2 w = *(const u32x2*)(F + (size_t)row * D + 4 * lane + 256 * j);
;                 f[j] = (f32x4){lo_bf(w.x), hi_bf(w.x), lo_bf(w.y), hi_bf(w.y)}; ss += (f[j].x * f[j].x + f[j].y * f[j].y) + (f[j].z * f[j].z + f[j].w * f[j].w); }
;             const float rs = 1.0f / sqrtf(wave_sum(ss) * (1.0f / D) + EPS) * resw;
;             const float* gate = mod + b * 9216 + sp * 3072 + 2048; const float* gp = p.in[7] + sp * D;
; #pragma unroll
;             for (int j = 0; j < 4; ++j) { const f32x4 g = *(const f32x4*)(gate + 4 * lane + 256 * j), q = *(const f32x4*)(gp + 4 * lane + 256 * j);
;                 v[j] = v[j] + g * (f[j] * rs * q);
;                 if (write_x) *(f32x4*)(p.out + (size_t)row * D + 4 * lane + 256 * j) = v[j]; }
;         }
;         if (HAS_H) {
;             float ss = 0.f;
; #pragma unroll
;             for (int j = 0; j < 4; ++j) ss += (v[j].x * v[j].x + v[j].y * v[j].y) + (v[j].z * v[j].z + v[j].w * v[j].w);
;             const float rs = 1.0f / sqrtf(wave_sum(ss) * (1.0f / D) + EPS);
.Lrp4_pk8:
	s_waitcnt vmcnt(32)
	v_lshlrev_b32_e32 v112, 16, v52
	v_and_b32_e32 v113, 0xffff0000, v52
	v_lshlrev_b32_e32 v114, 16, v53
	v_and_b32_e32 v115, 0xffff0000, v53
	v_lshlrev_b32_e32 v116, 16, v54
	v_and_b32_e32 v117, 0xffff0000, v54
	v_lshlrev_b32_e32 v118, 16, v55
	v_and_b32_e32 v119, 0xffff0000, v55
	v_lshlrev_b32_e32 v120, 16, v56
	v_and_b32_e32 v121, 0xffff0000, v56
	v_lshlrev_b32_e32 v122, 16, v57
	v_and_b32_e32 v123, 0xffff0000, v57
	v_lshlrev_b32_e32 v124, 16, v58
	v_and_b32_e32 v125, 0xffff0000, v58
	v_lshlrev_b32_e32 v100, 16, v59
	v_and_b32_e32 v101, 0xffff0000, v59
	v_pk_mul_f32 v[102:103], v[112:113], v[112:113]
	v_pk_mul_f32 v[106:107], v[114:115], v[114:115]
	v_pk_fma_f32 v[102:103], v[116:117], v[116:117], v[102:103]
	v_pk_fma_f32 v[106:107], v[118:119], v[118:119], v[106:107]
	v_pk_fma_f32 v[102:103], v[120:121], v[120:121], v[102:103]
	v_pk_fma_f32 v[106:107], v[122:123], v[122:123], v[106:107]
	v_pk_fma_f32 v[102:103], v[124:125], v[124:125], v[102:103]
	v_pk_fma_f32 v[106:107], v[100:101], v[100:101], v[106:107]
	v_pk_add_f32 v[102:103], v[102:103], v[106:107]
	v_add_f32_e32 v102, v102, v103
	s_nop 1
	v_add_f32_dpp v102, v102, v102 quad_perm:[1,0,3,2] row_mask:0xf bank_mask:0xf
	s_nop 1
	v_add_f32_dpp v102, v102, v102 quad_perm:[2,3,0,1] row_mask:0xf bank_mask:0xf
	s_nop 1
	v_add_f32_dpp v102, v102, v102 row_half_mirror row_mask:0xf bank_mask:0xf
	s_nop 1
	v_add_f32_dpp v102, v102, v102 row_mirror row_mask:0xf bank_mask:0xf
	s_nop 1
	v_add_f32_dpp v102, v102, v102 row_bcast:15 row_mask:0xa bank_mask:0xf
	s_nop 1
	v_add_f32_dpp v102, v102, v102 row_bcast:31 row_mask:0xc bank_mask:0xf
	s_nop 1
	v_readlane_b32 s74, v102, 63
	s_nop 2
	v_mov_b32_e32 v102, s74
	v_fmamk_f32 v102, v102, 0x3a800000, v2
	v_mul_f32_e32 v103, 0x4f800000, v102
	v_cmp_gt_f32_e32 vcc, 0xf800000, v102
	s_nop 1
	v_cndmask_b32_e32 v102, v102, v103, vcc
	v_sqrt_f32_e32 v103, v102
	s_nop 0
	v_add_u32_e32 v104, -1, v103
	v_add_u32_e32 v106, 1, v103
	v_fma_f32 v107, -v104, v103, v102
	v_fma_f32 v108, -v106, v103, v102
	v_cmp_ge_f32_e64 s[76:77], 0, v107
	s_nop 1
	v_cndmask_b32_e64 v103, v103, v104, s[76:77]
	v_cmp_lt_f32_e64 s[76:77], 0, v108
	s_nop 1
	v_cndmask_b32_e64 v103, v103, v106, s[76:77]
	v_mul_f32_e32 v104, 0x37800000, v103
	v_cndmask_b32_e32 v103, v103, v104, vcc
	v_cmp_class_f32_e32 vcc, v102, v3
	s_nop 1
	v_cndmask_b32_e32 v102, v103, v102, vcc
	v_div_scale_f32 v103, s[76:77], v102, v102, 1.0
	v_rcp_f32_e32 v104, v103
	v_div_scale_f32 v106, vcc, 1.0, v102, 1.0
	v_fma_f32 v107, -v103, v104, 1.0
	v_fmac_f32_e32 v104, v107, v104
	v_mul_f32_e32 v107, v106, v104
	v_fma_f32 v108, -v103, v107, v106
	v_fmac_f32_e32 v107, v108, v104
	v_fma_f32 v103, -v103, v107, v106
	v_div_fmas_f32 v103, v103, v104, v107
	v_div_fixup_f32 v110, v103, v102, 1.0
	v_mul_f32_e32 v110, 0.5, v110
	v_pk_mul_f32 v[112:113], v[112:113], v[110:111] op_sel_hi:[1,0]
	v_pk_mul_f32 v[114:115], v[114:115], v[110:111] op_sel_hi:[1,0]
	v_pk_mul_f32 v[116:117], v[116:117], v[110:111] op_sel_hi:[1,0]
	v_pk_mul_f32 v[118:119], v[118:119], v[110:111] op_sel_hi:[1,0]
	v_pk_mul_f32 v[120:121], v[120:121], v[110:111] op_sel_hi:[1,0]
	v_pk_mul_f32 v[122:123], v[122:123], v[110:111] op_sel_hi:[1,0]
	v_pk_mul_f32 v[124:125], v[124:125], v[110:111] op_sel_hi:[1,0]
	v_pk_mul_f32 v[100:101], v[100:101], v[110:111] op_sel_hi:[1,0]
	v_pk_mul_f32 v[112:113], v[176:177], v[112:113]
	v_pk_mul_f32 v[114:115], v[178:179], v[114:115]
	v_pk_mul_f32 v[116:117], v[180:181], v[116:117]
	v_pk_mul_f32 v[118:119], v[182:183], v[118:119]
	v_pk_mul_f32 v[120:121], v[184:185], v[120:121]
	v_pk_mul_f32 v[122:123], v[186:187], v[122:123]
	v_pk_mul_f32 v[124:125], v[188:189], v[124:125]
	v_pk_mul_f32 v[100:101], v[190:191], v[100:101]
	v_pk_fma_f32 v[36:37], v[160:161], v[112:113], v[36:37]
	v_pk_fma_f32 v[38:39], v[162:163], v[114:115], v[38:39]
	v_pk_fma_f32 v[40:41], v[164:165], v[116:117], v[40:41]
	v_pk_fma_f32 v[42:43], v[166:167], v[118:119], v[42:43]
	v_pk_fma_f32 v[44:45], v[168:169], v[120:121], v[44:45]
	v_pk_fma_f32 v[46:47], v[170:171], v[122:123], v[46:47]
	v_pk_fma_f32 v[48:49], v[172:173], v[124:125], v[48:49]
	v_pk_fma_f32 v[50:51], v[174:175], v[100:101], v[50:51]
	s_lshl_b32 s60, s55, 12
	s_add_u32 s72, s84, s60
	s_addc_u32 s73, s85, 0
	global_store_dwordx4 v0, v[36:39], s[72:73] sc1
	global_store_dwordx4 v0, v[40:43], s[72:73] offset:1024 sc1
	global_store_dwordx4 v0, v[44:47], s[72:73] offset:2048 sc1
	global_store_dwordx4 v0, v[48:51], s[72:73] offset:3072 sc1
	v_pk_mul_f32 v[102:103], v[36:37], v[36:37]
	v_pk_mul_f32 v[106:107], v[38:39], v[38:39]
	v_pk_fma_f32 v[102:103], v[40:41], v[40:41], v[102:103]
	v_pk_fma_f32 v[106:107], v[42:43], v[42:43], v[106:107]
	v_pk_fma_f32 v[102:103], v[44:45], v[44:45], v[102:103]
	v_pk_fma_f32 v[106:107], v[46:47], v[46:47], v[106:107]
	v_pk_fma_f32 v[102:103], v[48:49], v[48:49], v[102:103]
	v_pk_fma_f32 v[106:107], v[50:51], v[50:51], v[106:107]
	v_pk_add_f32 v[102:103], v[102:103], v[106:107]
	v_add_f32_e32 v102, v102, v103
	s_nop 1
	v_add_f32_dpp v102, v102, v102 quad_perm:[1,0,3,2] row_mask:0xf bank_mask:0xf
	s_nop 1
	v_add_f32_dpp v102, v102, v102 quad_perm:[2,3,0,1] row_mask:0xf bank_mask:0xf
	s_nop 1
	v_add_f32_dpp v102, v102, v102 row_half_mirror row_mask:0xf bank_mask:0xf
	s_nop 1
	v_add_f32_dpp v102, v102, v102 row_mirror row_mask:0xf bank_mask:0xf
	s_nop 1
	v_add_f32_dpp v102, v102, v102 row_bcast:15 row_mask:0xa bank_mask:0xf
	s_nop 1
	v_add_f32_dpp v102, v102, v102 row_bcast:31 row_mask:0xc bank_mask:0xf
	s_nop 1
	v_readlane_b32 s74, v102, 63
	s_nop 2
	v_mov_b32_e32 v102, s74
	v_fmamk_f32 v102, v102, 0x3a800000, v2
	v_mul_f32_e32 v103, 0x4f800000, v102
; __device__ __forceinline__ unsigned pk_bf16(float lo, float hi) { const f32x2 v = {lo, hi}; const bf16x2_t b = __builtin_convertvector(v, bf16x2_t); return __builtin_bit_cast(unsigned, b); }
; __device__ __forceinline__ float lo_bf(unsigned w) { return __uint_as_float(w << 16); }
; __device__ __forceinline__ float hi_bf(unsigned w) { return __uint_as_float(w & 0xffff0000u); }
; template <bool HAS_F, bool HAS_H>
; __device__ __forceinline__ void phase_rows(const Params& p, int sp, int sn, float resw, bool from_input, bool write_x = true) {
;     ...
;     for (int row = gw; row < T; row += NGW) {
;         const int b = row_batch(row);
;         const float* xin = !from_input ? p.out + (size_t)row * D : (row < TP ? p.in[0] + (size_t)row * D : p.in[1] + (size_t)(row - TP) * D);
;         f32x4 v[4];
; #pragma unroll
;         for (int j = 0; j < 4; ++j) v[j] = *(const f32x4*)(xin + 4 * lane + 256 * j);
;         if (HAS_F) {
;             f32x4 f[4]; float ss = 0.f;
; #pragma unroll
;             for (int j = 0; j < 4; ++j) { const u32x2 w = *(const u32x2*)(F + (size_t)row * D + 4 * lane + 256 * j);
;                 f[j] = (f32x4){lo_bf(w.x), hi_bf(w.x), lo_bf(w.y), hi_bf(w.y)}; ss += (f[j].x * f[j].x + f[j].y * f[j].y) + (f[j].z * f[j].z + f[j].w * f[j].w); }
;             const float rs = 1.0f / sqrtf(wave_sum(ss) * (1.0f / D) + EPS) * resw;
;             const float* gate = mod + b * 9216 + sp * 3072 + 2048; const float* gp = p.in[7] + sp * D;
; #pragma unroll
;             for (int j = 0; j < 4; ++j) { const f32x4 g = *(const f32x4*)(gate + 4 * lane + 256 * j), q = *(const f32x4*)(gp + 4 * lane + 256 * j);
;     ...
;             const float rs = 1.0f / sqrtf(wave_sum(ss) * (1.0f / D) + EPS);
;             const float* sh = mod + b * 9216 + sn * 3072; const float* scl = sh + 1024; const float* gq = p.in[6] + sn * D;
; #pragma unroll
;             for (int j = 0; j < 4; ++j) { const f32x4 a = *(const f32x4*)(sh + 4 * lane + 256 * j), s = *(const f32x4*)(scl + 4 * lane + 256 * j), q = *(const f32x4*)(gq + 4 * lane + 256 * j);
;                 const f32x4 h = (v[j] * rs * q) * (s + 1.0f) + a;
;                 u32x2 w; w.x = pk_bf16(h.x, h.y); w.y = pk_bf16(h.z, h.w);
;                 *(u32x2*)(H + (size_t)row * D + 4 * lane + 256 * j) = w; }
	v_cmp_gt_f32_e32 vcc, 0xf800000, v102
	s_nop 1
	v_cndmask_b32_e32 v102, v102, v103, vcc
	v_sqrt_f32_e32 v103, v102
	s_nop 0
	v_add_u32_e32 v104, -1, v103
	v_add_u32_e32 v106, 1, v103
	v_fma_f32 v107, -v104, v103, v102
	v_fma_f32 v108, -v106, v103, v102
	v_cmp_ge_f32_e64 s[76:77], 0, v107
	s_nop 1
	v_cndmask_b32_e64 v103, v103, v104, s[76:77]
	v_cmp_lt_f32_e64 s[76:77], 0, v108
	s_nop 1
	v_cndmask_b32_e64 v103, v103, v106, s[76:77]
	v_mul_f32_e32 v104, 0x37800000, v103
	v_cndmask_b32_e32 v103, v103, v104, vcc
	v_cmp_class_f32_e32 vcc, v102, v3
	s_nop 1
	v_cndmask_b32_e32 v102, v103, v102, vcc
	v_div_scale_f32 v103, s[76:77], v102, v102, 1.0
	v_rcp_f32_e32 v104, v103
	v_div_scale_f32 v106, vcc, 1.0, v102, 1.0
	v_fma_f32 v107, -v103, v104, 1.0
	v_fmac_f32_e32 v104, v107, v104
	v_mul_f32_e32 v107, v106, v104
	v_fma_f32 v108, -v103, v107, v106
	v_fmac_f32_e32 v107, v108, v104
	v_fma_f32 v103, -v103, v107, v106
	v_div_fmas_f32 v103, v103, v104, v107
	v_div_fixup_f32 v110, v103, v102, 1.0
	s_lshl_b32 s60, s55, 11
	s_add_u32 s70, s78, s60
	s_addc_u32 s71, s79, 0
	v_pk_mul_f32 v[112:113], v[36:37], v[110:111] op_sel_hi:[1,0]
	v_pk_mul_f32 v[114:115], v[38:39], v[110:111] op_sel_hi:[1,0]
	v_pk_mul_f32 v[116:117], v[40:41], v[110:111] op_sel_hi:[1,0]
	v_pk_mul_f32 v[118:119], v[42:43], v[110:111] op_sel_hi:[1,0]
	v_pk_mul_f32 v[120:121], v[44:45], v[110:111] op_sel_hi:[1,0]
	v_pk_mul_f32 v[122:123], v[46:47], v[110:111] op_sel_hi:[1,0]
	v_pk_mul_f32 v[124:125], v[48:49], v[110:111] op_sel_hi:[1,0]
	v_pk_mul_f32 v[100:101], v[50:51], v[110:111] op_sel_hi:[1,0]
	v_pk_mul_f32 v[112:113], v[192:193], v[112:113]
	v_pk_mul_f32 v[114:115], v[194:195], v[114:115]
	v_pk_mul_f32 v[116:117], v[196:197], v[116:117]
	v_pk_mul_f32 v[118:119], v[198:199], v[118:119]
	v_pk_mul_f32 v[120:121], v[200:201], v[120:121]
	v_pk_mul_f32 v[122:123], v[202:203], v[122:123]
	v_pk_mul_f32 v[124:125], v[204:205], v[124:125]
	v_pk_mul_f32 v[100:101], v[206:207], v[100:101]
	v_pk_fma_f32 v[112:113], v[208:209], v[112:113], v[224:225]
	v_pk_fma_f32 v[114:115], v[210:211], v[114:115], v[226:227]
	v_pk_fma_f32 v[116:117], v[212:213], v[116:117], v[228:229]
	v_pk_fma_f32 v[118:119], v[214:215], v[118:119], v[230:231]
	v_pk_fma_f32 v[120:121], v[216:217], v[120:121], v[232:233]
	v_pk_fma_f32 v[122:123], v[218:219], v[122:123], v[234:235]
	v_pk_fma_f32 v[124:125], v[220:221], v[124:125], v[236:237]
	v_pk_fma_f32 v[100:101], v[222:223], v[100:101], v[238:239]
	v_cvt_pk_bf16_f32 v240, v112, v113
	v_cvt_pk_bf16_f32 v241, v114, v115
	v_cvt_pk_bf16_f32 v242, v116, v117
	v_cvt_pk_bf16_f32 v243, v118, v119
	v_cvt_pk_bf16_f32 v244, v120, v121
	v_cvt_pk_bf16_f32 v245, v122, v123
	v_cvt_pk_bf16_f32 v246, v124, v125
	v_cvt_pk_bf16_f32 v247, v100, v101
	global_store_dwordx2 v1, v[240:241], s[70:71]
	global_store_dwordx2 v1, v[242:243], s[70:71] offset:512
	global_store_dwordx2 v1, v[244:245], s[70:71] offset:1024
	global_store_dwordx2 v1, v[246:247], s[70:71] offset:1536
	s_add_u32 s55, s55, 8
	s_add_u32 s57, s55, 16
	s_min_u32 s57, s57, s54
	s_cmp_lt_u32 s57, 0x8000
	s_cselect_b32 s64, s8, s10
	s_cselect_b32 s65, s9, s11
	s_cselect_b32 s60, 0, 0x8000
	s_sub_u32 s60, s57, s60
	s_lshl_b32 s60, s60, 12
	s_add_u32 s64, s64, s60
	s_addc_u32 s65, s65, 0
	s_lshl_b32 s60, s57, 11
	s_add_u32 s66, s82, s60
	s_addc_u32 s67, s83, 0
	global_load_dwordx4 v[36:39], v0, s[64:65] nt
	global_load_dwordx4 v[40:43], v0, s[64:65] offset:1024 nt
	global_load_dwordx4 v[44:47], v0, s[64:65] offset:2048 nt
	global_load_dwordx4 v[48:51], v0, s[64:65] offset:3072 nt
	global_load_dwordx2 v[52:53], v1, s[66:67] nt
	global_load_dwordx2 v[54:55], v1, s[66:67] offset:512 nt
	global_load_dwordx2 v[56:57], v1, s[66:67] offset:1024 nt
	global_load_dwordx2 v[58:59], v1, s[66:67] offset:1536 nt
	s_lshr_b32 s60, s55, 11
	s_sub_u32 s61, s55, 0x8000
	s_lshr_b32 s61, s61, 12
	s_add_u32 s61, s61, 16
	s_cmp_lt_u32 s55, 0x8000
	s_cselect_b32 s63, s60, s61
	s_cmp_eq_u32 s63, s56
	s_cbranch_scc1 .Lrp4_pk9
	s_mov_b32 s56, s63
	s_mul_i32 s60, s56, 0x9000
	s_add_u32 s60, s60, 0x3182000
	s_add_u32 s0, s92, s60
	s_addc_u32 s1, s93, 0
	global_load_dwordx4 v[160:163], v0, s[0:1]
	global_load_dwordx4 v[164:167], v0, s[0:1] offset:1024
	global_load_dwordx4 v[168:171], v0, s[0:1] offset:2048
	global_load_dwordx4 v[172:175], v0, s[0:1] offset:3072
	s_add_u32 s0, s22, 0x0
	s_addc_u32 s1, s23, 0
	global_load_dwordx4 v[176:179], v0, s[0:1]
	global_load_dwordx4 v[180:183], v0, s[0:1] offset:1024
	global_load_dwordx4 v[184:187], v0, s[0:1] offset:2048
	global_load_dwordx4 v[188:191], v0, s[0:1] offset:3072
	s_add_u32 s0, s20, 0x1000
	s_addc_u32 s1, s21, 0
	global_load_dwordx4 v[192:195], v0, s[0:1]
	global_load_dwordx4 v[196:199], v0, s[0:1] offset:1024
	global_load_dwordx4 v[200:203], v0, s[0:1] offset:2048
	global_load_dwordx4 v[204:207], v0, s[0:1] offset:3072
	s_mul_i32 s60, s56, 0x9000
	s_add_u32 s60, s60, 0x3184000
	s_add_u32 s0, s92, s60
	s_addc_u32 s1, s93, 0
	global_load_dwordx4 v[208:211], v0, s[0:1]
	global_load_dwordx4 v[212:215], v0, s[0:1] offset:1024
	global_load_dwordx4 v[216:219], v0, s[0:1] offset:2048
	global_load_dwordx4 v[220:223], v0, s[0:1] offset:3072
	s_mul_i32 s60, s56, 0x9000
	s_add_u32 s60, s60, 0x3183000
	s_add_u32 s0, s92, s60
	s_addc_u32 s1, s93, 0
	global_load_dwordx4 v[224:227], v0, s[0:1]
	global_load_dwordx4 v[228:231], v0, s[0:1] offset:1024
	global_load_dwordx4 v[232:235], v0, s[0:1] offset:2048
	global_load_dwordx4 v[236:239], v0, s[0:1] offset:3072
	s_waitcnt vmcnt(0)
	v_pk_add_f32 v[208:209], v[208:209], 1.0 op_sel_hi:[1,0]
	v_pk_add_f32 v[210:211], v[210:211], 1.0 op_sel_hi:[1,0]
	v_pk_add_f32 v[212:213], v[212:213], 1.0 op_sel_hi:[1,0]
	v_pk_add_f32 v[214:215], v[214:215], 1.0 op_sel_hi:[1,0]
	v_pk_add_f32 v[216:217], v[216:217], 1.0 op_sel_hi:[1,0]
	v_pk_add_f32 v[218:219], v[218:219], 1.0 op_sel_hi:[1,0]
	v_pk_add_f32 v[220:221], v[220:221], 1.0 op_sel_hi:[1,0]
	v_pk_add_f32 v[222:223], v[222:223], 1.0 op_sel_hi:[1,0]
; __device__ __forceinline__ float lo_bf(unsigned w) { return __uint_as_float(w << 16); }
; __device__ __forceinline__ float hi_bf(unsigned w) { return __uint_as_float(w & 0xffff0000u); }
; template <bool HAS_F, bool HAS_H>
; __device__ __forceinline__ void phase_rows(const Params& p, int sp, int sn, float resw, bool from_input, bool write_x = true) {
;     ...
;             for (int j = 0; j < 4; ++j) { const u32x2 w = *(const u32x2*)(F + (size_t)row * D + 4 * lane + 256 * j);
;                 f[j] = (f32x4){lo_bf(w.x), hi_bf(w.x), lo_bf(w.y), hi_bf(w.y)}; ss += (f[j].x * f[j].x + f[j].y * f[j].y) + (f[j].z * f[j].z + f[j].w * f[j].w); }
;             const float rs = 1.0f / sqrtf(wave_sum(ss) * (1.0f / D) + EPS) * resw;
;             const float* gate = mod + b * 9216 + sp * 3072 + 2048; const float* gp = p.in[7] + sp * D;
; #pragma unroll
;             for (int j = 0; j < 4; ++j) { const f32x4 g = *(const f32x4*)(gate + 4 * lane + 256 * j), q = *(const f32x4*)(gp + 4 * lane + 256 * j);
;                 v[j] = v[j] + g * (f[j] * rs * q);
;                 if (write_x) *(f32x4*)(p.out + (size_t)row * D + 4 * lane + 256 * j) = v[j]; }
.Lrp4_pk9:
	s_waitcnt vmcnt(32)
	v_lshlrev_b32_e32 v112, 16, v84
	v_and_b32_e32 v113, 0xffff0000, v84
	v_lshlrev_b32_e32 v114, 16, v85
	v_and_b32_e32 v115, 0xffff0000, v85
	v_lshlrev_b32_e32 v116, 16, v86
	v_and_b32_e32 v117, 0xffff0000, v86
	v_lshlrev_b32_e32 v118, 16, v87
	v_and_b32_e32 v119, 0xffff0000, v87
	v_lshlrev_b32_e32 v120, 16, v88
	v_and_b32_e32 v121, 0xffff0000, v88
	v_lshlrev_b32_e32 v122, 16, v89
	v_and_b32_e32 v123, 0xffff0000, v89
	v_lshlrev_b32_e32 v124, 16, v90
	v_and_b32_e32 v125, 0xffff0000, v90
	v_lshlrev_b32_e32 v100, 16, v91
	v_and_b32_e32 v101, 0xffff0000, v91
	v_pk_mul_f32 v[102:103], v[112:113], v[112:113]
	v_pk_mul_f32 v[106:107], v[114:115], v[114:115]
	v_pk_fma_f32 v[102:103], v[116:117], v[116:117], v[102:103]
	v_pk_fma_f32 v[106:107], v[118:119], v[118:119], v[106:107]
	v_pk_fma_f32 v[102:103], v[120:121], v[120:121], v[102:103]
	v_pk_fma_f32 v[106:107], v[122:123], v[122:123], v[106:107]
	v_pk_fma_f32 v[102:103], v[124:125], v[124:125], v[102:103]
	v_pk_fma_f32 v[106:107], v[100:101], v[100:101], v[106:107]
	v_pk_add_f32 v[102:103], v[102:103], v[106:107]
	v_add_f32_e32 v102, v102, v103
	s_nop 1
	v_add_f32_dpp v102, v102, v102 quad_perm:[1,0,3,2] row_mask:0xf bank_mask:0xf
	s_nop 1
	v_add_f32_dpp v102, v102, v102 quad_perm:[2,3,0,1] row_mask:0xf bank_mask:0xf
	s_nop 1
	v_add_f32_dpp v102, v102, v102 row_half_mirror row_mask:0xf bank_mask:0xf
	s_nop 1
	v_add_f32_dpp v102, v102, v102 row_mirror row_mask:0xf bank_mask:0xf
	s_nop 1
	v_add_f32_dpp v102, v102, v102 row_bcast:15 row_mask:0xa bank_mask:0xf
	s_nop 1
	v_add_f32_dpp v102, v102, v102 row_bcast:31 row_mask:0xc bank_mask:0xf
	s_nop 1
	v_readlane_b32 s74, v102, 63
	s_nop 2
	v_mov_b32_e32 v102, s74
	v_fmamk_f32 v102, v102, 0x3a800000, v2
	v_mul_f32_e32 v103, 0x4f800000, v102
	v_cmp_gt_f32_e32 vcc, 0xf800000, v102
	s_nop 1
	v_cndmask_b32_e32 v102, v102, v103, vcc
	v_sqrt_f32_e32 v103, v102
	s_nop 0
	v_add_u32_e32 v104, -1, v103
	v_add_u32_e32 v106, 1, v103
	v_fma_f32 v107, -v104, v103, v102
	v_fma_f32 v108, -v106, v103, v102
	v_cmp_ge_f32_e64 s[76:77], 0, v107
	s_nop 1
	v_cndmask_b32_e64 v103, v103, v104, s[76:77]
	v_cmp_lt_f32_e64 s[76:77], 0, v108
	s_nop 1
	v_cndmask_b32_e64 v103, v103, v106, s[76:77]
	v_mul_f32_e32 v104, 0x37800000, v103
	v_cndmask_b32_e32 v103, v103, v104, vcc
	v_cmp_class_f32_e32 vcc, v102, v3
	s_nop 1
	v_cndmask_b32_e32 v102, v103, v102, vcc
	v_div_scale_f32 v103, s[76:77], v102, v102, 1.0
	v_rcp_f32_e32 v104, v103
	v_div_scale_f32 v106, vcc, 1.0, v102, 1.0
	v_fma_f32 v107, -v103, v104, 1.0
	v_fmac_f32_e32 v104, v107, v104
	v_mul_f32_e32 v107, v106, v104
	v_fma_f32 v108, -v103, v107, v106
	v_fmac_f32_e32 v107, v108, v104
	v_fma_f32 v103, -v103, v107, v106
	v_div_fmas_f32 v103, v103, v104, v107
	v_div_fixup_f32 v110, v103, v102, 1.0
	v_mul_f32_e32 v110, 0.5, v110
	v_pk_mul_f32 v[112:113], v[112:113], v[110:111] op_sel_hi:[1,0]
	v_pk_mul_f32 v[114:115], v[114:115], v[110:111] op_sel_hi:[1,0]
	v_pk_mul_f32 v[116:117], v[116:117], v[110:111] op_sel_hi:[1,0]
	v_pk_mul_f32 v[118:119], v[118:119], v[110:111] op_sel_hi:[1,0]
	v_pk_mul_f32 v[120:121], v[120:121], v[110:111] op_sel_hi:[1,0]
	v_pk_mul_f32 v[122:123], v[122:123], v[110:111] op_sel_hi:[1,0]
	v_pk_mul_f32 v[124:125], v[124:125], v[110:111] op_sel_hi:[1,0]
	v_pk_mul_f32 v[100:101], v[100:101], v[110:111] op_sel_hi:[1,0]
	v_pk_mul_f32 v[112:113], v[176:177], v[112:113]
	v_pk_mul_f32 v[114:115], v[178:179], v[114:115]
	v_pk_mul_f32 v[116:117], v[180:181], v[116:117]
	v_pk_mul_f32 v[118:119], v[182:183], v[118:119]
	v_pk_mul_f32 v[120:121], v[184:185], v[120:121]
	v_pk_mul_f32 v[122:123], v[186:187], v[122:123]
	v_pk_mul_f32 v[124:125], v[188:189], v[124:125]
	v_pk_mul_f32 v[100:101], v[190:191], v[100:101]
	v_pk_fma_f32 v[68:69], v[160:161], v[112:113], v[68:69]
	v_pk_fma_f32 v[70:71], v[162:163], v[114:115], v[70:71]
	v_pk_fma_f32 v[72:73], v[164:165], v[116:117], v[72:73]
	v_pk_fma_f32 v[74:75], v[166:167], v[118:119], v[74:75]
	v_pk_fma_f32 v[76:77], v[168:169], v[120:121], v[76:77]
	v_pk_fma_f32 v[78:79], v[170:171], v[122:123], v[78:79]
	v_pk_fma_f32 v[80:81], v[172:173], v[124:125], v[80:81]
	v_pk_fma_f32 v[82:83], v[174:175], v[100:101], v[82:83]
	s_lshl_b32 s60, s55, 12
	s_add_u32 s72, s84, s60
	s_addc_u32 s73, s85, 0
	global_store_dwordx4 v0, v[68:71], s[72:73] sc1
	global_store_dwordx4 v0, v[72:75], s[72:73] offset:1024 sc1
; __device__ __forceinline__ unsigned pk_bf16(float lo, float hi) { const f32x2 v = {lo, hi}; const bf16x2_t b = __builtin_convertvector(v, bf16x2_t); return __builtin_bit_cast(unsigned, b); }
; template <bool HAS_F, bool HAS_H>
; __device__ __forceinline__ void phase_rows(const Params& p, int sp, int sn, float resw, bool from_input, bool write_x = true) {
;     ...
;                 if (write_x) *(f32x4*)(p.out + (size_t)row * D + 4 * lane + 256 * j) = v[j]; }
;         }
;         if (HAS_H) {
;             float ss = 0.f;
; #pragma unroll
;             for (int j = 0; j < 4; ++j) ss += (v[j].x * v[j].x + v[j].y * v[j].y) + (v[j].z * v[j].z + v[j].w * v[j].w);
;             const float rs = 1.0f / sqrtf(wave_sum(ss) * (1.0f / D) + EPS);
;             const float* sh = mod + b * 9216 + sn * 3072; const float* scl = sh + 1024; const float* gq = p.in[6] + sn * D;
; #pragma unroll
;             for (int j = 0; j < 4; ++j) { const f32x4 a = *(const f32x4*)(sh + 4 * lane + 256 * j), s = *(const f32x4*)(scl + 4 * lane + 256 * j), q = *(const f32x4*)(gq + 4 * lane + 256 * j);
;                 const f32x4 h = (v[j] * rs * q) * (s + 1.0f) + a;
;                 u32x2 w; w.x = pk_bf16(h.x, h.y); w.y = pk_bf16(h.z, h.w);
;                 *(u32x2*)(H + (size_t)row * D + 4 * lane + 256 * j) = w; }
;         }
;     }
	global_store_dwordx4 v0, v[76:79], s[72:73] offset:2048 sc1
	global_store_dwordx4 v0, v[80:83], s[72:73] offset:3072 sc1
	v_pk_mul_f32 v[102:103], v[68:69], v[68:69]
	v_pk_mul_f32 v[106:107], v[70:71], v[70:71]
	v_pk_fma_f32 v[102:103], v[72:73], v[72:73], v[102:103]
	v_pk_fma_f32 v[106:107], v[74:75], v[74:75], v[106:107]
	v_pk_fma_f32 v[102:103], v[76:77], v[76:77], v[102:103]
	v_pk_fma_f32 v[106:107], v[78:79], v[78:79], v[106:107]
	v_pk_fma_f32 v[102:103], v[80:81], v[80:81], v[102:103]
	v_pk_fma_f32 v[106:107], v[82:83], v[82:83], v[106:107]
	v_pk_add_f32 v[102:103], v[102:103], v[106:107]
	v_add_f32_e32 v102, v102, v103
	s_nop 1
	v_add_f32_dpp v102, v102, v102 quad_perm:[1,0,3,2] row_mask:0xf bank_mask:0xf
	s_nop 1
	v_add_f32_dpp v102, v102, v102 quad_perm:[2,3,0,1] row_mask:0xf bank_mask:0xf
	s_nop 1
	v_add_f32_dpp v102, v102, v102 row_half_mirror row_mask:0xf bank_mask:0xf
	s_nop 1
	v_add_f32_dpp v102, v102, v102 row_mirror row_mask:0xf bank_mask:0xf
	s_nop 1
	v_add_f32_dpp v102, v102, v102 row_bcast:15 row_mask:0xa bank_mask:0xf
	s_nop 1
	v_add_f32_dpp v102, v102, v102 row_bcast:31 row_mask:0xc bank_mask:0xf
	s_nop 1
	v_readlane_b32 s74, v102, 63
	s_nop 2
	v_mov_b32_e32 v102, s74
	v_fmamk_f32 v102, v102, 0x3a800000, v2
	v_mul_f32_e32 v103, 0x4f800000, v102
	v_cmp_gt_f32_e32 vcc, 0xf800000, v102
	s_nop 1
	v_cndmask_b32_e32 v102, v102, v103, vcc
	v_sqrt_f32_e32 v103, v102
	s_nop 0
	v_add_u32_e32 v104, -1, v103
	v_add_u32_e32 v106, 1, v103
	v_fma_f32 v107, -v104, v103, v102
	v_fma_f32 v108, -v106, v103, v102
	v_cmp_ge_f32_e64 s[76:77], 0, v107
	s_nop 1
	v_cndmask_b32_e64 v103, v103, v104, s[76:77]
	v_cmp_lt_f32_e64 s[76:77], 0, v108
	s_nop 1
	v_cndmask_b32_e64 v103, v103, v106, s[76:77]
	v_mul_f32_e32 v104, 0x37800000, v103
	v_cndmask_b32_e32 v103, v103, v104, vcc
	v_cmp_class_f32_e32 vcc, v102, v3
	s_nop 1
	v_cndmask_b32_e32 v102, v103, v102, vcc
	v_div_scale_f32 v103, s[76:77], v102, v102, 1.0
	v_rcp_f32_e32 v104, v103
	v_div_scale_f32 v106, vcc, 1.0, v102, 1.0
	v_fma_f32 v107, -v103, v104, 1.0
	v_fmac_f32_e32 v104, v107, v104
	v_mul_f32_e32 v107, v106, v104
	v_fma_f32 v108, -v103, v107, v106
	v_fmac_f32_e32 v107, v108, v104
	v_fma_f32 v103, -v103, v107, v106
	v_div_fmas_f32 v103, v103, v104, v107
	v_div_fixup_f32 v110, v103, v102, 1.0
	s_lshl_b32 s60, s55, 11
	s_add_u32 s70, s78, s60
	s_addc_u32 s71, s79, 0
	v_pk_mul_f32 v[112:113], v[68:69], v[110:111] op_sel_hi:[1,0]
	v_pk_mul_f32 v[114:115], v[70:71], v[110:111] op_sel_hi:[1,0]
	v_pk_mul_f32 v[116:117], v[72:73], v[110:111] op_sel_hi:[1,0]
	v_pk_mul_f32 v[118:119], v[74:75], v[110:111] op_sel_hi:[1,0]
	v_pk_mul_f32 v[120:121], v[76:77], v[110:111] op_sel_hi:[1,0]
	v_pk_mul_f32 v[122:123], v[78:79], v[110:111] op_sel_hi:[1,0]
	v_pk_mul_f32 v[124:125], v[80:81], v[110:111] op_sel_hi:[1,0]
	v_pk_mul_f32 v[100:101], v[82:83], v[110:111] op_sel_hi:[1,0]
	v_pk_mul_f32 v[112:113], v[192:193], v[112:113]
	v_pk_mul_f32 v[114:115], v[194:195], v[114:115]
	v_pk_mul_f32 v[116:117], v[196:197], v[116:117]
	v_pk_mul_f32 v[118:119], v[198:199], v[118:119]
	v_pk_mul_f32 v[120:121], v[200:201], v[120:121]
	v_pk_mul_f32 v[122:123], v[202:203], v[122:123]
	v_pk_mul_f32 v[124:125], v[204:205], v[124:125]
	v_pk_mul_f32 v[100:101], v[206:207], v[100:101]
	v_pk_fma_f32 v[112:113], v[208:209], v[112:113], v[224:225]
	v_pk_fma_f32 v[114:115], v[210:211], v[114:115], v[226:227]
	v_pk_fma_f32 v[116:117], v[212:213], v[116:117], v[228:229]
	v_pk_fma_f32 v[118:119], v[214:215], v[118:119], v[230:231]
	v_pk_fma_f32 v[120:121], v[216:217], v[120:121], v[232:233]
	v_pk_fma_f32 v[122:123], v[218:219], v[122:123], v[234:235]
	v_pk_fma_f32 v[124:125], v[220:221], v[124:125], v[236:237]
	v_pk_fma_f32 v[100:101], v[222:223], v[100:101], v[238:239]
	v_cvt_pk_bf16_f32 v240, v112, v113
	v_cvt_pk_bf16_f32 v241, v114, v115
	v_cvt_pk_bf16_f32 v242, v116, v117
	v_cvt_pk_bf16_f32 v243, v118, v119
	v_cvt_pk_bf16_f32 v244, v120, v121
	v_cvt_pk_bf16_f32 v245, v122, v123
	v_cvt_pk_bf16_f32 v246, v124, v125
	v_cvt_pk_bf16_f32 v247, v100, v101
	global_store_dwordx2 v1, v[240:241], s[70:71]
	global_store_dwordx2 v1, v[242:243], s[70:71] offset:512
	global_store_dwordx2 v1, v[244:245], s[70:71] offset:1024
	global_store_dwordx2 v1, v[246:247], s[70:71] offset:1536
	s_add_u32 s55, s55, 8
	s_cmp_le_u32 s55, s54
	s_cbranch_scc1 .Lrp4_loop3
	s_add_u32 s51, s51, s52
	s_branch .Lrp4_chunk1

; __device__ __forceinline__ float lo_bf(unsigned w) { return __uint_as_float(w << 16); }
; __device__ __forceinline__ float hi_bf(unsigned w) { return __uint_as_float(w & 0xffff0000u); }
; __device__ __forceinline__ void phase_final(const Params& p) {
;     ...
;         for (int j = 0; j < 4; ++j) { v[j] = *(const f32x4*)(p.out + (size_t)row * D + 4 * lane + 256 * j);
;             const u32x2 wm = *(const u32x2*)(Fm + (size_t)row * D + 4 * lane + 256 * j), wf = *(const u32x2*)(F2 + (size_t)row * D + 4 * lane + 256 * j);
;             m[j] = (f32x4){lo_bf(wm.x), hi_bf(wm.x), lo_bf(wm.y), hi_bf(wm.y)}; f[j] = (f32x4){lo_bf(wf.x), hi_bf(wf.x), lo_bf(wf.y), hi_bf(wf.y)};
;             sm += (m[j].x * m[j].x + m[j].y * m[j].y) + (m[j].z * m[j].z + m[j].w * m[j].w); sf += (f[j].x * f[j].x + f[j].y * f[j].y) + (f[j].z * f[j].z + f[j].w * f[j].w); }
;         const float rm = 1.0f / sqrtf(wave_sum(sm) * (1.0f / D) + EPS), rf = 1.0f / sqrtf(wave_sum(sf) * (1.0f / D) + EPS) * 0.5f;
.Lrp15_pk4:
	s_waitcnt vmcnt(24)
	v_lshlrev_b32_e32 v112, 16, v20
	v_and_b32_e32 v113, 0xffff0000, v20
	v_lshlrev_b32_e32 v114, 16, v21
	v_and_b32_e32 v115, 0xffff0000, v21
	v_lshlrev_b32_e32 v116, 16, v22
	v_and_b32_e32 v117, 0xffff0000, v22
	v_lshlrev_b32_e32 v118, 16, v23
	v_and_b32_e32 v119, 0xffff0000, v23
	v_lshlrev_b32_e32 v120, 16, v24
	v_and_b32_e32 v121, 0xffff0000, v24
	v_lshlrev_b32_e32 v122, 16, v25
	v_and_b32_e32 v123, 0xffff0000, v25
	v_lshlrev_b32_e32 v124, 16, v26
	v_and_b32_e32 v125, 0xffff0000, v26
	v_lshlrev_b32_e32 v100, 16, v27
	v_and_b32_e32 v101, 0xffff0000, v27
	v_pk_mul_f32 v[102:103], v[112:113], v[112:113]
	v_pk_mul_f32 v[106:107], v[114:115], v[114:115]
	v_pk_fma_f32 v[102:103], v[116:117], v[116:117], v[102:103]
	v_pk_fma_f32 v[106:107], v[118:119], v[118:119], v[106:107]
	v_pk_fma_f32 v[102:103], v[120:121], v[120:121], v[102:103]
	v_pk_fma_f32 v[106:107], v[122:123], v[122:123], v[106:107]
	v_pk_fma_f32 v[102:103], v[124:125], v[124:125], v[102:103]
	v_pk_fma_f32 v[106:107], v[100:101], v[100:101], v[106:107]
	v_pk_add_f32 v[102:103], v[102:103], v[106:107]
	v_add_f32_e32 v102, v102, v103
	v_mov_b32_e32 v104, v102
	v_lshlrev_b32_e32 v112, 16, v28
	v_and_b32_e32 v113, 0xffff0000, v28
	v_lshlrev_b32_e32 v114, 16, v29
	v_and_b32_e32 v115, 0xffff0000, v29
	v_lshlrev_b32_e32 v116, 16, v30
	v_and_b32_e32 v117, 0xffff0000, v30
	v_lshlrev_b32_e32 v118, 16, v31
	v_and_b32_e32 v119, 0xffff0000, v31
	v_lshlrev_b32_e32 v120, 16, v32
	v_and_b32_e32 v121, 0xffff0000, v32
	v_lshlrev_b32_e32 v122, 16, v33
	v_and_b32_e32 v123, 0xffff0000, v33
	v_lshlrev_b32_e32 v124, 16, v34
	v_and_b32_e32 v125, 0xffff0000, v34
	v_lshlrev_b32_e32 v100, 16, v35
	v_and_b32_e32 v101, 0xffff0000, v35
	v_pk_mul_f32 v[102:103], v[112:113], v[112:113]
	v_pk_mul_f32 v[106:107], v[114:115], v[114:115]
	v_pk_fma_f32 v[102:103], v[116:117], v[116:117], v[102:103]
	v_pk_fma_f32 v[106:107], v[118:119], v[118:119], v[106:107]
	v_pk_fma_f32 v[102:103], v[120:121], v[120:121], v[102:103]
	v_pk_fma_f32 v[106:107], v[122:123], v[122:123], v[106:107]
	v_pk_fma_f32 v[102:103], v[124:125], v[124:125], v[102:103]
	v_pk_fma_f32 v[106:107], v[100:101], v[100:101], v[106:107]
	v_pk_add_f32 v[102:103], v[102:103], v[106:107]
	v_add_f32_e32 v102, v102, v103
	s_nop 1
	v_add_f32_dpp v104, v104, v104 quad_perm:[1,0,3,2] row_mask:0xf bank_mask:0xf
	v_add_f32_dpp v102, v102, v102 quad_perm:[1,0,3,2] row_mask:0xf bank_mask:0xf
	s_nop 1
	v_add_f32_dpp v104, v104, v104 quad_perm:[2,3,0,1] row_mask:0xf bank_mask:0xf
	v_add_f32_dpp v102, v102, v102 quad_perm:[2,3,0,1] row_mask:0xf bank_mask:0xf
	s_nop 1
	v_add_f32_dpp v104, v104, v104 row_half_mirror row_mask:0xf bank_mask:0xf
	v_add_f32_dpp v102, v102, v102 row_half_mirror row_mask:0xf bank_mask:0xf
	s_nop 1
	v_add_f32_dpp v104, v104, v104 row_mirror row_mask:0xf bank_mask:0xf
	v_add_f32_dpp v102, v102, v102 row_mirror row_mask:0xf bank_mask:0xf
	s_nop 1
	v_add_f32_dpp v104, v104, v104 row_bcast:15 row_mask:0xa bank_mask:0xf
	v_add_f32_dpp v102, v102, v102 row_bcast:15 row_mask:0xa bank_mask:0xf
	s_nop 1
	v_add_f32_dpp v104, v104, v104 row_bcast:31 row_mask:0xc bank_mask:0xf
	v_add_f32_dpp v102, v102, v102 row_bcast:31 row_mask:0xc bank_mask:0xf
	s_nop 1
	v_readlane_b32 s74, v104, 63
	v_readlane_b32 s75, v102, 63
	s_nop 2
	v_mov_b32_e32 v102, s74
	v_fmamk_f32 v102, v102, 0x3a800000, v2
	v_mul_f32_e32 v103, 0x4f800000, v102
	v_cmp_gt_f32_e32 vcc, 0xf800000, v102
	s_nop 1
	v_cndmask_b32_e32 v102, v102, v103, vcc
	v_sqrt_f32_e32 v103, v102
	s_nop 0
	v_add_u32_e32 v104, -1, v103
	v_add_u32_e32 v106, 1, v103
	v_fma_f32 v107, -v104, v103, v102
	v_fma_f32 v108, -v106, v103, v102
	v_cmp_ge_f32_e64 s[76:77], 0, v107
	s_nop 1
	v_cndmask_b32_e64 v103, v103, v104, s[76:77]
	v_cmp_lt_f32_e64 s[76:77], 0, v108
	s_nop 1
	v_cndmask_b32_e64 v103, v103, v106, s[76:77]
	v_mul_f32_e32 v104, 0x37800000, v103
	v_cndmask_b32_e32 v103, v103, v104, vcc
	v_cmp_class_f32_e32 vcc, v102, v3
	s_nop 1
	v_cndmask_b32_e32 v102, v103, v102, vcc
	v_div_scale_f32 v103, s[76:77], v102, v102, 1.0
	v_rcp_f32_e32 v104, v103
	v_div_scale_f32 v106, vcc, 1.0, v102, 1.0
	v_fma_f32 v107, -v103, v104, 1.0
	v_fmac_f32_e32 v104, v107, v104
	v_mul_f32_e32 v107, v106, v104
	v_fma_f32 v108, -v103, v107, v106
	v_fmac_f32_e32 v107, v108, v104
	v_fma_f32 v103, -v103, v107, v106
	v_div_fmas_f32 v103, v103, v104, v107
	v_div_fixup_f32 v110, v103, v102, 1.0
	v_mov_b32_e32 v102, s75
	v_fmamk_f32 v102, v102, 0x3a800000, v2
	v_mul_f32_e32 v103, 0x4f800000, v102
	v_cmp_gt_f32_e32 vcc, 0xf800000, v102
	s_nop 1
	v_cndmask_b32_e32 v102, v102, v103, vcc
	v_sqrt_f32_e32 v103, v102
	s_nop 0
	v_add_u32_e32 v104, -1, v103
	v_add_u32_e32 v106, 1, v103
	v_fma_f32 v107, -v104, v103, v102
	v_fma_f32 v108, -v106, v103, v102
	v_cmp_ge_f32_e64 s[76:77], 0, v107
	s_nop 1
	v_cndmask_b32_e64 v103, v103, v104, s[76:77]
	v_cmp_lt_f32_e64 s[76:77], 0, v108
	s_nop 1
	v_cndmask_b32_e64 v103, v103, v106, s[76:77]
	v_mul_f32_e32 v104, 0x37800000, v103
	v_cndmask_b32_e32 v103, v103, v104, vcc
	v_cmp_class_f32_e32 vcc, v102, v3
	s_nop 1
	v_cndmask_b32_e32 v102, v103, v102, vcc
	v_div_scale_f32 v103, s[76:77], v102, v102, 1.0
	v_rcp_f32_e32 v104, v103
	v_div_scale_f32 v106, vcc, 1.0, v102, 1.0
	v_fma_f32 v107, -v103, v104, 1.0
	v_fmac_f32_e32 v104, v107, v104
	v_mul_f32_e32 v107, v106, v104
	v_fma_f32 v108, -v103, v107, v106
	v_fmac_f32_e32 v107, v108, v104
	v_fma_f32 v103, -v103, v107, v106
	v_div_fmas_f32 v103, v103, v104, v107
	v_div_fixup_f32 v108, v103, v102, 1.0
	v_mul_f32_e32 v108, 0.5, v108
	v_pk_mul_f32 v[112:113], v[112:113], v[108:109] op_sel_hi:[1,0]
	v_pk_mul_f32 v[114:115], v[114:115], v[108:109] op_sel_hi:[1,0]
; __device__ __forceinline__ void phase_final(const Params& p) {
;     ...
;         for (int j = 0; j < 4; ++j) { v[j] = *(const f32x4*)(p.out + (size_t)row * D + 4 * lane + 256 * j);
;             const u32x2 wm = *(const u32x2*)(Fm + (size_t)row * D + 4 * lane + 256 * j), wf = *(const u32x2*)(F2 + (size_t)row * D + 4 * lane + 256 * j);
;     ...
;         const float* g1 = mod + b * 9216 + 1 * 3072 + 2048; const float* g2 = mod + b * 9216 + 2 * 3072 + 2048;
;         const float* q1 = p.in[7] + 1 * D; const float* q2 = p.in[7] + 2 * D;
; #pragma unroll
;         for (int j = 0; j < 4; ++j) { const int c = 4 * lane + 256 * j;
;             const f32x4 x2 = v[j] + *(const f32x4*)(g1 + c) * (m[j] * rm * *(const f32x4*)(q1 + c));
;             *(f32x4*)(p.out + (size_t)row * D + c) = x2 + *(const f32x4*)(g2 + c) * (f[j] * rf * *(const f32x4*)(q2 + c)); }
	v_pk_mul_f32 v[116:117], v[116:117], v[108:109] op_sel_hi:[1,0]
	v_pk_mul_f32 v[118:119], v[118:119], v[108:109] op_sel_hi:[1,0]
	v_pk_mul_f32 v[120:121], v[120:121], v[108:109] op_sel_hi:[1,0]
	v_pk_mul_f32 v[122:123], v[122:123], v[108:109] op_sel_hi:[1,0]
	v_pk_mul_f32 v[124:125], v[124:125], v[108:109] op_sel_hi:[1,0]
	v_pk_mul_f32 v[100:101], v[100:101], v[108:109] op_sel_hi:[1,0]
	v_pk_mul_f32 v[112:113], v[112:113], v[208:209]
	v_pk_mul_f32 v[114:115], v[114:115], v[210:211]
	v_pk_mul_f32 v[116:117], v[116:117], v[212:213]
	v_pk_mul_f32 v[118:119], v[118:119], v[214:215]
	v_pk_mul_f32 v[120:121], v[120:121], v[216:217]
	v_pk_mul_f32 v[122:123], v[122:123], v[218:219]
	v_pk_mul_f32 v[124:125], v[124:125], v[220:221]
	v_pk_mul_f32 v[100:101], v[100:101], v[222:223]
	v_lshlrev_b32_e32 v28, 16, v20
	v_and_b32_e32 v29, 0xffff0000, v20
	v_lshlrev_b32_e32 v30, 16, v21
	v_and_b32_e32 v31, 0xffff0000, v21
	v_lshlrev_b32_e32 v32, 16, v22
	v_and_b32_e32 v33, 0xffff0000, v22
	v_lshlrev_b32_e32 v34, 16, v23
	v_and_b32_e32 v35, 0xffff0000, v23
	v_lshlrev_b32_e32 v240, 16, v24
	v_and_b32_e32 v241, 0xffff0000, v24
	v_lshlrev_b32_e32 v242, 16, v25
	v_and_b32_e32 v243, 0xffff0000, v25
	v_lshlrev_b32_e32 v244, 16, v26
	v_and_b32_e32 v245, 0xffff0000, v26
	v_lshlrev_b32_e32 v246, 16, v27
	v_and_b32_e32 v247, 0xffff0000, v27
	v_pk_mul_f32 v[28:29], v[28:29], v[110:111] op_sel_hi:[1,0]
	v_pk_mul_f32 v[30:31], v[30:31], v[110:111] op_sel_hi:[1,0]
	v_pk_mul_f32 v[32:33], v[32:33], v[110:111] op_sel_hi:[1,0]
	v_pk_mul_f32 v[34:35], v[34:35], v[110:111] op_sel_hi:[1,0]
	v_pk_mul_f32 v[240:241], v[240:241], v[110:111] op_sel_hi:[1,0]
	v_pk_mul_f32 v[242:243], v[242:243], v[110:111] op_sel_hi:[1,0]
	v_pk_mul_f32 v[244:245], v[244:245], v[110:111] op_sel_hi:[1,0]
	v_pk_mul_f32 v[246:247], v[246:247], v[110:111] op_sel_hi:[1,0]
	v_pk_mul_f32 v[28:29], v[28:29], v[176:177]
	v_pk_mul_f32 v[30:31], v[30:31], v[178:179]
	v_pk_mul_f32 v[32:33], v[32:33], v[180:181]
	v_pk_mul_f32 v[34:35], v[34:35], v[182:183]
	v_pk_mul_f32 v[240:241], v[240:241], v[184:185]
	v_pk_mul_f32 v[242:243], v[242:243], v[186:187]
	v_pk_mul_f32 v[244:245], v[244:245], v[188:189]
	v_pk_mul_f32 v[246:247], v[246:247], v[190:191]
	v_pk_fma_f32 v[4:5], v[160:161], v[28:29], v[4:5]
	v_pk_fma_f32 v[6:7], v[162:163], v[30:31], v[6:7]
	v_pk_fma_f32 v[8:9], v[164:165], v[32:33], v[8:9]
	v_pk_fma_f32 v[10:11], v[166:167], v[34:35], v[10:11]
	v_pk_fma_f32 v[12:13], v[168:169], v[240:241], v[12:13]
	v_pk_fma_f32 v[14:15], v[170:171], v[242:243], v[14:15]
	v_pk_fma_f32 v[16:17], v[172:173], v[244:245], v[16:17]
	v_pk_fma_f32 v[18:19], v[174:175], v[246:247], v[18:19]
	v_pk_fma_f32 v[4:5], v[192:193], v[112:113], v[4:5]
	v_pk_fma_f32 v[6:7], v[194:195], v[114:115], v[6:7]
	v_pk_fma_f32 v[8:9], v[196:197], v[116:117], v[8:9]
	v_pk_fma_f32 v[10:11], v[198:199], v[118:119], v[10:11]
	v_pk_fma_f32 v[12:13], v[200:201], v[120:121], v[12:13]
	v_pk_fma_f32 v[14:15], v[202:203], v[122:123], v[14:15]
	v_pk_fma_f32 v[16:17], v[204:205], v[124:125], v[16:17]
	v_pk_fma_f32 v[18:19], v[206:207], v[100:101], v[18:19]
	s_lshl_b32 s60, s55, 12
	s_add_u32 s72, s84, s60
	s_addc_u32 s73, s85, 0
	global_store_dwordx4 v0, v[4:7], s[72:73] sc1
	global_store_dwordx4 v0, v[8:11], s[72:73] offset:1024 sc1
	global_store_dwordx4 v0, v[12:15], s[72:73] offset:2048 sc1
	global_store_dwordx4 v0, v[16:19], s[72:73] offset:3072 sc1
	s_add_u32 s55, s55, 8
	s_add_u32 s57, s55, 16
	s_min_u32 s57, s57, s54
	s_lshl_b32 s60, s57, 12
	s_add_u32 s64, s84, s60
	s_addc_u32 s65, s85, 0
	s_lshl_b32 s60, s57, 11
	s_add_u32 s66, s82, s60
	s_addc_u32 s67, s83, 0
	s_lshl_b32 s60, s57, 11
	s_add_u32 s68, s78, s60
	s_addc_u32 s69, s79, 0
	global_load_dwordx4 v[4:7], v0, s[64:65] nt
	global_load_dwordx4 v[8:11], v0, s[64:65] offset:1024 nt
	global_load_dwordx4 v[12:15], v0, s[64:65] offset:2048 nt
	global_load_dwordx4 v[16:19], v0, s[64:65] offset:3072 nt
	global_load_dwordx2 v[20:21], v1, s[66:67] nt
	global_load_dwordx2 v[22:23], v1, s[66:67] offset:512 nt
	global_load_dwordx2 v[24:25], v1, s[66:67] offset:1024 nt
	global_load_dwordx2 v[26:27], v1, s[66:67] offset:1536 nt
	global_load_dwordx2 v[28:29], v1, s[68:69] nt
	global_load_dwordx2 v[30:31], v1, s[68:69] offset:512 nt
	global_load_dwordx2 v[32:33], v1, s[68:69] offset:1024 nt
	global_load_dwordx2 v[34:35], v1, s[68:69] offset:1536 nt
	s_lshr_b32 s60, s55, 11
	s_sub_u32 s61, s55, 0x8000
	s_lshr_b32 s61, s61, 12
	s_add_u32 s61, s61, 16
	s_cmp_lt_u32 s55, 0x8000
	s_cselect_b32 s63, s60, s61
	s_cmp_eq_u32 s63, s56
	s_cbranch_scc1 .Lrp15_pk5
	s_mov_b32 s56, s63
	s_mul_i32 s60, s56, 0x9000
	s_add_u32 s60, s60, 0x3185000
	s_add_u32 s0, s92, s60
	s_addc_u32 s1, s93, 0
	global_load_dwordx4 v[160:163], v0, s[0:1]
	global_load_dwordx4 v[164:167], v0, s[0:1] offset:1024
	global_load_dwordx4 v[168:171], v0, s[0:1] offset:2048
	global_load_dwordx4 v[172:175], v0, s[0:1] offset:3072
	s_add_u32 s0, s22, 0x1000
	s_addc_u32 s1, s23, 0
	global_load_dwordx4 v[176:179], v0, s[0:1]
	global_load_dwordx4 v[180:183], v0, s[0:1] offset:1024
	global_load_dwordx4 v[184:187], v0, s[0:1] offset:2048
	global_load_dwordx4 v[188:191], v0, s[0:1] offset:3072
	s_mul_i32 s60, s56, 0x9000
	s_add_u32 s60, s60, 0x3188000
	s_add_u32 s0, s92, s60
	s_addc_u32 s1, s93, 0
	global_load_dwordx4 v[192:195], v0, s[0:1]
	global_load_dwordx4 v[196:199], v0, s[0:1] offset:1024
	global_load_dwordx4 v[200:203], v0, s[0:1] offset:2048
	global_load_dwordx4 v[204:207], v0, s[0:1] offset:3072
	s_add_u32 s0, s22, 0x2000
	s_addc_u32 s1, s23, 0
	global_load_dwordx4 v[208:211], v0, s[0:1]
	global_load_dwordx4 v[212:215], v0, s[0:1] offset:1024
	global_load_dwordx4 v[216:219], v0, s[0:1] offset:2048
	global_load_dwordx4 v[220:223], v0, s[0:1] offset:3072
	s_waitcnt vmcnt(0)
; __device__ __forceinline__ float lo_bf(unsigned w) { return __uint_as_float(w << 16); }
; __device__ __forceinline__ float hi_bf(unsigned w) { return __uint_as_float(w & 0xffff0000u); }
; __device__ __forceinline__ void phase_final(const Params& p) {
;     ...
;         for (int j = 0; j < 4; ++j) { v[j] = *(const f32x4*)(p.out + (size_t)row * D + 4 * lane + 256 * j);
;             const u32x2 wm = *(const u32x2*)(Fm + (size_t)row * D + 4 * lane + 256 * j), wf = *(const u32x2*)(F2 + (size_t)row * D + 4 * lane + 256 * j);
;             m[j] = (f32x4){lo_bf(wm.x), hi_bf(wm.x), lo_bf(wm.y), hi_bf(wm.y)}; f[j] = (f32x4){lo_bf(wf.x), hi_bf(wf.x), lo_bf(wf.y), hi_bf(wf.y)};
;             sm += (m[j].x * m[j].x + m[j].y * m[j].y) + (m[j].z * m[j].z + m[j].w * m[j].w); sf += (f[j].x * f[j].x + f[j].y * f[j].y) + (f[j].z * f[j].z + f[j].w * f[j].w); }
;         const float rm = 1.0f / sqrtf(wave_sum(sm) * (1.0f / D) + EPS), rf = 1.0f / sqrtf(wave_sum(sf) * (1.0f / D) + EPS) * 0.5f;
.Lrp15_pk5:
	s_waitcnt vmcnt(28)
	v_lshlrev_b32_e32 v112, 16, v52
	v_and_b32_e32 v113, 0xffff0000, v52
	v_lshlrev_b32_e32 v114, 16, v53
	v_and_b32_e32 v115, 0xffff0000, v53
	v_lshlrev_b32_e32 v116, 16, v54
	v_and_b32_e32 v117, 0xffff0000, v54
	v_lshlrev_b32_e32 v118, 16, v55
	v_and_b32_e32 v119, 0xffff0000, v55
	v_lshlrev_b32_e32 v120, 16, v56
	v_and_b32_e32 v121, 0xffff0000, v56
	v_lshlrev_b32_e32 v122, 16, v57
	v_and_b32_e32 v123, 0xffff0000, v57
	v_lshlrev_b32_e32 v124, 16, v58
	v_and_b32_e32 v125, 0xffff0000, v58
	v_lshlrev_b32_e32 v100, 16, v59
	v_and_b32_e32 v101, 0xffff0000, v59
	v_pk_mul_f32 v[102:103], v[112:113], v[112:113]
	v_pk_mul_f32 v[106:107], v[114:115], v[114:115]
	v_pk_fma_f32 v[102:103], v[116:117], v[116:117], v[102:103]
	v_pk_fma_f32 v[106:107], v[118:119], v[118:119], v[106:107]
	v_pk_fma_f32 v[102:103], v[120:121], v[120:121], v[102:103]
	v_pk_fma_f32 v[106:107], v[122:123], v[122:123], v[106:107]
	v_pk_fma_f32 v[102:103], v[124:125], v[124:125], v[102:103]
	v_pk_fma_f32 v[106:107], v[100:101], v[100:101], v[106:107]
	v_pk_add_f32 v[102:103], v[102:103], v[106:107]
	v_add_f32_e32 v102, v102, v103
	v_mov_b32_e32 v104, v102
	v_lshlrev_b32_e32 v112, 16, v60
	v_and_b32_e32 v113, 0xffff0000, v60
	v_lshlrev_b32_e32 v114, 16, v61
	v_and_b32_e32 v115, 0xffff0000, v61
	v_lshlrev_b32_e32 v116, 16, v62
	v_and_b32_e32 v117, 0xffff0000, v62
	v_lshlrev_b32_e32 v118, 16, v63
	v_and_b32_e32 v119, 0xffff0000, v63
	v_lshlrev_b32_e32 v120, 16, v64
	v_and_b32_e32 v121, 0xffff0000, v64
	v_lshlrev_b32_e32 v122, 16, v65
	v_and_b32_e32 v123, 0xffff0000, v65
	v_lshlrev_b32_e32 v124, 16, v66
	v_and_b32_e32 v125, 0xffff0000, v66
	v_lshlrev_b32_e32 v100, 16, v67
	v_and_b32_e32 v101, 0xffff0000, v67
	v_pk_mul_f32 v[102:103], v[112:113], v[112:113]
	v_pk_mul_f32 v[106:107], v[114:115], v[114:115]
	v_pk_fma_f32 v[102:103], v[116:117], v[116:117], v[102:103]
	v_pk_fma_f32 v[106:107], v[118:119], v[118:119], v[106:107]
	v_pk_fma_f32 v[102:103], v[120:121], v[120:121], v[102:103]
	v_pk_fma_f32 v[106:107], v[122:123], v[122:123], v[106:107]
	v_pk_fma_f32 v[102:103], v[124:125], v[124:125], v[102:103]
	v_pk_fma_f32 v[106:107], v[100:101], v[100:101], v[106:107]
	v_pk_add_f32 v[102:103], v[102:103], v[106:107]
	v_add_f32_e32 v102, v102, v103
	s_nop 1
	v_add_f32_dpp v104, v104, v104 quad_perm:[1,0,3,2] row_mask:0xf bank_mask:0xf
	v_add_f32_dpp v102, v102, v102 quad_perm:[1,0,3,2] row_mask:0xf bank_mask:0xf
	s_nop 1
	v_add_f32_dpp v104, v104, v104 quad_perm:[2,3,0,1] row_mask:0xf bank_mask:0xf
	v_add_f32_dpp v102, v102, v102 quad_perm:[2,3,0,1] row_mask:0xf bank_mask:0xf
	s_nop 1
	v_add_f32_dpp v104, v104, v104 row_half_mirror row_mask:0xf bank_mask:0xf
	v_add_f32_dpp v102, v102, v102 row_half_mirror row_mask:0xf bank_mask:0xf
	s_nop 1
	v_add_f32_dpp v104, v104, v104 row_mirror row_mask:0xf bank_mask:0xf
	v_add_f32_dpp v102, v102, v102 row_mirror row_mask:0xf bank_mask:0xf
	s_nop 1
	v_add_f32_dpp v104, v104, v104 row_bcast:15 row_mask:0xa bank_mask:0xf
	v_add_f32_dpp v102, v102, v102 row_bcast:15 row_mask:0xa bank_mask:0xf
	s_nop 1
	v_add_f32_dpp v104, v104, v104 row_bcast:31 row_mask:0xc bank_mask:0xf
	v_add_f32_dpp v102, v102, v102 row_bcast:31 row_mask:0xc bank_mask:0xf
	s_nop 1
	v_readlane_b32 s74, v104, 63
	v_readlane_b32 s75, v102, 63
	s_nop 2
	v_mov_b32_e32 v102, s74
	v_fmamk_f32 v102, v102, 0x3a800000, v2
	v_mul_f32_e32 v103, 0x4f800000, v102
	v_cmp_gt_f32_e32 vcc, 0xf800000, v102
	s_nop 1
	v_cndmask_b32_e32 v102, v102, v103, vcc
	v_sqrt_f32_e32 v103, v102
	s_nop 0
	v_add_u32_e32 v104, -1, v103
	v_add_u32_e32 v106, 1, v103
	v_fma_f32 v107, -v104, v103, v102
	v_fma_f32 v108, -v106, v103, v102
	v_cmp_ge_f32_e64 s[76:77], 0, v107
	s_nop 1
	v_cndmask_b32_e64 v103, v103, v104, s[76:77]
	v_cmp_lt_f32_e64 s[76:77], 0, v108
	s_nop 1
	v_cndmask_b32_e64 v103, v103, v106, s[76:77]
	v_mul_f32_e32 v104, 0x37800000, v103
	v_cndmask_b32_e32 v103, v103, v104, vcc
	v_cmp_class_f32_e32 vcc, v102, v3
	s_nop 1
	v_cndmask_b32_e32 v102, v103, v102, vcc
	v_div_scale_f32 v103, s[76:77], v102, v102, 1.0
	v_rcp_f32_e32 v104, v103
	v_div_scale_f32 v106, vcc, 1.0, v102, 1.0
	v_fma_f32 v107, -v103, v104, 1.0
	v_fmac_f32_e32 v104, v107, v104
	v_mul_f32_e32 v107, v106, v104
	v_fma_f32 v108, -v103, v107, v106
	v_fmac_f32_e32 v107, v108, v104
	v_fma_f32 v103, -v103, v107, v106
	v_div_fmas_f32 v103, v103, v104, v107
	v_div_fixup_f32 v110, v103, v102, 1.0
	v_mov_b32_e32 v102, s75
	v_fmamk_f32 v102, v102, 0x3a800000, v2
	v_mul_f32_e32 v103, 0x4f800000, v102
	v_cmp_gt_f32_e32 vcc, 0xf800000, v102
	s_nop 1
	v_cndmask_b32_e32 v102, v102, v103, vcc
	v_sqrt_f32_e32 v103, v102
	s_nop 0
	v_add_u32_e32 v104, -1, v103
	v_add_u32_e32 v106, 1, v103
	v_fma_f32 v107, -v104, v103, v102
	v_fma_f32 v108, -v106, v103, v102
	v_cmp_ge_f32_e64 s[76:77], 0, v107
	s_nop 1
	v_cndmask_b32_e64 v103, v103, v104, s[76:77]
	v_cmp_lt_f32_e64 s[76:77], 0, v108
	s_nop 1
	v_cndmask_b32_e64 v103, v103, v106, s[76:77]
	v_mul_f32_e32 v104, 0x37800000, v103
	v_cndmask_b32_e32 v103, v103, v104, vcc
	v_cmp_class_f32_e32 vcc, v102, v3
	s_nop 1
	v_cndmask_b32_e32 v102, v103, v102, vcc
	v_div_scale_f32 v103, s[76:77], v102, v102, 1.0
	v_rcp_f32_e32 v104, v103
	v_div_scale_f32 v106, vcc, 1.0, v102, 1.0
	v_fma_f32 v107, -v103, v104, 1.0
	v_fmac_f32_e32 v104, v107, v104
	v_mul_f32_e32 v107, v106, v104
	v_fma_f32 v108, -v103, v107, v106
	v_fmac_f32_e32 v107, v108, v104
	v_fma_f32 v103, -v103, v107, v106
	v_div_fmas_f32 v103, v103, v104, v107
	v_div_fixup_f32 v108, v103, v102, 1.0
	v_mul_f32_e32 v108, 0.5, v108
	v_pk_mul_f32 v[112:113], v[112:113], v[108:109] op_sel_hi:[1,0]
	v_pk_mul_f32 v[114:115], v[114:115], v[108:109] op_sel_hi:[1,0]
; __device__ __forceinline__ void phase_final(const Params& p) {
;     ...
;         for (int j = 0; j < 4; ++j) { v[j] = *(const f32x4*)(p.out + (size_t)row * D + 4 * lane + 256 * j);
;             const u32x2 wm = *(const u32x2*)(Fm + (size_t)row * D + 4 * lane + 256 * j), wf = *(const u32x2*)(F2 + (size_t)row * D + 4 * lane + 256 * j);
;     ...
;         const float* g1 = mod + b * 9216 + 1 * 3072 + 2048; const float* g2 = mod + b * 9216 + 2 * 3072 + 2048;
;         const float* q1 = p.in[7] + 1 * D; const float* q2 = p.in[7] + 2 * D;
; #pragma unroll
;         for (int j = 0; j < 4; ++j) { const int c = 4 * lane + 256 * j;
;             const f32x4 x2 = v[j] + *(const f32x4*)(g1 + c) * (m[j] * rm * *(const f32x4*)(q1 + c));
;             *(f32x4*)(p.out + (size_t)row * D + c) = x2 + *(const f32x4*)(g2 + c) * (f[j] * rf * *(const f32x4*)(q2 + c)); }
	v_pk_mul_f32 v[116:117], v[116:117], v[108:109] op_sel_hi:[1,0]
	v_pk_mul_f32 v[118:119], v[118:119], v[108:109] op_sel_hi:[1,0]
	v_pk_mul_f32 v[120:121], v[120:121], v[108:109] op_sel_hi:[1,0]
	v_pk_mul_f32 v[122:123], v[122:123], v[108:109] op_sel_hi:[1,0]
	v_pk_mul_f32 v[124:125], v[124:125], v[108:109] op_sel_hi:[1,0]
	v_pk_mul_f32 v[100:101], v[100:101], v[108:109] op_sel_hi:[1,0]
	v_pk_mul_f32 v[112:113], v[112:113], v[208:209]
	v_pk_mul_f32 v[114:115], v[114:115], v[210:211]
	v_pk_mul_f32 v[116:117], v[116:117], v[212:213]
	v_pk_mul_f32 v[118:119], v[118:119], v[214:215]
	v_pk_mul_f32 v[120:121], v[120:121], v[216:217]
	v_pk_mul_f32 v[122:123], v[122:123], v[218:219]
	v_pk_mul_f32 v[124:125], v[124:125], v[220:221]
	v_pk_mul_f32 v[100:101], v[100:101], v[222:223]
	v_lshlrev_b32_e32 v60, 16, v52
	v_and_b32_e32 v61, 0xffff0000, v52
	v_lshlrev_b32_e32 v62, 16, v53
	v_and_b32_e32 v63, 0xffff0000, v53
	v_lshlrev_b32_e32 v64, 16, v54
	v_and_b32_e32 v65, 0xffff0000, v54
	v_lshlrev_b32_e32 v66, 16, v55
	v_and_b32_e32 v67, 0xffff0000, v55
	v_lshlrev_b32_e32 v240, 16, v56
	v_and_b32_e32 v241, 0xffff0000, v56
	v_lshlrev_b32_e32 v242, 16, v57
	v_and_b32_e32 v243, 0xffff0000, v57
	v_lshlrev_b32_e32 v244, 16, v58
	v_and_b32_e32 v245, 0xffff0000, v58
	v_lshlrev_b32_e32 v246, 16, v59
	v_and_b32_e32 v247, 0xffff0000, v59
	v_pk_mul_f32 v[60:61], v[60:61], v[110:111] op_sel_hi:[1,0]
	v_pk_mul_f32 v[62:63], v[62:63], v[110:111] op_sel_hi:[1,0]
	v_pk_mul_f32 v[64:65], v[64:65], v[110:111] op_sel_hi:[1,0]
	v_pk_mul_f32 v[66:67], v[66:67], v[110:111] op_sel_hi:[1,0]
	v_pk_mul_f32 v[240:241], v[240:241], v[110:111] op_sel_hi:[1,0]
	v_pk_mul_f32 v[242:243], v[242:243], v[110:111] op_sel_hi:[1,0]
	v_pk_mul_f32 v[244:245], v[244:245], v[110:111] op_sel_hi:[1,0]
	v_pk_mul_f32 v[246:247], v[246:247], v[110:111] op_sel_hi:[1,0]
	v_pk_mul_f32 v[60:61], v[60:61], v[176:177]
	v_pk_mul_f32 v[62:63], v[62:63], v[178:179]
	v_pk_mul_f32 v[64:65], v[64:65], v[180:181]
	v_pk_mul_f32 v[66:67], v[66:67], v[182:183]
	v_pk_mul_f32 v[240:241], v[240:241], v[184:185]
	v_pk_mul_f32 v[242:243], v[242:243], v[186:187]
	v_pk_mul_f32 v[244:245], v[244:245], v[188:189]
	v_pk_mul_f32 v[246:247], v[246:247], v[190:191]
	v_pk_fma_f32 v[36:37], v[160:161], v[60:61], v[36:37]
	v_pk_fma_f32 v[38:39], v[162:163], v[62:63], v[38:39]
	v_pk_fma_f32 v[40:41], v[164:165], v[64:65], v[40:41]
	v_pk_fma_f32 v[42:43], v[166:167], v[66:67], v[42:43]
	v_pk_fma_f32 v[44:45], v[168:169], v[240:241], v[44:45]
	v_pk_fma_f32 v[46:47], v[170:171], v[242:243], v[46:47]
	v_pk_fma_f32 v[48:49], v[172:173], v[244:245], v[48:49]
	v_pk_fma_f32 v[50:51], v[174:175], v[246:247], v[50:51]
	v_pk_fma_f32 v[36:37], v[192:193], v[112:113], v[36:37]
	v_pk_fma_f32 v[38:39], v[194:195], v[114:115], v[38:39]
	v_pk_fma_f32 v[40:41], v[196:197], v[116:117], v[40:41]
	v_pk_fma_f32 v[42:43], v[198:199], v[118:119], v[42:43]
	v_pk_fma_f32 v[44:45], v[200:201], v[120:121], v[44:45]
	v_pk_fma_f32 v[46:47], v[202:203], v[122:123], v[46:47]
	v_pk_fma_f32 v[48:49], v[204:205], v[124:125], v[48:49]
	v_pk_fma_f32 v[50:51], v[206:207], v[100:101], v[50:51]
	s_lshl_b32 s60, s55, 12
	s_add_u32 s72, s84, s60
	s_addc_u32 s73, s85, 0
	global_store_dwordx4 v0, v[36:39], s[72:73] sc1
	global_store_dwordx4 v0, v[40:43], s[72:73] offset:1024 sc1
	global_store_dwordx4 v0, v[44:47], s[72:73] offset:2048 sc1
	global_store_dwordx4 v0, v[48:51], s[72:73] offset:3072 sc1
	s_add_u32 s55, s55, 8
	s_add_u32 s57, s55, 16
	s_min_u32 s57, s57, s54
	s_lshl_b32 s60, s57, 12
	s_add_u32 s64, s84, s60
	s_addc_u32 s65, s85, 0
	s_lshl_b32 s60, s57, 11
	s_add_u32 s66, s82, s60
	s_addc_u32 s67, s83, 0
	s_lshl_b32 s60, s57, 11
	s_add_u32 s68, s78, s60
	s_addc_u32 s69, s79, 0
	global_load_dwordx4 v[36:39], v0, s[64:65] nt
	global_load_dwordx4 v[40:43], v0, s[64:65] offset:1024 nt
	global_load_dwordx4 v[44:47], v0, s[64:65] offset:2048 nt
	global_load_dwordx4 v[48:51], v0, s[64:65] offset:3072 nt
	global_load_dwordx2 v[52:53], v1, s[66:67] nt
	global_load_dwordx2 v[54:55], v1, s[66:67] offset:512 nt
	global_load_dwordx2 v[56:57], v1, s[66:67] offset:1024 nt
	global_load_dwordx2 v[58:59], v1, s[66:67] offset:1536 nt
	global_load_dwordx2 v[60:61], v1, s[68:69] nt
	global_load_dwordx2 v[62:63], v1, s[68:69] offset:512 nt
	global_load_dwordx2 v[64:65], v1, s[68:69] offset:1024 nt
	global_load_dwordx2 v[66:67], v1, s[68:69] offset:1536 nt
	s_lshr_b32 s60, s55, 11
	s_sub_u32 s61, s55, 0x8000
	s_lshr_b32 s61, s61, 12
	s_add_u32 s61, s61, 16
	s_cmp_lt_u32 s55, 0x8000
	s_cselect_b32 s63, s60, s61
	s_cmp_eq_u32 s63, s56
	s_cbranch_scc1 .Lrp15_pk6
	s_mov_b32 s56, s63
	s_mul_i32 s60, s56, 0x9000
	s_add_u32 s60, s60, 0x3185000
	s_add_u32 s0, s92, s60
	s_addc_u32 s1, s93, 0
	global_load_dwordx4 v[160:163], v0, s[0:1]
	global_load_dwordx4 v[164:167], v0, s[0:1] offset:1024
	global_load_dwordx4 v[168:171], v0, s[0:1] offset:2048
	global_load_dwordx4 v[172:175], v0, s[0:1] offset:3072
	s_add_u32 s0, s22, 0x1000
	s_addc_u32 s1, s23, 0
	global_load_dwordx4 v[176:179], v0, s[0:1]
	global_load_dwordx4 v[180:183], v0, s[0:1] offset:1024
	global_load_dwordx4 v[184:187], v0, s[0:1] offset:2048
	global_load_dwordx4 v[188:191], v0, s[0:1] offset:3072
	s_mul_i32 s60, s56, 0x9000
	s_add_u32 s60, s60, 0x3188000
	s_add_u32 s0, s92, s60
	s_addc_u32 s1, s93, 0
	global_load_dwordx4 v[192:195], v0, s[0:1]
	global_load_dwordx4 v[196:199], v0, s[0:1] offset:1024
	global_load_dwordx4 v[200:203], v0, s[0:1] offset:2048
	global_load_dwordx4 v[204:207], v0, s[0:1] offset:3072
	s_add_u32 s0, s22, 0x2000
	s_addc_u32 s1, s23, 0
	global_load_dwordx4 v[208:211], v0, s[0:1]
	global_load_dwordx4 v[212:215], v0, s[0:1] offset:1024
	global_load_dwordx4 v[216:219], v0, s[0:1] offset:2048
	global_load_dwordx4 v[220:223], v0, s[0:1] offset:3072
	s_waitcnt vmcnt(0)
; __device__ __forceinline__ float lo_bf(unsigned w) { return __uint_as_float(w << 16); }
; __device__ __forceinline__ float hi_bf(unsigned w) { return __uint_as_float(w & 0xffff0000u); }
; __device__ __forceinline__ void phase_final(const Params& p) {
;     ...
;         f32x4 v[4], m[4], f[4]; float sm = 0.f, sf = 0.f;
; #pragma unroll
;         for (int j = 0; j < 4; ++j) { v[j] = *(const f32x4*)(p.out + (size_t)row * D + 4 * lane + 256 * j);
;             const u32x2 wm = *(const u32x2*)(Fm + (size_t)row * D + 4 * lane + 256 * j), wf = *(const u32x2*)(F2 + (size_t)row * D + 4 * lane + 256 * j);
;             m[j] = (f32x4){lo_bf(wm.x), hi_bf(wm.x), lo_bf(wm.y), hi_bf(wm.y)}; f[j] = (f32x4){lo_bf(wf.x), hi_bf(wf.x), lo_bf(wf.y), hi_bf(wf.y)};
;             sm += (m[j].x * m[j].x + m[j].y * m[j].y) + (m[j].z * m[j].z + m[j].w * m[j].w); sf += (f[j].x * f[j].x + f[j].y * f[j].y) + (f[j].z * f[j].z + f[j].w * f[j].w); }
;         const float rm = 1.0f / sqrtf(wave_sum(sm) * (1.0f / D) + EPS), rf = 1.0f / sqrtf(wave_sum(sf) * (1.0f / D) + EPS) * 0.5f;
.Lrp15_pk6:
	s_waitcnt vmcnt(32)
	v_lshlrev_b32_e32 v112, 16, v84
	v_and_b32_e32 v113, 0xffff0000, v84
	v_lshlrev_b32_e32 v114, 16, v85
	v_and_b32_e32 v115, 0xffff0000, v85
	v_lshlrev_b32_e32 v116, 16, v86
	v_and_b32_e32 v117, 0xffff0000, v86
	v_lshlrev_b32_e32 v118, 16, v87
	v_and_b32_e32 v119, 0xffff0000, v87
	v_lshlrev_b32_e32 v120, 16, v88
	v_and_b32_e32 v121, 0xffff0000, v88
	v_lshlrev_b32_e32 v122, 16, v89
	v_and_b32_e32 v123, 0xffff0000, v89
	v_lshlrev_b32_e32 v124, 16, v90
	v_and_b32_e32 v125, 0xffff0000, v90
	v_lshlrev_b32_e32 v100, 16, v91
	v_and_b32_e32 v101, 0xffff0000, v91
	v_pk_mul_f32 v[102:103], v[112:113], v[112:113]
	v_pk_mul_f32 v[106:107], v[114:115], v[114:115]
	v_pk_fma_f32 v[102:103], v[116:117], v[116:117], v[102:103]
	v_pk_fma_f32 v[106:107], v[118:119], v[118:119], v[106:107]
	v_pk_fma_f32 v[102:103], v[120:121], v[120:121], v[102:103]
	v_pk_fma_f32 v[106:107], v[122:123], v[122:123], v[106:107]
	v_pk_fma_f32 v[102:103], v[124:125], v[124:125], v[102:103]
	v_pk_fma_f32 v[106:107], v[100:101], v[100:101], v[106:107]
	v_pk_add_f32 v[102:103], v[102:103], v[106:107]
	v_add_f32_e32 v102, v102, v103
	v_mov_b32_e32 v104, v102
	v_lshlrev_b32_e32 v112, 16, v92
	v_and_b32_e32 v113, 0xffff0000, v92
	v_lshlrev_b32_e32 v114, 16, v93
	v_and_b32_e32 v115, 0xffff0000, v93
	v_lshlrev_b32_e32 v116, 16, v94
	v_and_b32_e32 v117, 0xffff0000, v94
	v_lshlrev_b32_e32 v118, 16, v95
	v_and_b32_e32 v119, 0xffff0000, v95
	v_lshlrev_b32_e32 v120, 16, v96
	v_and_b32_e32 v121, 0xffff0000, v96
	v_lshlrev_b32_e32 v122, 16, v97
	v_and_b32_e32 v123, 0xffff0000, v97
	v_lshlrev_b32_e32 v124, 16, v98
	v_and_b32_e32 v125, 0xffff0000, v98
	v_lshlrev_b32_e32 v100, 16, v99
	v_and_b32_e32 v101, 0xffff0000, v99
	v_pk_mul_f32 v[102:103], v[112:113], v[112:113]
	v_pk_mul_f32 v[106:107], v[114:115], v[114:115]
	v_pk_fma_f32 v[102:103], v[116:117], v[116:117], v[102:103]
	v_pk_fma_f32 v[106:107], v[118:119], v[118:119], v[106:107]
	v_pk_fma_f32 v[102:103], v[120:121], v[120:121], v[102:103]
	v_pk_fma_f32 v[106:107], v[122:123], v[122:123], v[106:107]
	v_pk_fma_f32 v[102:103], v[124:125], v[124:125], v[102:103]
	v_pk_fma_f32 v[106:107], v[100:101], v[100:101], v[106:107]
	v_pk_add_f32 v[102:103], v[102:103], v[106:107]
	v_add_f32_e32 v102, v102, v103
	s_nop 1
	v_add_f32_dpp v104, v104, v104 quad_perm:[1,0,3,2] row_mask:0xf bank_mask:0xf
	v_add_f32_dpp v102, v102, v102 quad_perm:[1,0,3,2] row_mask:0xf bank_mask:0xf
	s_nop 1
	v_add_f32_dpp v104, v104, v104 quad_perm:[2,3,0,1] row_mask:0xf bank_mask:0xf
	v_add_f32_dpp v102, v102, v102 quad_perm:[2,3,0,1] row_mask:0xf bank_mask:0xf
	s_nop 1
	v_add_f32_dpp v104, v104, v104 row_half_mirror row_mask:0xf bank_mask:0xf
	v_add_f32_dpp v102, v102, v102 row_half_mirror row_mask:0xf bank_mask:0xf
	s_nop 1
	v_add_f32_dpp v104, v104, v104 row_mirror row_mask:0xf bank_mask:0xf
	v_add_f32_dpp v102, v102, v102 row_mirror row_mask:0xf bank_mask:0xf
	s_nop 1
	v_add_f32_dpp v104, v104, v104 row_bcast:15 row_mask:0xa bank_mask:0xf
	v_add_f32_dpp v102, v102, v102 row_bcast:15 row_mask:0xa bank_mask:0xf
	s_nop 1
	v_add_f32_dpp v104, v104, v104 row_bcast:31 row_mask:0xc bank_mask:0xf
	v_add_f32_dpp v102, v102, v102 row_bcast:31 row_mask:0xc bank_mask:0xf
	s_nop 1
	v_readlane_b32 s74, v104, 63
	v_readlane_b32 s75, v102, 63
	s_nop 2
	v_mov_b32_e32 v102, s74
	v_fmamk_f32 v102, v102, 0x3a800000, v2
	v_mul_f32_e32 v103, 0x4f800000, v102
	v_cmp_gt_f32_e32 vcc, 0xf800000, v102
	s_nop 1
	v_cndmask_b32_e32 v102, v102, v103, vcc
	v_sqrt_f32_e32 v103, v102
	s_nop 0
	v_add_u32_e32 v104, -1, v103
	v_add_u32_e32 v106, 1, v103
	v_fma_f32 v107, -v104, v103, v102
	v_fma_f32 v108, -v106, v103, v102
	v_cmp_ge_f32_e64 s[76:77], 0, v107
	s_nop 1
	v_cndmask_b32_e64 v103, v103, v104, s[76:77]
	v_cmp_lt_f32_e64 s[76:77], 0, v108
	s_nop 1
	v_cndmask_b32_e64 v103, v103, v106, s[76:77]
	v_mul_f32_e32 v104, 0x37800000, v103
	v_cndmask_b32_e32 v103, v103, v104, vcc
	v_cmp_class_f32_e32 vcc, v102, v3
	s_nop 1
	v_cndmask_b32_e32 v102, v103, v102, vcc
	v_div_scale_f32 v103, s[76:77], v102, v102, 1.0
	v_rcp_f32_e32 v104, v103
	v_div_scale_f32 v106, vcc, 1.0, v102, 1.0
	v_fma_f32 v107, -v103, v104, 1.0
	v_fmac_f32_e32 v104, v107, v104
	v_mul_f32_e32 v107, v106, v104
	v_fma_f32 v108, -v103, v107, v106
	v_fmac_f32_e32 v107, v108, v104
	v_fma_f32 v103, -v103, v107, v106
	v_div_fmas_f32 v103, v103, v104, v107
	v_div_fixup_f32 v110, v103, v102, 1.0
	v_mov_b32_e32 v102, s75
	v_fmamk_f32 v102, v102, 0x3a800000, v2
	v_mul_f32_e32 v103, 0x4f800000, v102
	v_cmp_gt_f32_e32 vcc, 0xf800000, v102
	s_nop 1
; __device__ __forceinline__ void phase_final(const Params& p) {
;     ...
;         const float rm = 1.0f / sqrtf(wave_sum(sm) * (1.0f / D) + EPS), rf = 1.0f / sqrtf(wave_sum(sf) * (1.0f / D) + EPS) * 0.5f;
;         const float* g1 = mod + b * 9216 + 1 * 3072 + 2048; const float* g2 = mod + b * 9216 + 2 * 3072 + 2048;
;         const float* q1 = p.in[7] + 1 * D; const float* q2 = p.in[7] + 2 * D;
; #pragma unroll
;         for (int j = 0; j < 4; ++j) { const int c = 4 * lane + 256 * j;
;             const f32x4 x2 = v[j] + *(const f32x4*)(g1 + c) * (m[j] * rm * *(const f32x4*)(q1 + c));
;             *(f32x4*)(p.out + (size_t)row * D + c) = x2 + *(const f32x4*)(g2 + c) * (f[j] * rf * *(const f32x4*)(q2 + c)); }
	v_cndmask_b32_e32 v102, v102, v103, vcc
	v_sqrt_f32_e32 v103, v102
	s_nop 0
	v_add_u32_e32 v104, -1, v103
	v_add_u32_e32 v106, 1, v103
	v_fma_f32 v107, -v104, v103, v102
	v_fma_f32 v108, -v106, v103, v102
	v_cmp_ge_f32_e64 s[76:77], 0, v107
	s_nop 1
	v_cndmask_b32_e64 v103, v103, v104, s[76:77]
	v_cmp_lt_f32_e64 s[76:77], 0, v108
	s_nop 1
	v_cndmask_b32_e64 v103, v103, v106, s[76:77]
	v_mul_f32_e32 v104, 0x37800000, v103
	v_cndmask_b32_e32 v103, v103, v104, vcc
	v_cmp_class_f32_e32 vcc, v102, v3
	s_nop 1
	v_cndmask_b32_e32 v102, v103, v102, vcc
	v_div_scale_f32 v103, s[76:77], v102, v102, 1.0
	v_rcp_f32_e32 v104, v103
	v_div_scale_f32 v106, vcc, 1.0, v102, 1.0
	v_fma_f32 v107, -v103, v104, 1.0
	v_fmac_f32_e32 v104, v107, v104
	v_mul_f32_e32 v107, v106, v104
	v_fma_f32 v108, -v103, v107, v106
	v_fmac_f32_e32 v107, v108, v104
	v_fma_f32 v103, -v103, v107, v106
	v_div_fmas_f32 v103, v103, v104, v107
	v_div_fixup_f32 v108, v103, v102, 1.0
	v_mul_f32_e32 v108, 0.5, v108
	v_pk_mul_f32 v[112:113], v[112:113], v[108:109] op_sel_hi:[1,0]
	v_pk_mul_f32 v[114:115], v[114:115], v[108:109] op_sel_hi:[1,0]
	v_pk_mul_f32 v[116:117], v[116:117], v[108:109] op_sel_hi:[1,0]
	v_pk_mul_f32 v[118:119], v[118:119], v[108:109] op_sel_hi:[1,0]
	v_pk_mul_f32 v[120:121], v[120:121], v[108:109] op_sel_hi:[1,0]
	v_pk_mul_f32 v[122:123], v[122:123], v[108:109] op_sel_hi:[1,0]
	v_pk_mul_f32 v[124:125], v[124:125], v[108:109] op_sel_hi:[1,0]
	v_pk_mul_f32 v[100:101], v[100:101], v[108:109] op_sel_hi:[1,0]
	v_pk_mul_f32 v[112:113], v[112:113], v[208:209]
	v_pk_mul_f32 v[114:115], v[114:115], v[210:211]
	v_pk_mul_f32 v[116:117], v[116:117], v[212:213]
	v_pk_mul_f32 v[118:119], v[118:119], v[214:215]
	v_pk_mul_f32 v[120:121], v[120:121], v[216:217]
	v_pk_mul_f32 v[122:123], v[122:123], v[218:219]
	v_pk_mul_f32 v[124:125], v[124:125], v[220:221]
	v_pk_mul_f32 v[100:101], v[100:101], v[222:223]
	v_lshlrev_b32_e32 v92, 16, v84
	v_and_b32_e32 v93, 0xffff0000, v84
	v_lshlrev_b32_e32 v94, 16, v85
	v_and_b32_e32 v95, 0xffff0000, v85
	v_lshlrev_b32_e32 v96, 16, v86
	v_and_b32_e32 v97, 0xffff0000, v86
	v_lshlrev_b32_e32 v98, 16, v87
	v_and_b32_e32 v99, 0xffff0000, v87
	v_lshlrev_b32_e32 v240, 16, v88
	v_and_b32_e32 v241, 0xffff0000, v88
	v_lshlrev_b32_e32 v242, 16, v89
	v_and_b32_e32 v243, 0xffff0000, v89
	v_lshlrev_b32_e32 v244, 16, v90
	v_and_b32_e32 v245, 0xffff0000, v90
	v_lshlrev_b32_e32 v246, 16, v91
	v_and_b32_e32 v247, 0xffff0000, v91
	v_pk_mul_f32 v[92:93], v[92:93], v[110:111] op_sel_hi:[1,0]
	v_pk_mul_f32 v[94:95], v[94:95], v[110:111] op_sel_hi:[1,0]
	v_pk_mul_f32 v[96:97], v[96:97], v[110:111] op_sel_hi:[1,0]
	v_pk_mul_f32 v[98:99], v[98:99], v[110:111] op_sel_hi:[1,0]
	v_pk_mul_f32 v[240:241], v[240:241], v[110:111] op_sel_hi:[1,0]
	v_pk_mul_f32 v[242:243], v[242:243], v[110:111] op_sel_hi:[1,0]
	v_pk_mul_f32 v[244:245], v[244:245], v[110:111] op_sel_hi:[1,0]
	v_pk_mul_f32 v[246:247], v[246:247], v[110:111] op_sel_hi:[1,0]
	v_pk_mul_f32 v[92:93], v[92:93], v[176:177]
	v_pk_mul_f32 v[94:95], v[94:95], v[178:179]
	v_pk_mul_f32 v[96:97], v[96:97], v[180:181]
	v_pk_mul_f32 v[98:99], v[98:99], v[182:183]
	v_pk_mul_f32 v[240:241], v[240:241], v[184:185]
	v_pk_mul_f32 v[242:243], v[242:243], v[186:187]
	v_pk_mul_f32 v[244:245], v[244:245], v[188:189]
	v_pk_mul_f32 v[246:247], v[246:247], v[190:191]
	v_pk_fma_f32 v[68:69], v[160:161], v[92:93], v[68:69]
	v_pk_fma_f32 v[70:71], v[162:163], v[94:95], v[70:71]
	v_pk_fma_f32 v[72:73], v[164:165], v[96:97], v[72:73]
	v_pk_fma_f32 v[74:75], v[166:167], v[98:99], v[74:75]
	v_pk_fma_f32 v[76:77], v[168:169], v[240:241], v[76:77]
	v_pk_fma_f32 v[78:79], v[170:171], v[242:243], v[78:79]
	v_pk_fma_f32 v[80:81], v[172:173], v[244:245], v[80:81]
	v_pk_fma_f32 v[82:83], v[174:175], v[246:247], v[82:83]
	v_pk_fma_f32 v[68:69], v[192:193], v[112:113], v[68:69]
	v_pk_fma_f32 v[70:71], v[194:195], v[114:115], v[70:71]
	v_pk_fma_f32 v[72:73], v[196:197], v[116:117], v[72:73]
	v_pk_fma_f32 v[74:75], v[198:199], v[118:119], v[74:75]
	v_pk_fma_f32 v[76:77], v[200:201], v[120:121], v[76:77]
	v_pk_fma_f32 v[78:79], v[202:203], v[122:123], v[78:79]
	v_pk_fma_f32 v[80:81], v[204:205], v[124:125], v[80:81]
	v_pk_fma_f32 v[82:83], v[206:207], v[100:101], v[82:83]
	s_lshl_b32 s60, s55, 12
	s_add_u32 s72, s84, s60
	s_addc_u32 s73, s85, 0
	global_store_dwordx4 v0, v[68:71], s[72:73] sc1
	global_store_dwordx4 v0, v[72:75], s[72:73] offset:1024 sc1
	global_store_dwordx4 v0, v[76:79], s[72:73] offset:2048 sc1
	global_store_dwordx4 v0, v[80:83], s[72:73] offset:3072 sc1
	s_add_u32 s55, s55, 8

; __device__ __forceinline__ float lo_bf(unsigned w) { return __uint_as_float(w << 16); }
; __device__ __forceinline__ float hi_bf(unsigned w) { return __uint_as_float(w & 0xffff0000u); }
; __device__ __forceinline__ void phase_final(const Params& p) {
;     ...
;         for (int j = 0; j < 4; ++j) { v[j] = *(const f32x4*)(p.out + (size_t)row * D + 4 * lane + 256 * j);
;             const u32x2 wm = *(const u32x2*)(Fm + (size_t)row * D + 4 * lane + 256 * j), wf = *(const u32x2*)(F2 + (size_t)row * D + 4 * lane + 256 * j);
;             m[j] = (f32x4){lo_bf(wm.x), hi_bf(wm.x), lo_bf(wm.y), hi_bf(wm.y)}; f[j] = (f32x4){lo_bf(wf.x), hi_bf(wf.x), lo_bf(wf.y), hi_bf(wf.y)};
;             sm += (m[j].x * m[j].x + m[j].y * m[j].y) + (m[j].z * m[j].z + m[j].w * m[j].w); sf += (f[j].x * f[j].x + f[j].y * f[j].y) + (f[j].z * f[j].z + f[j].w * f[j].w); }
;         const float rm = 1.0f / sqrtf(wave_sum(sm) * (1.0f / D) + EPS), rf = 1.0f / sqrtf(wave_sum(sf) * (1.0f / D) + EPS) * 0.5f;
.Lrp15_pk7:
	s_waitcnt vmcnt(32)
	v_lshlrev_b32_e32 v112, 16, v20
	v_and_b32_e32 v113, 0xffff0000, v20
	v_lshlrev_b32_e32 v114, 16, v21
	v_and_b32_e32 v115, 0xffff0000, v21
	v_lshlrev_b32_e32 v116, 16, v22
	v_and_b32_e32 v117, 0xffff0000, v22
	v_lshlrev_b32_e32 v118, 16, v23
	v_and_b32_e32 v119, 0xffff0000, v23
	v_lshlrev_b32_e32 v120, 16, v24
	v_and_b32_e32 v121, 0xffff0000, v24
	v_lshlrev_b32_e32 v122, 16, v25
	v_and_b32_e32 v123, 0xffff0000, v25
	v_lshlrev_b32_e32 v124, 16, v26
	v_and_b32_e32 v125, 0xffff0000, v26
	v_lshlrev_b32_e32 v100, 16, v27
	v_and_b32_e32 v101, 0xffff0000, v27
	v_pk_mul_f32 v[102:103], v[112:113], v[112:113]
	v_pk_mul_f32 v[106:107], v[114:115], v[114:115]
	v_pk_fma_f32 v[102:103], v[116:117], v[116:117], v[102:103]
	v_pk_fma_f32 v[106:107], v[118:119], v[118:119], v[106:107]
	v_pk_fma_f32 v[102:103], v[120:121], v[120:121], v[102:103]
	v_pk_fma_f32 v[106:107], v[122:123], v[122:123], v[106:107]
	v_pk_fma_f32 v[102:103], v[124:125], v[124:125], v[102:103]
	v_pk_fma_f32 v[106:107], v[100:101], v[100:101], v[106:107]
	v_pk_add_f32 v[102:103], v[102:103], v[106:107]
	v_add_f32_e32 v102, v102, v103
	v_mov_b32_e32 v104, v102
	v_lshlrev_b32_e32 v112, 16, v28
	v_and_b32_e32 v113, 0xffff0000, v28
	v_lshlrev_b32_e32 v114, 16, v29
	v_and_b32_e32 v115, 0xffff0000, v29
	v_lshlrev_b32_e32 v116, 16, v30
	v_and_b32_e32 v117, 0xffff0000, v30
	v_lshlrev_b32_e32 v118, 16, v31
	v_and_b32_e32 v119, 0xffff0000, v31
	v_lshlrev_b32_e32 v120, 16, v32
	v_and_b32_e32 v121, 0xffff0000, v32
	v_lshlrev_b32_e32 v122, 16, v33
	v_and_b32_e32 v123, 0xffff0000, v33
	v_lshlrev_b32_e32 v124, 16, v34
	v_and_b32_e32 v125, 0xffff0000, v34
	v_lshlrev_b32_e32 v100, 16, v35
	v_and_b32_e32 v101, 0xffff0000, v35
	v_pk_mul_f32 v[102:103], v[112:113], v[112:113]
	v_pk_mul_f32 v[106:107], v[114:115], v[114:115]
	v_pk_fma_f32 v[102:103], v[116:117], v[116:117], v[102:103]
	v_pk_fma_f32 v[106:107], v[118:119], v[118:119], v[106:107]
	v_pk_fma_f32 v[102:103], v[120:121], v[120:121], v[102:103]
	v_pk_fma_f32 v[106:107], v[122:123], v[122:123], v[106:107]
	v_pk_fma_f32 v[102:103], v[124:125], v[124:125], v[102:103]
	v_pk_fma_f32 v[106:107], v[100:101], v[100:101], v[106:107]
	v_pk_add_f32 v[102:103], v[102:103], v[106:107]
	v_add_f32_e32 v102, v102, v103
	s_nop 1
	v_add_f32_dpp v104, v104, v104 quad_perm:[1,0,3,2] row_mask:0xf bank_mask:0xf
	v_add_f32_dpp v102, v102, v102 quad_perm:[1,0,3,2] row_mask:0xf bank_mask:0xf
	s_nop 1
	v_add_f32_dpp v104, v104, v104 quad_perm:[2,3,0,1] row_mask:0xf bank_mask:0xf
	v_add_f32_dpp v102, v102, v102 quad_perm:[2,3,0,1] row_mask:0xf bank_mask:0xf
	s_nop 1
	v_add_f32_dpp v104, v104, v104 row_half_mirror row_mask:0xf bank_mask:0xf
	v_add_f32_dpp v102, v102, v102 row_half_mirror row_mask:0xf bank_mask:0xf
	s_nop 1
	v_add_f32_dpp v104, v104, v104 row_mirror row_mask:0xf bank_mask:0xf
	v_add_f32_dpp v102, v102, v102 row_mirror row_mask:0xf bank_mask:0xf
	s_nop 1
	v_add_f32_dpp v104, v104, v104 row_bcast:15 row_mask:0xa bank_mask:0xf
	v_add_f32_dpp v102, v102, v102 row_bcast:15 row_mask:0xa bank_mask:0xf
	s_nop 1
	v_add_f32_dpp v104, v104, v104 row_bcast:31 row_mask:0xc bank_mask:0xf
	v_add_f32_dpp v102, v102, v102 row_bcast:31 row_mask:0xc bank_mask:0xf
	s_nop 1
	v_readlane_b32 s74, v104, 63
	v_readlane_b32 s75, v102, 63
	s_nop 2
	v_mov_b32_e32 v102, s74
	v_fmamk_f32 v102, v102, 0x3a800000, v2
	v_mul_f32_e32 v103, 0x4f800000, v102
	v_cmp_gt_f32_e32 vcc, 0xf800000, v102
	s_nop 1
	v_cndmask_b32_e32 v102, v102, v103, vcc
	v_sqrt_f32_e32 v103, v102
	s_nop 0
	v_add_u32_e32 v104, -1, v103
	v_add_u32_e32 v106, 1, v103
	v_fma_f32 v107, -v104, v103, v102
	v_fma_f32 v108, -v106, v103, v102
	v_cmp_ge_f32_e64 s[76:77], 0, v107
	s_nop 1
	v_cndmask_b32_e64 v103, v103, v104, s[76:77]
	v_cmp_lt_f32_e64 s[76:77], 0, v108
	s_nop 1
	v_cndmask_b32_e64 v103, v103, v106, s[76:77]
	v_mul_f32_e32 v104, 0x37800000, v103
	v_cndmask_b32_e32 v103, v103, v104, vcc
	v_cmp_class_f32_e32 vcc, v102, v3
	s_nop 1
	v_cndmask_b32_e32 v102, v103, v102, vcc
	v_div_scale_f32 v103, s[76:77], v102, v102, 1.0
	v_rcp_f32_e32 v104, v103
	v_div_scale_f32 v106, vcc, 1.0, v102, 1.0
	v_fma_f32 v107, -v103, v104, 1.0
	v_fmac_f32_e32 v104, v107, v104
	v_mul_f32_e32 v107, v106, v104
	v_fma_f32 v108, -v103, v107, v106
	v_fmac_f32_e32 v107, v108, v104
	v_fma_f32 v103, -v103, v107, v106
	v_div_fmas_f32 v103, v103, v104, v107
	v_div_fixup_f32 v110, v103, v102, 1.0
	v_mov_b32_e32 v102, s75
	v_fmamk_f32 v102, v102, 0x3a800000, v2
	v_mul_f32_e32 v103, 0x4f800000, v102
	v_cmp_gt_f32_e32 vcc, 0xf800000, v102
	s_nop 1
	v_cndmask_b32_e32 v102, v102, v103, vcc
	v_sqrt_f32_e32 v103, v102
	s_nop 0
	v_add_u32_e32 v104, -1, v103
	v_add_u32_e32 v106, 1, v103
	v_fma_f32 v107, -v104, v103, v102
	v_fma_f32 v108, -v106, v103, v102
	v_cmp_ge_f32_e64 s[76:77], 0, v107
	s_nop 1
	v_cndmask_b32_e64 v103, v103, v104, s[76:77]
	v_cmp_lt_f32_e64 s[76:77], 0, v108
	s_nop 1
	v_cndmask_b32_e64 v103, v103, v106, s[76:77]
	v_mul_f32_e32 v104, 0x37800000, v103
	v_cndmask_b32_e32 v103, v103, v104, vcc
	v_cmp_class_f32_e32 vcc, v102, v3
	s_nop 1
	v_cndmask_b32_e32 v102, v103, v102, vcc
	v_div_scale_f32 v103, s[76:77], v102, v102, 1.0
	v_rcp_f32_e32 v104, v103
	v_div_scale_f32 v106, vcc, 1.0, v102, 1.0
	v_fma_f32 v107, -v103, v104, 1.0
	v_fmac_f32_e32 v104, v107, v104
	v_mul_f32_e32 v107, v106, v104
	v_fma_f32 v108, -v103, v107, v106
	v_fmac_f32_e32 v107, v108, v104
	v_fma_f32 v103, -v103, v107, v106
	v_div_fmas_f32 v103, v103, v104, v107
	v_div_fixup_f32 v108, v103, v102, 1.0
	v_mul_f32_e32 v108, 0.5, v108
	v_pk_mul_f32 v[112:113], v[112:113], v[108:109] op_sel_hi:[1,0]
	v_pk_mul_f32 v[114:115], v[114:115], v[108:109] op_sel_hi:[1,0]
; __device__ __forceinline__ void phase_final(const Params& p) {
;     ...
;         for (int j = 0; j < 4; ++j) { v[j] = *(const f32x4*)(p.out + (size_t)row * D + 4 * lane + 256 * j);
;             const u32x2 wm = *(const u32x2*)(Fm + (size_t)row * D + 4 * lane + 256 * j), wf = *(const u32x2*)(F2 + (size_t)row * D + 4 * lane + 256 * j);
;     ...
;         const float rm = 1.0f / sqrtf(wave_sum(sm) * (1.0f / D) + EPS), rf = 1.0f / sqrtf(wave_sum(sf) * (1.0f / D) + EPS) * 0.5f;
;         const float* g1 = mod + b * 9216 + 1 * 3072 + 2048; const float* g2 = mod + b * 9216 + 2 * 3072 + 2048;
;         const float* q1 = p.in[7] + 1 * D; const float* q2 = p.in[7] + 2 * D;
; #pragma unroll
;         for (int j = 0; j < 4; ++j) { const int c = 4 * lane + 256 * j;
;             const f32x4 x2 = v[j] + *(const f32x4*)(g1 + c) * (m[j] * rm * *(const f32x4*)(q1 + c));
;             *(f32x4*)(p.out + (size_t)row * D + c) = x2 + *(const f32x4*)(g2 + c) * (f[j] * rf * *(const f32x4*)(q2 + c)); }
	v_pk_mul_f32 v[116:117], v[116:117], v[108:109] op_sel_hi:[1,0]
	v_pk_mul_f32 v[118:119], v[118:119], v[108:109] op_sel_hi:[1,0]
	v_pk_mul_f32 v[120:121], v[120:121], v[108:109] op_sel_hi:[1,0]
	v_pk_mul_f32 v[122:123], v[122:123], v[108:109] op_sel_hi:[1,0]
	v_pk_mul_f32 v[124:125], v[124:125], v[108:109] op_sel_hi:[1,0]
	v_pk_mul_f32 v[100:101], v[100:101], v[108:109] op_sel_hi:[1,0]
	v_pk_mul_f32 v[112:113], v[112:113], v[208:209]
	v_pk_mul_f32 v[114:115], v[114:115], v[210:211]
	v_pk_mul_f32 v[116:117], v[116:117], v[212:213]
	v_pk_mul_f32 v[118:119], v[118:119], v[214:215]
	v_pk_mul_f32 v[120:121], v[120:121], v[216:217]
	v_pk_mul_f32 v[122:123], v[122:123], v[218:219]
	v_pk_mul_f32 v[124:125], v[124:125], v[220:221]
	v_pk_mul_f32 v[100:101], v[100:101], v[222:223]
	v_lshlrev_b32_e32 v28, 16, v20
	v_and_b32_e32 v29, 0xffff0000, v20
	v_lshlrev_b32_e32 v30, 16, v21
	v_and_b32_e32 v31, 0xffff0000, v21
	v_lshlrev_b32_e32 v32, 16, v22
	v_and_b32_e32 v33, 0xffff0000, v22
	v_lshlrev_b32_e32 v34, 16, v23
	v_and_b32_e32 v35, 0xffff0000, v23
	v_lshlrev_b32_e32 v240, 16, v24
	v_and_b32_e32 v241, 0xffff0000, v24
	v_lshlrev_b32_e32 v242, 16, v25
	v_and_b32_e32 v243, 0xffff0000, v25
	v_lshlrev_b32_e32 v244, 16, v26
	v_and_b32_e32 v245, 0xffff0000, v26
	v_lshlrev_b32_e32 v246, 16, v27
	v_and_b32_e32 v247, 0xffff0000, v27
	v_pk_mul_f32 v[28:29], v[28:29], v[110:111] op_sel_hi:[1,0]
	v_pk_mul_f32 v[30:31], v[30:31], v[110:111] op_sel_hi:[1,0]
	v_pk_mul_f32 v[32:33], v[32:33], v[110:111] op_sel_hi:[1,0]
	v_pk_mul_f32 v[34:35], v[34:35], v[110:111] op_sel_hi:[1,0]
	v_pk_mul_f32 v[240:241], v[240:241], v[110:111] op_sel_hi:[1,0]
	v_pk_mul_f32 v[242:243], v[242:243], v[110:111] op_sel_hi:[1,0]
	v_pk_mul_f32 v[244:245], v[244:245], v[110:111] op_sel_hi:[1,0]
	v_pk_mul_f32 v[246:247], v[246:247], v[110:111] op_sel_hi:[1,0]
	v_pk_mul_f32 v[28:29], v[28:29], v[176:177]
	v_pk_mul_f32 v[30:31], v[30:31], v[178:179]
	v_pk_mul_f32 v[32:33], v[32:33], v[180:181]
	v_pk_mul_f32 v[34:35], v[34:35], v[182:183]
	v_pk_mul_f32 v[240:241], v[240:241], v[184:185]
	v_pk_mul_f32 v[242:243], v[242:243], v[186:187]
	v_pk_mul_f32 v[244:245], v[244:245], v[188:189]
	v_pk_mul_f32 v[246:247], v[246:247], v[190:191]
	v_pk_fma_f32 v[4:5], v[160:161], v[28:29], v[4:5]
	v_pk_fma_f32 v[6:7], v[162:163], v[30:31], v[6:7]
	v_pk_fma_f32 v[8:9], v[164:165], v[32:33], v[8:9]
	v_pk_fma_f32 v[10:11], v[166:167], v[34:35], v[10:11]
	v_pk_fma_f32 v[12:13], v[168:169], v[240:241], v[12:13]
	v_pk_fma_f32 v[14:15], v[170:171], v[242:243], v[14:15]
	v_pk_fma_f32 v[16:17], v[172:173], v[244:245], v[16:17]
	v_pk_fma_f32 v[18:19], v[174:175], v[246:247], v[18:19]
	v_pk_fma_f32 v[4:5], v[192:193], v[112:113], v[4:5]
	v_pk_fma_f32 v[6:7], v[194:195], v[114:115], v[6:7]
	v_pk_fma_f32 v[8:9], v[196:197], v[116:117], v[8:9]
	v_pk_fma_f32 v[10:11], v[198:199], v[118:119], v[10:11]
	v_pk_fma_f32 v[12:13], v[200:201], v[120:121], v[12:13]
	v_pk_fma_f32 v[14:15], v[202:203], v[122:123], v[14:15]
	v_pk_fma_f32 v[16:17], v[204:205], v[124:125], v[16:17]
	v_pk_fma_f32 v[18:19], v[206:207], v[100:101], v[18:19]
	s_lshl_b32 s60, s55, 12
	s_add_u32 s72, s84, s60
	s_addc_u32 s73, s85, 0
	global_store_dwordx4 v0, v[4:7], s[72:73] sc1
	global_store_dwordx4 v0, v[8:11], s[72:73] offset:1024 sc1
	global_store_dwordx4 v0, v[12:15], s[72:73] offset:2048 sc1
	global_store_dwordx4 v0, v[16:19], s[72:73] offset:3072 sc1
	s_add_u32 s55, s55, 8
	s_add_u32 s57, s55, 16
	s_min_u32 s57, s57, s54
	s_lshl_b32 s60, s57, 12
	s_add_u32 s64, s84, s60
	s_addc_u32 s65, s85, 0
	s_lshl_b32 s60, s57, 11
	s_add_u32 s66, s82, s60
	s_addc_u32 s67, s83, 0
	s_lshl_b32 s60, s57, 11
	s_add_u32 s68, s78, s60
	s_addc_u32 s69, s79, 0
	global_load_dwordx4 v[4:7], v0, s[64:65] nt
	global_load_dwordx4 v[8:11], v0, s[64:65] offset:1024 nt
	global_load_dwordx4 v[12:15], v0, s[64:65] offset:2048 nt
	global_load_dwordx4 v[16:19], v0, s[64:65] offset:3072 nt
	global_load_dwordx2 v[20:21], v1, s[66:67] nt
	global_load_dwordx2 v[22:23], v1, s[66:67] offset:512 nt
	global_load_dwordx2 v[24:25], v1, s[66:67] offset:1024 nt
	global_load_dwordx2 v[26:27], v1, s[66:67] offset:1536 nt
	global_load_dwordx2 v[28:29], v1, s[68:69] nt
	global_load_dwordx2 v[30:31], v1, s[68:69] offset:512 nt
	global_load_dwordx2 v[32:33], v1, s[68:69] offset:1024 nt
	global_load_dwordx2 v[34:35], v1, s[68:69] offset:1536 nt
	s_lshr_b32 s60, s55, 11
	s_sub_u32 s61, s55, 0x8000
	s_lshr_b32 s61, s61, 12
	s_add_u32 s61, s61, 16
	s_cmp_lt_u32 s55, 0x8000
	s_cselect_b32 s63, s60, s61
	s_cmp_eq_u32 s63, s56
	s_cbranch_scc1 .Lrp15_pk8
	s_mov_b32 s56, s63
	s_mul_i32 s60, s56, 0x9000
	s_add_u32 s60, s60, 0x3185000
	s_add_u32 s0, s92, s60
	s_addc_u32 s1, s93, 0
	global_load_dwordx4 v[160:163], v0, s[0:1]
	global_load_dwordx4 v[164:167], v0, s[0:1] offset:1024
	global_load_dwordx4 v[168:171], v0, s[0:1] offset:2048
	global_load_dwordx4 v[172:175], v0, s[0:1] offset:3072
	s_add_u32 s0, s22, 0x1000
	s_addc_u32 s1, s23, 0
	global_load_dwordx4 v[176:179], v0, s[0:1]
	global_load_dwordx4 v[180:183], v0, s[0:1] offset:1024
	global_load_dwordx4 v[184:187], v0, s[0:1] offset:2048
	global_load_dwordx4 v[188:191], v0, s[0:1] offset:3072
	s_mul_i32 s60, s56, 0x9000
	s_add_u32 s60, s60, 0x3188000
	s_add_u32 s0, s92, s60
	s_addc_u32 s1, s93, 0
	global_load_dwordx4 v[192:195], v0, s[0:1]
	global_load_dwordx4 v[196:199], v0, s[0:1] offset:1024
	global_load_dwordx4 v[200:203], v0, s[0:1] offset:2048
	global_load_dwordx4 v[204:207], v0, s[0:1] offset:3072
	s_add_u32 s0, s22, 0x2000
	s_addc_u32 s1, s23, 0
	global_load_dwordx4 v[208:211], v0, s[0:1]
	global_load_dwordx4 v[212:215], v0, s[0:1] offset:1024
	global_load_dwordx4 v[216:219], v0, s[0:1] offset:2048
	global_load_dwordx4 v[220:223], v0, s[0:1] offset:3072
	s_waitcnt vmcnt(0)
; __device__ __forceinline__ float lo_bf(unsigned w) { return __uint_as_float(w << 16); }
; __device__ __forceinline__ float hi_bf(unsigned w) { return __uint_as_float(w & 0xffff0000u); }
; __device__ __forceinline__ void phase_final(const Params& p) {
;     ...
;         for (int j = 0; j < 4; ++j) { v[j] = *(const f32x4*)(p.out + (size_t)row * D + 4 * lane + 256 * j);
;             const u32x2 wm = *(const u32x2*)(Fm + (size_t)row * D + 4 * lane + 256 * j), wf = *(const u32x2*)(F2 + (size_t)row * D + 4 * lane + 256 * j);
;             m[j] = (f32x4){lo_bf(wm.x), hi_bf(wm.x), lo_bf(wm.y), hi_bf(wm.y)}; f[j] = (f32x4){lo_bf(wf.x), hi_bf(wf.x), lo_bf(wf.y), hi_bf(wf.y)};
;             sm += (m[j].x * m[j].x + m[j].y * m[j].y) + (m[j].z * m[j].z + m[j].w * m[j].w); sf += (f[j].x * f[j].x + f[j].y * f[j].y) + (f[j].z * f[j].z + f[j].w * f[j].w); }
;         const float rm = 1.0f / sqrtf(wave_sum(sm) * (1.0f / D) + EPS), rf = 1.0f / sqrtf(wave_sum(sf) * (1.0f / D) + EPS) * 0.5f;
.Lrp15_pk8:
	s_waitcnt vmcnt(32)
	v_lshlrev_b32_e32 v112, 16, v52
	v_and_b32_e32 v113, 0xffff0000, v52
	v_lshlrev_b32_e32 v114, 16, v53
	v_and_b32_e32 v115, 0xffff0000, v53
	v_lshlrev_b32_e32 v116, 16, v54
	v_and_b32_e32 v117, 0xffff0000, v54
	v_lshlrev_b32_e32 v118, 16, v55
	v_and_b32_e32 v119, 0xffff0000, v55
	v_lshlrev_b32_e32 v120, 16, v56
	v_and_b32_e32 v121, 0xffff0000, v56
	v_lshlrev_b32_e32 v122, 16, v57
	v_and_b32_e32 v123, 0xffff0000, v57
	v_lshlrev_b32_e32 v124, 16, v58
	v_and_b32_e32 v125, 0xffff0000, v58
	v_lshlrev_b32_e32 v100, 16, v59
	v_and_b32_e32 v101, 0xffff0000, v59
	v_pk_mul_f32 v[102:103], v[112:113], v[112:113]
	v_pk_mul_f32 v[106:107], v[114:115], v[114:115]
	v_pk_fma_f32 v[102:103], v[116:117], v[116:117], v[102:103]
	v_pk_fma_f32 v[106:107], v[118:119], v[118:119], v[106:107]
	v_pk_fma_f32 v[102:103], v[120:121], v[120:121], v[102:103]
	v_pk_fma_f32 v[106:107], v[122:123], v[122:123], v[106:107]
	v_pk_fma_f32 v[102:103], v[124:125], v[124:125], v[102:103]
	v_pk_fma_f32 v[106:107], v[100:101], v[100:101], v[106:107]
	v_pk_add_f32 v[102:103], v[102:103], v[106:107]
	v_add_f32_e32 v102, v102, v103
	v_mov_b32_e32 v104, v102
	v_lshlrev_b32_e32 v112, 16, v60
	v_and_b32_e32 v113, 0xffff0000, v60
	v_lshlrev_b32_e32 v114, 16, v61
	v_and_b32_e32 v115, 0xffff0000, v61
	v_lshlrev_b32_e32 v116, 16, v62
	v_and_b32_e32 v117, 0xffff0000, v62
	v_lshlrev_b32_e32 v118, 16, v63
	v_and_b32_e32 v119, 0xffff0000, v63
	v_lshlrev_b32_e32 v120, 16, v64
	v_and_b32_e32 v121, 0xffff0000, v64
	v_lshlrev_b32_e32 v122, 16, v65
	v_and_b32_e32 v123, 0xffff0000, v65
	v_lshlrev_b32_e32 v124, 16, v66
	v_and_b32_e32 v125, 0xffff0000, v66
	v_lshlrev_b32_e32 v100, 16, v67
	v_and_b32_e32 v101, 0xffff0000, v67
	v_pk_mul_f32 v[102:103], v[112:113], v[112:113]
	v_pk_mul_f32 v[106:107], v[114:115], v[114:115]
	v_pk_fma_f32 v[102:103], v[116:117], v[116:117], v[102:103]
	v_pk_fma_f32 v[106:107], v[118:119], v[118:119], v[106:107]
	v_pk_fma_f32 v[102:103], v[120:121], v[120:121], v[102:103]
	v_pk_fma_f32 v[106:107], v[122:123], v[122:123], v[106:107]
	v_pk_fma_f32 v[102:103], v[124:125], v[124:125], v[102:103]
	v_pk_fma_f32 v[106:107], v[100:101], v[100:101], v[106:107]
	v_pk_add_f32 v[102:103], v[102:103], v[106:107]
	v_add_f32_e32 v102, v102, v103
	s_nop 1
	v_add_f32_dpp v104, v104, v104 quad_perm:[1,0,3,2] row_mask:0xf bank_mask:0xf
	v_add_f32_dpp v102, v102, v102 quad_perm:[1,0,3,2] row_mask:0xf bank_mask:0xf
	s_nop 1
	v_add_f32_dpp v104, v104, v104 quad_perm:[2,3,0,1] row_mask:0xf bank_mask:0xf
	v_add_f32_dpp v102, v102, v102 quad_perm:[2,3,0,1] row_mask:0xf bank_mask:0xf
	s_nop 1
	v_add_f32_dpp v104, v104, v104 row_half_mirror row_mask:0xf bank_mask:0xf
	v_add_f32_dpp v102, v102, v102 row_half_mirror row_mask:0xf bank_mask:0xf
	s_nop 1
	v_add_f32_dpp v104, v104, v104 row_mirror row_mask:0xf bank_mask:0xf
	v_add_f32_dpp v102, v102, v102 row_mirror row_mask:0xf bank_mask:0xf
	s_nop 1
	v_add_f32_dpp v104, v104, v104 row_bcast:15 row_mask:0xa bank_mask:0xf
	v_add_f32_dpp v102, v102, v102 row_bcast:15 row_mask:0xa bank_mask:0xf
	s_nop 1
	v_add_f32_dpp v104, v104, v104 row_bcast:31 row_mask:0xc bank_mask:0xf
	v_add_f32_dpp v102, v102, v102 row_bcast:31 row_mask:0xc bank_mask:0xf
	s_nop 1
	v_readlane_b32 s74, v104, 63
	v_readlane_b32 s75, v102, 63
	s_nop 2
	v_mov_b32_e32 v102, s74
	v_fmamk_f32 v102, v102, 0x3a800000, v2
	v_mul_f32_e32 v103, 0x4f800000, v102
	v_cmp_gt_f32_e32 vcc, 0xf800000, v102
	s_nop 1
	v_cndmask_b32_e32 v102, v102, v103, vcc
	v_sqrt_f32_e32 v103, v102
	s_nop 0
	v_add_u32_e32 v104, -1, v103
	v_add_u32_e32 v106, 1, v103
	v_fma_f32 v107, -v104, v103, v102
	v_fma_f32 v108, -v106, v103, v102
	v_cmp_ge_f32_e64 s[76:77], 0, v107
	s_nop 1
	v_cndmask_b32_e64 v103, v103, v104, s[76:77]
	v_cmp_lt_f32_e64 s[76:77], 0, v108
	s_nop 1
	v_cndmask_b32_e64 v103, v103, v106, s[76:77]
	v_mul_f32_e32 v104, 0x37800000, v103
	v_cndmask_b32_e32 v103, v103, v104, vcc
	v_cmp_class_f32_e32 vcc, v102, v3
	s_nop 1
	v_cndmask_b32_e32 v102, v103, v102, vcc
	v_div_scale_f32 v103, s[76:77], v102, v102, 1.0
	v_rcp_f32_e32 v104, v103
	v_div_scale_f32 v106, vcc, 1.0, v102, 1.0
	v_fma_f32 v107, -v103, v104, 1.0
	v_fmac_f32_e32 v104, v107, v104
	v_mul_f32_e32 v107, v106, v104
	v_fma_f32 v108, -v103, v107, v106
	v_fmac_f32_e32 v107, v108, v104
	v_fma_f32 v103, -v103, v107, v106
	v_div_fmas_f32 v103, v103, v104, v107
	v_div_fixup_f32 v110, v103, v102, 1.0
	v_mov_b32_e32 v102, s75
	v_fmamk_f32 v102, v102, 0x3a800000, v2
	v_mul_f32_e32 v103, 0x4f800000, v102
	v_cmp_gt_f32_e32 vcc, 0xf800000, v102
	s_nop 1
	v_cndmask_b32_e32 v102, v102, v103, vcc
	v_sqrt_f32_e32 v103, v102
	s_nop 0
	v_add_u32_e32 v104, -1, v103
	v_add_u32_e32 v106, 1, v103
	v_fma_f32 v107, -v104, v103, v102
	v_fma_f32 v108, -v106, v103, v102
	v_cmp_ge_f32_e64 s[76:77], 0, v107
	s_nop 1
	v_cndmask_b32_e64 v103, v103, v104, s[76:77]
	v_cmp_lt_f32_e64 s[76:77], 0, v108
	s_nop 1
	v_cndmask_b32_e64 v103, v103, v106, s[76:77]
	v_mul_f32_e32 v104, 0x37800000, v103
	v_cndmask_b32_e32 v103, v103, v104, vcc
	v_cmp_class_f32_e32 vcc, v102, v3
	s_nop 1
	v_cndmask_b32_e32 v102, v103, v102, vcc
	v_div_scale_f32 v103, s[76:77], v102, v102, 1.0
	v_rcp_f32_e32 v104, v103
	v_div_scale_f32 v106, vcc, 1.0, v102, 1.0
	v_fma_f32 v107, -v103, v104, 1.0
	v_fmac_f32_e32 v104, v107, v104
	v_mul_f32_e32 v107, v106, v104
	v_fma_f32 v108, -v103, v107, v106
	v_fmac_f32_e32 v107, v108, v104
	v_fma_f32 v103, -v103, v107, v106
	v_div_fmas_f32 v103, v103, v104, v107
	v_div_fixup_f32 v108, v103, v102, 1.0
	v_mul_f32_e32 v108, 0.5, v108
	v_pk_mul_f32 v[112:113], v[112:113], v[108:109] op_sel_hi:[1,0]
	v_pk_mul_f32 v[114:115], v[114:115], v[108:109] op_sel_hi:[1,0]
; __device__ __forceinline__ void phase_final(const Params& p) {
;     ...
;         for (int j = 0; j < 4; ++j) { v[j] = *(const f32x4*)(p.out + (size_t)row * D + 4 * lane + 256 * j);
;             const u32x2 wm = *(const u32x2*)(Fm + (size_t)row * D + 4 * lane + 256 * j), wf = *(const u32x2*)(F2 + (size_t)row * D + 4 * lane + 256 * j);
;     ...
;         const float rm = 1.0f / sqrtf(wave_sum(sm) * (1.0f / D) + EPS), rf = 1.0f / sqrtf(wave_sum(sf) * (1.0f / D) + EPS) * 0.5f;
;         const float* g1 = mod + b * 9216 + 1 * 3072 + 2048; const float* g2 = mod + b * 9216 + 2 * 3072 + 2048;
;         const float* q1 = p.in[7] + 1 * D; const float* q2 = p.in[7] + 2 * D;
; #pragma unroll
;         for (int j = 0; j < 4; ++j) { const int c = 4 * lane + 256 * j;
;             const f32x4 x2 = v[j] + *(const f32x4*)(g1 + c) * (m[j] * rm * *(const f32x4*)(q1 + c));
;             *(f32x4*)(p.out + (size_t)row * D + c) = x2 + *(const f32x4*)(g2 + c) * (f[j] * rf * *(const f32x4*)(q2 + c)); }
	v_pk_mul_f32 v[116:117], v[116:117], v[108:109] op_sel_hi:[1,0]
	v_pk_mul_f32 v[118:119], v[118:119], v[108:109] op_sel_hi:[1,0]
	v_pk_mul_f32 v[120:121], v[120:121], v[108:109] op_sel_hi:[1,0]
	v_pk_mul_f32 v[122:123], v[122:123], v[108:109] op_sel_hi:[1,0]
	v_pk_mul_f32 v[124:125], v[124:125], v[108:109] op_sel_hi:[1,0]
	v_pk_mul_f32 v[100:101], v[100:101], v[108:109] op_sel_hi:[1,0]
	v_pk_mul_f32 v[112:113], v[112:113], v[208:209]
	v_pk_mul_f32 v[114:115], v[114:115], v[210:211]
	v_pk_mul_f32 v[116:117], v[116:117], v[212:213]
	v_pk_mul_f32 v[118:119], v[118:119], v[214:215]
	v_pk_mul_f32 v[120:121], v[120:121], v[216:217]
	v_pk_mul_f32 v[122:123], v[122:123], v[218:219]
	v_pk_mul_f32 v[124:125], v[124:125], v[220:221]
	v_pk_mul_f32 v[100:101], v[100:101], v[222:223]
	v_lshlrev_b32_e32 v60, 16, v52
	v_and_b32_e32 v61, 0xffff0000, v52
	v_lshlrev_b32_e32 v62, 16, v53
	v_and_b32_e32 v63, 0xffff0000, v53
	v_lshlrev_b32_e32 v64, 16, v54
	v_and_b32_e32 v65, 0xffff0000, v54
	v_lshlrev_b32_e32 v66, 16, v55
	v_and_b32_e32 v67, 0xffff0000, v55
	v_lshlrev_b32_e32 v240, 16, v56
	v_and_b32_e32 v241, 0xffff0000, v56
	v_lshlrev_b32_e32 v242, 16, v57
	v_and_b32_e32 v243, 0xffff0000, v57
	v_lshlrev_b32_e32 v244, 16, v58
	v_and_b32_e32 v245, 0xffff0000, v58
	v_lshlrev_b32_e32 v246, 16, v59
	v_and_b32_e32 v247, 0xffff0000, v59
	v_pk_mul_f32 v[60:61], v[60:61], v[110:111] op_sel_hi:[1,0]
	v_pk_mul_f32 v[62:63], v[62:63], v[110:111] op_sel_hi:[1,0]
	v_pk_mul_f32 v[64:65], v[64:65], v[110:111] op_sel_hi:[1,0]
	v_pk_mul_f32 v[66:67], v[66:67], v[110:111] op_sel_hi:[1,0]
	v_pk_mul_f32 v[240:241], v[240:241], v[110:111] op_sel_hi:[1,0]
	v_pk_mul_f32 v[242:243], v[242:243], v[110:111] op_sel_hi:[1,0]
	v_pk_mul_f32 v[244:245], v[244:245], v[110:111] op_sel_hi:[1,0]
	v_pk_mul_f32 v[246:247], v[246:247], v[110:111] op_sel_hi:[1,0]
	v_pk_mul_f32 v[60:61], v[60:61], v[176:177]
	v_pk_mul_f32 v[62:63], v[62:63], v[178:179]
	v_pk_mul_f32 v[64:65], v[64:65], v[180:181]
	v_pk_mul_f32 v[66:67], v[66:67], v[182:183]
	v_pk_mul_f32 v[240:241], v[240:241], v[184:185]
	v_pk_mul_f32 v[242:243], v[242:243], v[186:187]
	v_pk_mul_f32 v[244:245], v[244:245], v[188:189]
	v_pk_mul_f32 v[246:247], v[246:247], v[190:191]
	v_pk_fma_f32 v[36:37], v[160:161], v[60:61], v[36:37]
	v_pk_fma_f32 v[38:39], v[162:163], v[62:63], v[38:39]
	v_pk_fma_f32 v[40:41], v[164:165], v[64:65], v[40:41]
	v_pk_fma_f32 v[42:43], v[166:167], v[66:67], v[42:43]
	v_pk_fma_f32 v[44:45], v[168:169], v[240:241], v[44:45]
	v_pk_fma_f32 v[46:47], v[170:171], v[242:243], v[46:47]
	v_pk_fma_f32 v[48:49], v[172:173], v[244:245], v[48:49]
	v_pk_fma_f32 v[50:51], v[174:175], v[246:247], v[50:51]
	v_pk_fma_f32 v[36:37], v[192:193], v[112:113], v[36:37]
	v_pk_fma_f32 v[38:39], v[194:195], v[114:115], v[38:39]
	v_pk_fma_f32 v[40:41], v[196:197], v[116:117], v[40:41]
	v_pk_fma_f32 v[42:43], v[198:199], v[118:119], v[42:43]
	v_pk_fma_f32 v[44:45], v[200:201], v[120:121], v[44:45]
	v_pk_fma_f32 v[46:47], v[202:203], v[122:123], v[46:47]
	v_pk_fma_f32 v[48:49], v[204:205], v[124:125], v[48:49]
	v_pk_fma_f32 v[50:51], v[206:207], v[100:101], v[50:51]
	s_lshl_b32 s60, s55, 12
	s_add_u32 s72, s84, s60
	s_addc_u32 s73, s85, 0
	global_store_dwordx4 v0, v[36:39], s[72:73] sc1
	global_store_dwordx4 v0, v[40:43], s[72:73] offset:1024 sc1
	global_store_dwordx4 v0, v[44:47], s[72:73] offset:2048 sc1
	global_store_dwordx4 v0, v[48:51], s[72:73] offset:3072 sc1
	s_add_u32 s55, s55, 8
	s_add_u32 s57, s55, 16
	s_min_u32 s57, s57, s54
	s_lshl_b32 s60, s57, 12
	s_add_u32 s64, s84, s60
	s_addc_u32 s65, s85, 0
	s_lshl_b32 s60, s57, 11
	s_add_u32 s66, s82, s60
	s_addc_u32 s67, s83, 0
	s_lshl_b32 s60, s57, 11
	s_add_u32 s68, s78, s60
	s_addc_u32 s69, s79, 0
	global_load_dwordx4 v[36:39], v0, s[64:65] nt
	global_load_dwordx4 v[40:43], v0, s[64:65] offset:1024 nt
	global_load_dwordx4 v[44:47], v0, s[64:65] offset:2048 nt
	global_load_dwordx4 v[48:51], v0, s[64:65] offset:3072 nt
	global_load_dwordx2 v[52:53], v1, s[66:67] nt
	global_load_dwordx2 v[54:55], v1, s[66:67] offset:512 nt
	global_load_dwordx2 v[56:57], v1, s[66:67] offset:1024 nt
	global_load_dwordx2 v[58:59], v1, s[66:67] offset:1536 nt
	global_load_dwordx2 v[60:61], v1, s[68:69] nt
	global_load_dwordx2 v[62:63], v1, s[68:69] offset:512 nt
	global_load_dwordx2 v[64:65], v1, s[68:69] offset:1024 nt
	global_load_dwordx2 v[66:67], v1, s[68:69] offset:1536 nt
	s_lshr_b32 s60, s55, 11
	s_sub_u32 s61, s55, 0x8000
	s_lshr_b32 s61, s61, 12
	s_add_u32 s61, s61, 16
	s_cmp_lt_u32 s55, 0x8000
	s_cselect_b32 s63, s60, s61
	s_cmp_eq_u32 s63, s56
	s_cbranch_scc1 .Lrp15_pk9
	s_mov_b32 s56, s63
	s_mul_i32 s60, s56, 0x9000
	s_add_u32 s60, s60, 0x3185000
	s_add_u32 s0, s92, s60
	s_addc_u32 s1, s93, 0
	global_load_dwordx4 v[160:163], v0, s[0:1]
	global_load_dwordx4 v[164:167], v0, s[0:1] offset:1024
	global_load_dwordx4 v[168:171], v0, s[0:1] offset:2048
	global_load_dwordx4 v[172:175], v0, s[0:1] offset:3072
	s_add_u32 s0, s22, 0x1000
	s_addc_u32 s1, s23, 0
	global_load_dwordx4 v[176:179], v0, s[0:1]
	global_load_dwordx4 v[180:183], v0, s[0:1] offset:1024
	global_load_dwordx4 v[184:187], v0, s[0:1] offset:2048
	global_load_dwordx4 v[188:191], v0, s[0:1] offset:3072
	s_mul_i32 s60, s56, 0x9000
	s_add_u32 s60, s60, 0x3188000
	s_add_u32 s0, s92, s60
	s_addc_u32 s1, s93, 0
	global_load_dwordx4 v[192:195], v0, s[0:1]
	global_load_dwordx4 v[196:199], v0, s[0:1] offset:1024
	global_load_dwordx4 v[200:203], v0, s[0:1] offset:2048
	global_load_dwordx4 v[204:207], v0, s[0:1] offset:3072
	s_add_u32 s0, s22, 0x2000
	s_addc_u32 s1, s23, 0
	global_load_dwordx4 v[208:211], v0, s[0:1]
	global_load_dwordx4 v[212:215], v0, s[0:1] offset:1024
	global_load_dwordx4 v[216:219], v0, s[0:1] offset:2048
	global_load_dwordx4 v[220:223], v0, s[0:1] offset:3072
	s_waitcnt vmcnt(0)
; __device__ __forceinline__ float lo_bf(unsigned w) { return __uint_as_float(w << 16); }
; __device__ __forceinline__ float hi_bf(unsigned w) { return __uint_as_float(w & 0xffff0000u); }
; __device__ __forceinline__ void phase_final(const Params& p) {
;     ...
;         for (int j = 0; j < 4; ++j) { v[j] = *(const f32x4*)(p.out + (size_t)row * D + 4 * lane + 256 * j);
;             const u32x2 wm = *(const u32x2*)(Fm + (size_t)row * D + 4 * lane + 256 * j), wf = *(const u32x2*)(F2 + (size_t)row * D + 4 * lane + 256 * j);
;             m[j] = (f32x4){lo_bf(wm.x), hi_bf(wm.x), lo_bf(wm.y), hi_bf(wm.y)}; f[j] = (f32x4){lo_bf(wf.x), hi_bf(wf.x), lo_bf(wf.y), hi_bf(wf.y)};
;             sm += (m[j].x * m[j].x + m[j].y * m[j].y) + (m[j].z * m[j].z + m[j].w * m[j].w); sf += (f[j].x * f[j].x + f[j].y * f[j].y) + (f[j].z * f[j].z + f[j].w * f[j].w); }
;         const float rm = 1.0f / sqrtf(wave_sum(sm) * (1.0f / D) + EPS), rf = 1.0f / sqrtf(wave_sum(sf) * (1.0f / D) + EPS) * 0.5f;
.Lrp15_pk9:
	s_waitcnt vmcnt(32)
	v_lshlrev_b32_e32 v112, 16, v84
	v_and_b32_e32 v113, 0xffff0000, v84
	v_lshlrev_b32_e32 v114, 16, v85
	v_and_b32_e32 v115, 0xffff0000, v85
	v_lshlrev_b32_e32 v116, 16, v86
	v_and_b32_e32 v117, 0xffff0000, v86
	v_lshlrev_b32_e32 v118, 16, v87
	v_and_b32_e32 v119, 0xffff0000, v87
	v_lshlrev_b32_e32 v120, 16, v88
	v_and_b32_e32 v121, 0xffff0000, v88
	v_lshlrev_b32_e32 v122, 16, v89
	v_and_b32_e32 v123, 0xffff0000, v89
	v_lshlrev_b32_e32 v124, 16, v90
	v_and_b32_e32 v125, 0xffff0000, v90
	v_lshlrev_b32_e32 v100, 16, v91
	v_and_b32_e32 v101, 0xffff0000, v91
	v_pk_mul_f32 v[102:103], v[112:113], v[112:113]
	v_pk_mul_f32 v[106:107], v[114:115], v[114:115]
	v_pk_fma_f32 v[102:103], v[116:117], v[116:117], v[102:103]
	v_pk_fma_f32 v[106:107], v[118:119], v[118:119], v[106:107]
	v_pk_fma_f32 v[102:103], v[120:121], v[120:121], v[102:103]
	v_pk_fma_f32 v[106:107], v[122:123], v[122:123], v[106:107]
	v_pk_fma_f32 v[102:103], v[124:125], v[124:125], v[102:103]
	v_pk_fma_f32 v[106:107], v[100:101], v[100:101], v[106:107]
	v_pk_add_f32 v[102:103], v[102:103], v[106:107]
	v_add_f32_e32 v102, v102, v103
	v_mov_b32_e32 v104, v102
	v_lshlrev_b32_e32 v112, 16, v92
	v_and_b32_e32 v113, 0xffff0000, v92
	v_lshlrev_b32_e32 v114, 16, v93
	v_and_b32_e32 v115, 0xffff0000, v93
	v_lshlrev_b32_e32 v116, 16, v94
	v_and_b32_e32 v117, 0xffff0000, v94
	v_lshlrev_b32_e32 v118, 16, v95
	v_and_b32_e32 v119, 0xffff0000, v95
	v_lshlrev_b32_e32 v120, 16, v96
	v_and_b32_e32 v121, 0xffff0000, v96
	v_lshlrev_b32_e32 v122, 16, v97
	v_and_b32_e32 v123, 0xffff0000, v97
	v_lshlrev_b32_e32 v124, 16, v98
	v_and_b32_e32 v125, 0xffff0000, v98
	v_lshlrev_b32_e32 v100, 16, v99
	v_and_b32_e32 v101, 0xffff0000, v99
	v_pk_mul_f32 v[102:103], v[112:113], v[112:113]
	v_pk_mul_f32 v[106:107], v[114:115], v[114:115]
	v_pk_fma_f32 v[102:103], v[116:117], v[116:117], v[102:103]
	v_pk_fma_f32 v[106:107], v[118:119], v[118:119], v[106:107]
	v_pk_fma_f32 v[102:103], v[120:121], v[120:121], v[102:103]
	v_pk_fma_f32 v[106:107], v[122:123], v[122:123], v[106:107]
	v_pk_fma_f32 v[102:103], v[124:125], v[124:125], v[102:103]
	v_pk_fma_f32 v[106:107], v[100:101], v[100:101], v[106:107]
	v_pk_add_f32 v[102:103], v[102:103], v[106:107]
	v_add_f32_e32 v102, v102, v103
	s_nop 1
	v_add_f32_dpp v104, v104, v104 quad_perm:[1,0,3,2] row_mask:0xf bank_mask:0xf
	v_add_f32_dpp v102, v102, v102 quad_perm:[1,0,3,2] row_mask:0xf bank_mask:0xf
	s_nop 1
	v_add_f32_dpp v104, v104, v104 quad_perm:[2,3,0,1] row_mask:0xf bank_mask:0xf
	v_add_f32_dpp v102, v102, v102 quad_perm:[2,3,0,1] row_mask:0xf bank_mask:0xf
	s_nop 1
	v_add_f32_dpp v104, v104, v104 row_half_mirror row_mask:0xf bank_mask:0xf
	v_add_f32_dpp v102, v102, v102 row_half_mirror row_mask:0xf bank_mask:0xf
	s_nop 1
	v_add_f32_dpp v104, v104, v104 row_mirror row_mask:0xf bank_mask:0xf
	v_add_f32_dpp v102, v102, v102 row_mirror row_mask:0xf bank_mask:0xf
	s_nop 1
	v_add_f32_dpp v104, v104, v104 row_bcast:15 row_mask:0xa bank_mask:0xf
	v_add_f32_dpp v102, v102, v102 row_bcast:15 row_mask:0xa bank_mask:0xf
	s_nop 1
	v_add_f32_dpp v104, v104, v104 row_bcast:31 row_mask:0xc bank_mask:0xf
	v_add_f32_dpp v102, v102, v102 row_bcast:31 row_mask:0xc bank_mask:0xf
	s_nop 1
	v_readlane_b32 s74, v104, 63
	v_readlane_b32 s75, v102, 63
	s_nop 2
	v_mov_b32_e32 v102, s74
	v_fmamk_f32 v102, v102, 0x3a800000, v2
	v_mul_f32_e32 v103, 0x4f800000, v102
	v_cmp_gt_f32_e32 vcc, 0xf800000, v102
	s_nop 1
	v_cndmask_b32_e32 v102, v102, v103, vcc
	v_sqrt_f32_e32 v103, v102
	s_nop 0
	v_add_u32_e32 v104, -1, v103
	v_add_u32_e32 v106, 1, v103
	v_fma_f32 v107, -v104, v103, v102
	v_fma_f32 v108, -v106, v103, v102
	v_cmp_ge_f32_e64 s[76:77], 0, v107
	s_nop 1
	v_cndmask_b32_e64 v103, v103, v104, s[76:77]
	v_cmp_lt_f32_e64 s[76:77], 0, v108
	s_nop 1
	v_cndmask_b32_e64 v103, v103, v106, s[76:77]
	v_mul_f32_e32 v104, 0x37800000, v103
	v_cndmask_b32_e32 v103, v103, v104, vcc
	v_cmp_class_f32_e32 vcc, v102, v3
	s_nop 1
	v_cndmask_b32_e32 v102, v103, v102, vcc
	v_div_scale_f32 v103, s[76:77], v102, v102, 1.0
	v_rcp_f32_e32 v104, v103
	v_div_scale_f32 v106, vcc, 1.0, v102, 1.0
	v_fma_f32 v107, -v103, v104, 1.0
	v_fmac_f32_e32 v104, v107, v104
	v_mul_f32_e32 v107, v106, v104
	v_fma_f32 v108, -v103, v107, v106
	v_fmac_f32_e32 v107, v108, v104
	v_fma_f32 v103, -v103, v107, v106
	v_div_fmas_f32 v103, v103, v104, v107
	v_div_fixup_f32 v110, v103, v102, 1.0
	v_mov_b32_e32 v102, s75
	v_fmamk_f32 v102, v102, 0x3a800000, v2
	v_mul_f32_e32 v103, 0x4f800000, v102
	v_cmp_gt_f32_e32 vcc, 0xf800000, v102
	s_nop 1
	v_cndmask_b32_e32 v102, v102, v103, vcc
	v_sqrt_f32_e32 v103, v102
; __device__ __forceinline__ void phase_final(const Params& p) {
;     ...
;         const float rm = 1.0f / sqrtf(wave_sum(sm) * (1.0f / D) + EPS), rf = 1.0f / sqrtf(wave_sum(sf) * (1.0f / D) + EPS) * 0.5f;
;         const float* g1 = mod + b * 9216 + 1 * 3072 + 2048; const float* g2 = mod + b * 9216 + 2 * 3072 + 2048;
;         const float* q1 = p.in[7] + 1 * D; const float* q2 = p.in[7] + 2 * D;
; #pragma unroll
;         for (int j = 0; j < 4; ++j) { const int c = 4 * lane + 256 * j;
;             const f32x4 x2 = v[j] + *(const f32x4*)(g1 + c) * (m[j] * rm * *(const f32x4*)(q1 + c));
;             *(f32x4*)(p.out + (size_t)row * D + c) = x2 + *(const f32x4*)(g2 + c) * (f[j] * rf * *(const f32x4*)(q2 + c)); }
;     }
	s_nop 0
	v_add_u32_e32 v104, -1, v103
	v_add_u32_e32 v106, 1, v103
	v_fma_f32 v107, -v104, v103, v102
	v_fma_f32 v108, -v106, v103, v102
	v_cmp_ge_f32_e64 s[76:77], 0, v107
	s_nop 1
	v_cndmask_b32_e64 v103, v103, v104, s[76:77]
	v_cmp_lt_f32_e64 s[76:77], 0, v108
	s_nop 1
	v_cndmask_b32_e64 v103, v103, v106, s[76:77]
	v_mul_f32_e32 v104, 0x37800000, v103
	v_cndmask_b32_e32 v103, v103, v104, vcc
	v_cmp_class_f32_e32 vcc, v102, v3
	s_nop 1
	v_cndmask_b32_e32 v102, v103, v102, vcc
	v_div_scale_f32 v103, s[76:77], v102, v102, 1.0
	v_rcp_f32_e32 v104, v103
	v_div_scale_f32 v106, vcc, 1.0, v102, 1.0
	v_fma_f32 v107, -v103, v104, 1.0
	v_fmac_f32_e32 v104, v107, v104
	v_mul_f32_e32 v107, v106, v104
	v_fma_f32 v108, -v103, v107, v106
	v_fmac_f32_e32 v107, v108, v104
	v_fma_f32 v103, -v103, v107, v106
	v_div_fmas_f32 v103, v103, v104, v107
	v_div_fixup_f32 v108, v103, v102, 1.0
	v_mul_f32_e32 v108, 0.5, v108
	v_pk_mul_f32 v[112:113], v[112:113], v[108:109] op_sel_hi:[1,0]
	v_pk_mul_f32 v[114:115], v[114:115], v[108:109] op_sel_hi:[1,0]
	v_pk_mul_f32 v[116:117], v[116:117], v[108:109] op_sel_hi:[1,0]
	v_pk_mul_f32 v[118:119], v[118:119], v[108:109] op_sel_hi:[1,0]
	v_pk_mul_f32 v[120:121], v[120:121], v[108:109] op_sel_hi:[1,0]
	v_pk_mul_f32 v[122:123], v[122:123], v[108:109] op_sel_hi:[1,0]
	v_pk_mul_f32 v[124:125], v[124:125], v[108:109] op_sel_hi:[1,0]
	v_pk_mul_f32 v[100:101], v[100:101], v[108:109] op_sel_hi:[1,0]
	v_pk_mul_f32 v[112:113], v[112:113], v[208:209]
	v_pk_mul_f32 v[114:115], v[114:115], v[210:211]
	v_pk_mul_f32 v[116:117], v[116:117], v[212:213]
	v_pk_mul_f32 v[118:119], v[118:119], v[214:215]
	v_pk_mul_f32 v[120:121], v[120:121], v[216:217]
	v_pk_mul_f32 v[122:123], v[122:123], v[218:219]
	v_pk_mul_f32 v[124:125], v[124:125], v[220:221]
	v_pk_mul_f32 v[100:101], v[100:101], v[222:223]
	v_lshlrev_b32_e32 v92, 16, v84
	v_and_b32_e32 v93, 0xffff0000, v84
	v_lshlrev_b32_e32 v94, 16, v85
	v_and_b32_e32 v95, 0xffff0000, v85
	v_lshlrev_b32_e32 v96, 16, v86
	v_and_b32_e32 v97, 0xffff0000, v86
	v_lshlrev_b32_e32 v98, 16, v87
	v_and_b32_e32 v99, 0xffff0000, v87
	v_lshlrev_b32_e32 v240, 16, v88
	v_and_b32_e32 v241, 0xffff0000, v88
	v_lshlrev_b32_e32 v242, 16, v89
	v_and_b32_e32 v243, 0xffff0000, v89
	v_lshlrev_b32_e32 v244, 16, v90
	v_and_b32_e32 v245, 0xffff0000, v90
	v_lshlrev_b32_e32 v246, 16, v91
	v_and_b32_e32 v247, 0xffff0000, v91
	v_pk_mul_f32 v[92:93], v[92:93], v[110:111] op_sel_hi:[1,0]
	v_pk_mul_f32 v[94:95], v[94:95], v[110:111] op_sel_hi:[1,0]
	v_pk_mul_f32 v[96:97], v[96:97], v[110:111] op_sel_hi:[1,0]
	v_pk_mul_f32 v[98:99], v[98:99], v[110:111] op_sel_hi:[1,0]
	v_pk_mul_f32 v[240:241], v[240:241], v[110:111] op_sel_hi:[1,0]
	v_pk_mul_f32 v[242:243], v[242:243], v[110:111] op_sel_hi:[1,0]
	v_pk_mul_f32 v[244:245], v[244:245], v[110:111] op_sel_hi:[1,0]
	v_pk_mul_f32 v[246:247], v[246:247], v[110:111] op_sel_hi:[1,0]
	v_pk_mul_f32 v[92:93], v[92:93], v[176:177]
	v_pk_mul_f32 v[94:95], v[94:95], v[178:179]
	v_pk_mul_f32 v[96:97], v[96:97], v[180:181]
	v_pk_mul_f32 v[98:99], v[98:99], v[182:183]
	v_pk_mul_f32 v[240:241], v[240:241], v[184:185]
	v_pk_mul_f32 v[242:243], v[242:243], v[186:187]
	v_pk_mul_f32 v[244:245], v[244:245], v[188:189]
	v_pk_mul_f32 v[246:247], v[246:247], v[190:191]
	v_pk_fma_f32 v[68:69], v[160:161], v[92:93], v[68:69]
	v_pk_fma_f32 v[70:71], v[162:163], v[94:95], v[70:71]
	v_pk_fma_f32 v[72:73], v[164:165], v[96:97], v[72:73]
	v_pk_fma_f32 v[74:75], v[166:167], v[98:99], v[74:75]
	v_pk_fma_f32 v[76:77], v[168:169], v[240:241], v[76:77]
	v_pk_fma_f32 v[78:79], v[170:171], v[242:243], v[78:79]
	v_pk_fma_f32 v[80:81], v[172:173], v[244:245], v[80:81]
	v_pk_fma_f32 v[82:83], v[174:175], v[246:247], v[82:83]
	v_pk_fma_f32 v[68:69], v[192:193], v[112:113], v[68:69]
	v_pk_fma_f32 v[70:71], v[194:195], v[114:115], v[70:71]
	v_pk_fma_f32 v[72:73], v[196:197], v[116:117], v[72:73]
	v_pk_fma_f32 v[74:75], v[198:199], v[118:119], v[74:75]
	v_pk_fma_f32 v[76:77], v[200:201], v[120:121], v[76:77]
	v_pk_fma_f32 v[78:79], v[202:203], v[122:123], v[78:79]
	v_pk_fma_f32 v[80:81], v[204:205], v[124:125], v[80:81]
	v_pk_fma_f32 v[82:83], v[206:207], v[100:101], v[82:83]
	s_lshl_b32 s60, s55, 12
	s_add_u32 s72, s84, s60
	s_addc_u32 s73, s85, 0
	global_store_dwordx4 v0, v[68:71], s[72:73] sc1
	global_store_dwordx4 v0, v[72:75], s[72:73] offset:1024 sc1
	global_store_dwordx4 v0, v[76:79], s[72:73] offset:2048 sc1
	global_store_dwordx4 v0, v[80:83], s[72:73] offset:3072 sc1
	s_add_u32 s55, s55, 8
	s_cmp_le_u32 s55, s54
	s_cbranch_scc1 .Lrp15_loop3
	s_add_u32 s51, s51, s52
	s_branch .Lrp15_chunk1
